# B-fragment LDS reads use one loop-invariant base VGPR with immediate offsets (4 VALU adds per iteration removed)
# speedup vs baseline: 1.0217x; 1.0061x over previous
; #define PG8_STAGE(bufoff, gbase, voff) do { _Pragma("unroll") for (int _i = 0; _i < 2; ++_i) \
;         __builtin_amdgcn_global_load_lds((const unsigned*)((const char*)(gbase) + (voff)[_i]), (LAS unsigned*)(lds + (bufoff) + ldsw + _i * 8192), 16, 0, 0); } while (0)
; #define PG8_LDA(dst, b, h) do { _Pragma("unroll") for (int m = 0; m < 4; ++m) _Pragma("unroll") for (int k = 0; k < 2; ++k) dst[m][k] = *(const LAS bf16x8*)(lds + PG8_SA(b, h) + aoff + m * 2048 + k * 1024); } while (0)
; #define PG8_LDB(dst, b, h) do { _Pragma("unroll") for (int n = 0; n < 2; ++n) _Pragma("unroll") for (int k = 0; k < 2; ++k) dst[n][k] = *(const LAS bf16x8*)(lds + PG8_SB(b, h) + boff + n * 2048 + k * 1024); } while (0)
; #define PG8_MMA(ai, bj, At, Bt) do { __builtin_amdgcn_s_setprio(1); _Pragma("unroll") for (int m = 0; m < 4; ++m) _Pragma("unroll") for (int n = 0; n < 2; ++n) _Pragma("unroll") for (int k = 0; k < 2; ++k) \
;         acc[ai][bj][m][n] = __builtin_amdgcn_mfma_f32_16x16x32_bf16(Bt[n][k], At[m][k], acc[ai][bj][m][n], 0, 0, 0); __builtin_amdgcn_s_setprio(0); } while (0)
; #define PG8_WAIT_L(n) asm volatile("s_waitcnt lgkmcnt(" #n ")" ::: "memory")
; #define PG8_BAR __builtin_amdgcn_s_barrier()
; template <class Epi, class Sched>
; __device__ __forceinline__ void gemm_phase(LAS unsigned char* lds, const Gemm g, const Sched& S, const Epi& E) {
;     ...
;         for (int t = 0; t < ntu; t += 2) {
;             const bool last = (t == ntu - 2);
;             const char* a1 = cA + (size_t)(t + 1) * kstep;
;             const char* a2 = last ? nA : cA + (size_t)(t + 2) * kstep; const char* b2 = last ? nB : cB + (size_t)(t + 2) * kstep;
;             const char* a3 = a2 + kstep; const char* b3 = b2 + kstep;
;             if (last && has_next) S.a_ready(nxt);
;             PG8_LDB(B0, 0, 0); PG8_SCHED; PG8_LDA(At, 0, 0); PG8_STAGE(PG8_SA(1, 1), a1 + hstepA, voffA);
;             PG8_WAIT_L(8); PG8_BAR; PG8_WAIT_L(0); PG8_MMA(0, 0, At, B0); PG8_BAR; PG8_SCHED;
;     ...
;         if (!E.keep(cur)) {
; #pragma unroll
;             for (int a = 0; a < 2; ++a)
; #pragma unroll
;                 for (int b = 0; b < 2; ++b)
; #pragma unroll
;                     for (int m = 0; m < 4; ++m)
; #pragma unroll
;                         for (int n = 0; n < 2; ++n) acc[a][b][m][n] = (f32x4){0.f, 0.f, 0.f, 0.f};
;         }
;         cur = nxt; cA = nA; cB = nB; ++ui;
.LBB0_380:
	v_mov_b64_e32 v[2:3], 0xd00
	s_ashr_i32 s25, s24, 31
	v_cmp_lt_i64_e32 vcc, s[26:27], v[2:3]
	s_lshl_b64 s[26:27], s[24:25], 20
	s_add_u32 s26, s58, s26
	s_addc_u32 s27, s59, s27
	s_and_b64 s[28:29], vcc, exec
	s_cselect_b32 s1, s27, s13
	s_cselect_b32 s25, s26, s12
	s_ashr_i32 s23, s22, 31
	s_lshl_b64 s[28:29], s[22:23], 20
	s_add_u32 s50, s56, s28
	s_addc_u32 s51, s57, s29
	s_and_b64 s[28:29], vcc, exec
	s_cselect_b32 s23, s51, s53
	s_cselect_b32 s28, s50, s52
	s_add_u32 s12, s12, 0x80080
	s_addc_u32 s13, s13, 0
	s_add_u32 s29, s52, 0x100
	v_mov_b32_e32 v2, 0
	s_addc_u32 s30, s53, 0
	s_mov_b32 s36, -2
	v_mov_b32_e32 v3, v2
	v_mov_b32_e32 v4, v2
	v_mov_b32_e32 v5, v2
	v_mov_b32_e32 v6, v2
	s_waitcnt lgkmcnt(0)
	v_mov_b32_e32 v7, v2
	v_mov_b32_e32 v8, v2
	v_mov_b32_e32 v9, v2
	v_mov_b32_e32 v18, v2
	v_mov_b32_e32 v19, v2
	v_mov_b32_e32 v20, v2
	v_mov_b32_e32 v21, v2
	v_mov_b32_e32 v22, v2
	v_mov_b32_e32 v23, v2
	v_mov_b32_e32 v24, v2
	v_mov_b32_e32 v25, v2
	v_mov_b32_e32 v34, v2
	v_mov_b32_e32 v35, v2
	v_mov_b32_e32 v36, v2
	v_mov_b32_e32 v37, v2
	v_mov_b32_e32 v38, v2
	v_mov_b32_e32 v39, v2
	v_mov_b32_e32 v40, v2
	v_mov_b32_e32 v41, v2
	v_mov_b32_e32 v50, v2
	v_mov_b32_e32 v51, v2
	v_mov_b32_e32 v52, v2
	v_mov_b32_e32 v53, v2
	v_mov_b32_e32 v54, v2
	v_mov_b32_e32 v55, v2
	v_mov_b32_e32 v56, v2
	v_mov_b32_e32 v57, v2
	v_mov_b32_e32 v10, v2
	v_mov_b32_e32 v11, v2
	v_mov_b32_e32 v12, v2
	v_mov_b32_e32 v13, v2
	v_mov_b32_e32 v14, v2
	v_mov_b32_e32 v15, v2
	v_mov_b32_e32 v16, v2
	v_mov_b32_e32 v17, v2
	v_mov_b32_e32 v26, v2
	v_mov_b32_e32 v27, v2
	v_mov_b32_e32 v28, v2
	v_mov_b32_e32 v29, v2
	v_mov_b32_e32 v30, v2
	v_mov_b32_e32 v31, v2
	v_mov_b32_e32 v32, v2
	v_mov_b32_e32 v33, v2
	v_mov_b32_e32 v42, v2
	v_mov_b32_e32 v43, v2
	v_mov_b32_e32 v44, v2
	v_mov_b32_e32 v45, v2
	v_mov_b32_e32 v46, v2
	v_mov_b32_e32 v47, v2
	v_mov_b32_e32 v48, v2
	v_mov_b32_e32 v49, v2
	v_mov_b32_e32 v58, v2
	v_mov_b32_e32 v59, v2
	v_mov_b32_e32 v60, v2
	v_mov_b32_e32 v61, v2
	v_mov_b32_e32 v62, v2
	v_mov_b32_e32 v63, v2
	v_mov_b32_e32 v64, v2
	v_mov_b32_e32 v65, v2
	v_mov_b32_e32 v66, v2
	v_mov_b32_e32 v67, v2
	v_mov_b32_e32 v68, v2
	v_mov_b32_e32 v69, v2
	v_mov_b32_e32 v70, v2
	v_mov_b32_e32 v71, v2
	v_mov_b32_e32 v72, v2
	v_mov_b32_e32 v73, v2
	v_mov_b32_e32 v82, v2
	v_mov_b32_e32 v83, v2
	v_mov_b32_e32 v84, v2
	v_mov_b32_e32 v85, v2
	v_mov_b32_e32 v86, v2
	v_mov_b32_e32 v87, v2
	v_mov_b32_e32 v88, v2
	v_mov_b32_e32 v89, v2
	v_mov_b32_e32 v98, v2
	v_mov_b32_e32 v99, v2
	v_mov_b32_e32 v100, v2
	v_mov_b32_e32 v101, v2
	v_mov_b32_e32 v102, v2
	v_mov_b32_e32 v103, v2
	v_mov_b32_e32 v104, v2
	v_mov_b32_e32 v105, v2
	v_mov_b32_e32 v114, v2
	v_mov_b32_e32 v115, v2
	v_mov_b32_e32 v116, v2
	v_mov_b32_e32 v117, v2
	v_mov_b32_e32 v118, v2
	v_mov_b32_e32 v119, v2
	v_mov_b32_e32 v120, v2
	v_mov_b32_e32 v121, v2
	v_mov_b32_e32 v74, v2
	v_mov_b32_e32 v75, v2
	v_mov_b32_e32 v76, v2
	v_mov_b32_e32 v77, v2
	v_mov_b32_e32 v78, v2
	v_mov_b32_e32 v79, v2
	v_mov_b32_e32 v80, v2
	v_mov_b32_e32 v81, v2
	v_mov_b32_e32 v90, v2
	v_mov_b32_e32 v91, v2
	v_mov_b32_e32 v92, v2
	v_mov_b32_e32 v93, v2
	v_mov_b32_e32 v94, v2
	v_mov_b32_e32 v95, v2
	v_mov_b32_e32 v96, v2
	v_mov_b32_e32 v97, v2
	v_mov_b32_e32 v106, v2
	v_mov_b32_e32 v107, v2
	v_mov_b32_e32 v108, v2
	v_mov_b32_e32 v109, v2
	v_mov_b32_e32 v110, v2
	v_mov_b32_e32 v111, v2
	v_mov_b32_e32 v112, v2
	v_mov_b32_e32 v113, v2
	v_mov_b32_e32 v122, v2
	v_mov_b32_e32 v123, v2
	v_mov_b32_e32 v124, v2
	v_mov_b32_e32 v125, v2
	v_mov_b32_e32 v126, v2
	v_mov_b32_e32 v127, v2
	v_mov_b32_e32 v128, v2
	v_mov_b32_e32 v129, v2
	v_add_u32_e32 v240, 0x10000, v170
.LBB0_381:
	s_add_u32 s37, s12, 0xfff80080
	s_addc_u32 s38, s13, -1
	s_add_i32 s46, 0, 0x10000
	ds_read_b128 v[150:153], v240
	ds_read_b128 v[154:157], v240 offset:1024
	ds_read_b128 v[158:161], v240 offset:2048
	ds_read_b128 v[162:165], v240 offset:3072
	s_cmp_eq_u32 s36, 28
	s_cselect_b32 s55, s1, s38
	s_cselect_b32 s54, s25, s37
	s_cselect_b32 s53, s23, s30
	s_cselect_b32 s52, s28, s29
	ds_read_b128 v[186:189], v176
	ds_read_b128 v[190:193], v176 offset:1024
	ds_read_b128 v[194:197], v176 offset:2048
	ds_read_b128 v[198:201], v176 offset:3072
	ds_read_b128 v[202:205], v176 offset:4096
	ds_read_b128 v[206:209], v176 offset:5120
	ds_read_b128 v[210:213], v176 offset:6144
	ds_read_b128 v[214:217], v176 offset:7168
	s_add_u32 s98, s12, 0xfff80000
	s_addc_u32 s99, s13, -1
	s_mov_b32 m0, s70
	s_nop 0
	global_load_lds_dwordx4 v146, s[98:99]
	s_mov_b32 m0, s71
	s_nop 0
	global_load_lds_dwordx4 v148, s[98:99]
	s_add_i32 m0, s63, 0xc000
	s_nop 0
	global_load_lds_dwordx4 v146, s[12:13]
	s_add_i32 m0, s63, 0xe000
	s_nop 0
	global_load_lds_dwordx4 v148, s[12:13]
	s_add_i32 s37, 0, 0x14000
	ds_read_b128 v[218:221], v240 offset:16384
	ds_read_b128 v[222:225], v240 offset:17408
	ds_read_b128 v[226:229], v240 offset:18432
	ds_read_b128 v[244:247], v240 offset:19456
	s_waitcnt lgkmcnt(0)
	s_barrier
; #define PG8_STAGE(bufoff, gbase, voff) do { _Pragma("unroll") for (int _i = 0; _i < 2; ++_i) \
;         __builtin_amdgcn_global_load_lds((const unsigned*)((const char*)(gbase) + (voff)[_i]), (LAS unsigned*)(lds + (bufoff) + ldsw + _i * 8192), 16, 0, 0); } while (0)
; #define PG8_LDA(dst, b, h) do { _Pragma("unroll") for (int m = 0; m < 4; ++m) _Pragma("unroll") for (int k = 0; k < 2; ++k) dst[m][k] = *(const LAS bf16x8*)(lds + PG8_SA(b, h) + aoff + m * 2048 + k * 1024); } while (0)
; #define PG8_LDB(dst, b, h) do { _Pragma("unroll") for (int n = 0; n < 2; ++n) _Pragma("unroll") for (int k = 0; k < 2; ++k) dst[n][k] = *(const LAS bf16x8*)(lds + PG8_SB(b, h) + boff + n * 2048 + k * 1024); } while (0)
; #define PG8_MMA(ai, bj, At, Bt) do { __builtin_amdgcn_s_setprio(1); _Pragma("unroll") for (int m = 0; m < 4; ++m) _Pragma("unroll") for (int n = 0; n < 2; ++n) _Pragma("unroll") for (int k = 0; k < 2; ++k) \
;         acc[ai][bj][m][n] = __builtin_amdgcn_mfma_f32_16x16x32_bf16(Bt[n][k], At[m][k], acc[ai][bj][m][n], 0, 0, 0); __builtin_amdgcn_s_setprio(0); } while (0)
; #define PG8_WAIT_V(n) asm volatile("s_waitcnt vmcnt(" #n ")" ::: "memory")
; #define PG8_WAIT_L(n) asm volatile("s_waitcnt lgkmcnt(" #n ")" ::: "memory")
; #define PG8_BAR __builtin_amdgcn_s_barrier()
; #define PG8_SCHED __builtin_amdgcn_sched_barrier(0)
; template <class Epi, class Sched>
; __device__ __forceinline__ void gemm_phase(LAS unsigned char* lds, const Gemm g, const Sched& S, const Epi& E) {
;     ...
;             PG8_WAIT_L(8); PG8_BAR; PG8_WAIT_L(0); PG8_MMA(0, 0, At, B0); PG8_BAR; PG8_SCHED;
;             PG8_LDB(B1, 0, 1); PG8_STAGE(PG8_SB(0, 0), b2, voffB);
;             PG8_BAR; PG8_WAIT_L(0); PG8_MMA(0, 1, At, B1); PG8_BAR;
;             PG8_LDA(At, 0, 1); PG8_STAGE(PG8_SA(0, 0), a2, voffA);
;             PG8_BAR; PG8_WAIT_L(0); PG8_MMA(1, 0, At, B0); PG8_BAR; PG8_SCHED;
;             PG8_STAGE(PG8_SB(0, 1), b2 + hstepB, voffB);
;             PG8_WAIT_V(6); PG8_BAR; PG8_MMA(1, 1, At, B1); PG8_BAR;
;             PG8_LDB(B0, 1, 0); PG8_SCHED; PG8_LDA(At, 1, 0); PG8_STAGE(PG8_SA(0, 1), a2 + hstepA, voffA);
	v_mfma_f32_16x16x32_bf16 v[126:129], v[150:153], v[186:189], v[126:129]
	v_mfma_f32_16x16x32_bf16 v[126:129], v[154:157], v[190:193], v[126:129]
	v_mfma_f32_16x16x32_bf16 v[110:113], v[150:153], v[194:197], v[110:113]
	v_mfma_f32_16x16x32_bf16 v[110:113], v[154:157], v[198:201], v[110:113]
	v_mfma_f32_16x16x32_bf16 v[94:97], v[150:153], v[202:205], v[94:97]
	v_mfma_f32_16x16x32_bf16 v[94:97], v[154:157], v[206:209], v[94:97]
	v_mfma_f32_16x16x32_bf16 v[78:81], v[150:153], v[210:213], v[78:81]
	v_mfma_f32_16x16x32_bf16 v[78:81], v[154:157], v[214:217], v[78:81]
	v_mfma_f32_16x16x32_bf16 v[122:125], v[158:161], v[186:189], v[122:125]
	v_mfma_f32_16x16x32_bf16 v[122:125], v[162:165], v[190:193], v[122:125]
	v_mfma_f32_16x16x32_bf16 v[106:109], v[158:161], v[194:197], v[106:109]
	v_mfma_f32_16x16x32_bf16 v[106:109], v[162:165], v[198:201], v[106:109]
	v_mfma_f32_16x16x32_bf16 v[90:93], v[158:161], v[202:205], v[90:93]
	v_mfma_f32_16x16x32_bf16 v[90:93], v[162:165], v[206:209], v[90:93]
	v_mfma_f32_16x16x32_bf16 v[74:77], v[158:161], v[210:213], v[74:77]
	v_mfma_f32_16x16x32_bf16 v[74:77], v[162:165], v[214:217], v[74:77]
	v_mfma_f32_16x16x32_bf16 v[118:121], v[218:221], v[186:189], v[118:121]
	v_mfma_f32_16x16x32_bf16 v[118:121], v[222:225], v[190:193], v[118:121]
	v_mfma_f32_16x16x32_bf16 v[102:105], v[218:221], v[194:197], v[102:105]
	v_mfma_f32_16x16x32_bf16 v[102:105], v[222:225], v[198:201], v[102:105]
	v_mfma_f32_16x16x32_bf16 v[86:89], v[218:221], v[202:205], v[86:89]
	v_mfma_f32_16x16x32_bf16 v[86:89], v[222:225], v[206:209], v[86:89]
	v_mfma_f32_16x16x32_bf16 v[70:73], v[218:221], v[210:213], v[70:73]
	v_mfma_f32_16x16x32_bf16 v[70:73], v[222:225], v[214:217], v[70:73]
	v_mfma_f32_16x16x32_bf16 v[114:117], v[226:229], v[186:189], v[114:117]
	v_mfma_f32_16x16x32_bf16 v[114:117], v[244:247], v[190:193], v[114:117]
	v_mfma_f32_16x16x32_bf16 v[98:101], v[226:229], v[194:197], v[98:101]
	v_mfma_f32_16x16x32_bf16 v[98:101], v[244:247], v[198:201], v[98:101]
	v_mfma_f32_16x16x32_bf16 v[82:85], v[226:229], v[202:205], v[82:85]
	v_mfma_f32_16x16x32_bf16 v[82:85], v[244:247], v[206:209], v[82:85]
	v_mfma_f32_16x16x32_bf16 v[66:69], v[226:229], v[210:213], v[66:69]
	v_mfma_f32_16x16x32_bf16 v[66:69], v[244:247], v[214:217], v[66:69]
	s_barrier
	ds_read_b128 v[186:189], v176 offset:16384
	ds_read_b128 v[190:193], v176 offset:17408
	ds_read_b128 v[194:197], v176 offset:18432
	ds_read_b128 v[198:201], v176 offset:19456
	ds_read_b128 v[202:205], v176 offset:20480
	ds_read_b128 v[206:209], v176 offset:21504
	ds_read_b128 v[210:213], v176 offset:22528
	ds_read_b128 v[214:217], v176 offset:23552
	s_add_i32 s38, s46, s62
	s_mov_b32 m0, s38
	s_nop 0
	global_load_lds_dwordx4 v134, s[52:53]
	s_add_i32 m0, s38, 0x2000
	s_nop 0
	global_load_lds_dwordx4 v130, s[52:53]
	s_add_u32 s76, s52, 0x80000
	s_addc_u32 s77, s53, 0
	s_add_i32 s37, s37, s62
	s_mov_b32 m0, s37
	s_nop 0
	global_load_lds_dwordx4 v134, s[76:77]
	s_add_i32 m0, s37, 0x2000
	s_nop 0
	global_load_lds_dwordx4 v130, s[76:77]
	s_waitcnt vmcnt(4)
	s_waitcnt lgkmcnt(0)
	s_barrier
	v_mfma_f32_16x16x32_bf16 v[62:65], v[150:153], v[186:189], v[62:65]
	v_mfma_f32_16x16x32_bf16 v[62:65], v[154:157], v[190:193], v[62:65]
	v_mfma_f32_16x16x32_bf16 v[46:49], v[150:153], v[194:197], v[46:49]
	v_mfma_f32_16x16x32_bf16 v[46:49], v[154:157], v[198:201], v[46:49]
	v_mfma_f32_16x16x32_bf16 v[30:33], v[150:153], v[202:205], v[30:33]
	v_mfma_f32_16x16x32_bf16 v[30:33], v[154:157], v[206:209], v[30:33]
	v_mfma_f32_16x16x32_bf16 v[14:17], v[150:153], v[210:213], v[14:17]
	v_mfma_f32_16x16x32_bf16 v[14:17], v[154:157], v[214:217], v[14:17]
	v_mfma_f32_16x16x32_bf16 v[58:61], v[158:161], v[186:189], v[58:61]
	v_mfma_f32_16x16x32_bf16 v[58:61], v[162:165], v[190:193], v[58:61]
	v_mfma_f32_16x16x32_bf16 v[42:45], v[158:161], v[194:197], v[42:45]
	v_mfma_f32_16x16x32_bf16 v[42:45], v[162:165], v[198:201], v[42:45]
	v_mfma_f32_16x16x32_bf16 v[26:29], v[158:161], v[202:205], v[26:29]
	v_mfma_f32_16x16x32_bf16 v[26:29], v[162:165], v[206:209], v[26:29]
	v_mfma_f32_16x16x32_bf16 v[10:13], v[158:161], v[210:213], v[10:13]
	v_mfma_f32_16x16x32_bf16 v[10:13], v[162:165], v[214:217], v[10:13]
	v_mfma_f32_16x16x32_bf16 v[54:57], v[218:221], v[186:189], v[54:57]
	v_mfma_f32_16x16x32_bf16 v[54:57], v[222:225], v[190:193], v[54:57]
	v_mfma_f32_16x16x32_bf16 v[38:41], v[218:221], v[194:197], v[38:41]
	v_mfma_f32_16x16x32_bf16 v[38:41], v[222:225], v[198:201], v[38:41]
	v_mfma_f32_16x16x32_bf16 v[22:25], v[218:221], v[202:205], v[22:25]
	v_mfma_f32_16x16x32_bf16 v[22:25], v[222:225], v[206:209], v[22:25]
	v_mfma_f32_16x16x32_bf16 v[6:9], v[218:221], v[210:213], v[6:9]
	v_mfma_f32_16x16x32_bf16 v[6:9], v[222:225], v[214:217], v[6:9]
	v_mfma_f32_16x16x32_bf16 v[50:53], v[226:229], v[186:189], v[50:53]
	v_mfma_f32_16x16x32_bf16 v[50:53], v[244:247], v[190:193], v[50:53]
	v_mfma_f32_16x16x32_bf16 v[34:37], v[226:229], v[194:197], v[34:37]
	v_mfma_f32_16x16x32_bf16 v[34:37], v[244:247], v[198:201], v[34:37]
	v_mfma_f32_16x16x32_bf16 v[18:21], v[226:229], v[202:205], v[18:21]
	v_mfma_f32_16x16x32_bf16 v[18:21], v[244:247], v[206:209], v[18:21]
	v_mfma_f32_16x16x32_bf16 v[2:5], v[226:229], v[210:213], v[2:5]
	v_mfma_f32_16x16x32_bf16 v[2:5], v[244:247], v[214:217], v[2:5]
	s_add_i32 s37, 0, 0x18000
	s_barrier
; #define PG8_STAGE(bufoff, gbase, voff) do { _Pragma("unroll") for (int _i = 0; _i < 2; ++_i) \
;         __builtin_amdgcn_global_load_lds((const unsigned*)((const char*)(gbase) + (voff)[_i]), (LAS unsigned*)(lds + (bufoff) + ldsw + _i * 8192), 16, 0, 0); } while (0)
; #define PG8_LDA(dst, b, h) do { _Pragma("unroll") for (int m = 0; m < 4; ++m) _Pragma("unroll") for (int k = 0; k < 2; ++k) dst[m][k] = *(const LAS bf16x8*)(lds + PG8_SA(b, h) + aoff + m * 2048 + k * 1024); } while (0)
; #define PG8_LDB(dst, b, h) do { _Pragma("unroll") for (int n = 0; n < 2; ++n) _Pragma("unroll") for (int k = 0; k < 2; ++k) dst[n][k] = *(const LAS bf16x8*)(lds + PG8_SB(b, h) + boff + n * 2048 + k * 1024); } while (0)
; #define PG8_MMA(ai, bj, At, Bt) do { __builtin_amdgcn_s_setprio(1); _Pragma("unroll") for (int m = 0; m < 4; ++m) _Pragma("unroll") for (int n = 0; n < 2; ++n) _Pragma("unroll") for (int k = 0; k < 2; ++k) \
;         acc[ai][bj][m][n] = __builtin_amdgcn_mfma_f32_16x16x32_bf16(Bt[n][k], At[m][k], acc[ai][bj][m][n], 0, 0, 0); __builtin_amdgcn_s_setprio(0); } while (0)
; #define PG8_WAIT_V(n) asm volatile("s_waitcnt vmcnt(" #n ")" ::: "memory")
; #define PG8_WAIT_L(n) asm volatile("s_waitcnt lgkmcnt(" #n ")" ::: "memory")
; #define PG8_BAR __builtin_amdgcn_s_barrier()
; #define PG8_SCHED __builtin_amdgcn_sched_barrier(0)
; template <class Epi, class Sched>
; __device__ __forceinline__ void gemm_phase(LAS unsigned char* lds, const Gemm g, const Sched& S, const Epi& E) {
;     ...
;             PG8_LDB(B0, 1, 0); PG8_SCHED; PG8_LDA(At, 1, 0); PG8_STAGE(PG8_SA(0, 1), a2 + hstepA, voffA);
;             PG8_WAIT_L(8); PG8_BAR; PG8_WAIT_L(0); PG8_MMA(0, 0, At, B0); PG8_BAR; PG8_SCHED;
;             PG8_LDB(B1, 1, 1); PG8_STAGE(PG8_SB(1, 0), b3, voffB);
;             PG8_BAR; PG8_WAIT_L(0); PG8_MMA(0, 1, At, B1); PG8_BAR;
;             PG8_LDA(At, 1, 1); PG8_STAGE(PG8_SA(1, 0), a3, voffA);
;             PG8_BAR; PG8_WAIT_L(0); PG8_MMA(1, 0, At, B0); PG8_BAR; PG8_SCHED;
;             PG8_STAGE(PG8_SB(1, 1), b3 + hstepB, voffB);
;             PG8_WAIT_V(6); PG8_BAR; PG8_MMA(1, 1, At, B1); PG8_BAR;
	ds_read_b128 v[150:153], v240 offset:32768
	ds_read_b128 v[154:157], v240 offset:33792
	ds_read_b128 v[158:161], v240 offset:34816
	ds_read_b128 v[162:165], v240 offset:35840
	ds_read_b128 v[186:189], v176 offset:32768
	ds_read_b128 v[190:193], v176 offset:33792
	ds_read_b128 v[194:197], v176 offset:34816
	ds_read_b128 v[198:201], v176 offset:35840
	ds_read_b128 v[202:205], v176 offset:36864
	ds_read_b128 v[206:209], v176 offset:37888
	ds_read_b128 v[210:213], v176 offset:38912
	ds_read_b128 v[214:217], v176 offset:39936
	s_mov_b32 m0, s63
	s_nop 0
	global_load_lds_dwordx4 v136, s[54:55]
	s_mov_b32 m0, s66
	s_nop 0
	global_load_lds_dwordx4 v132, s[54:55]
	s_add_u32 s54, s54, 0x80000
	s_addc_u32 s55, s55, 0
	s_mov_b32 m0, s67
	s_nop 0
	global_load_lds_dwordx4 v136, s[54:55]
	s_mov_b32 m0, s68
	s_nop 0
	global_load_lds_dwordx4 v132, s[54:55]
	s_add_i32 s38, 0, 0x1c000
	ds_read_b128 v[218:221], v240 offset:49152
	ds_read_b128 v[222:225], v240 offset:50176
	ds_read_b128 v[226:229], v240 offset:51200
	ds_read_b128 v[244:247], v240 offset:52224
	s_waitcnt lgkmcnt(0)
	s_barrier
	v_mfma_f32_16x16x32_bf16 v[126:129], v[150:153], v[186:189], v[126:129]
	v_mfma_f32_16x16x32_bf16 v[126:129], v[154:157], v[190:193], v[126:129]
	v_mfma_f32_16x16x32_bf16 v[110:113], v[150:153], v[194:197], v[110:113]
	v_mfma_f32_16x16x32_bf16 v[110:113], v[154:157], v[198:201], v[110:113]
	v_mfma_f32_16x16x32_bf16 v[94:97], v[150:153], v[202:205], v[94:97]
	v_mfma_f32_16x16x32_bf16 v[94:97], v[154:157], v[206:209], v[94:97]
	v_mfma_f32_16x16x32_bf16 v[78:81], v[150:153], v[210:213], v[78:81]
	v_mfma_f32_16x16x32_bf16 v[78:81], v[154:157], v[214:217], v[78:81]
	v_mfma_f32_16x16x32_bf16 v[122:125], v[158:161], v[186:189], v[122:125]
	v_mfma_f32_16x16x32_bf16 v[122:125], v[162:165], v[190:193], v[122:125]
	v_mfma_f32_16x16x32_bf16 v[106:109], v[158:161], v[194:197], v[106:109]
	v_mfma_f32_16x16x32_bf16 v[106:109], v[162:165], v[198:201], v[106:109]
	v_mfma_f32_16x16x32_bf16 v[90:93], v[158:161], v[202:205], v[90:93]
	v_mfma_f32_16x16x32_bf16 v[90:93], v[162:165], v[206:209], v[90:93]
	v_mfma_f32_16x16x32_bf16 v[74:77], v[158:161], v[210:213], v[74:77]
	v_mfma_f32_16x16x32_bf16 v[74:77], v[162:165], v[214:217], v[74:77]
	v_mfma_f32_16x16x32_bf16 v[118:121], v[218:221], v[186:189], v[118:121]
	v_mfma_f32_16x16x32_bf16 v[118:121], v[222:225], v[190:193], v[118:121]
	v_mfma_f32_16x16x32_bf16 v[102:105], v[218:221], v[194:197], v[102:105]
	v_mfma_f32_16x16x32_bf16 v[102:105], v[222:225], v[198:201], v[102:105]
	v_mfma_f32_16x16x32_bf16 v[86:89], v[218:221], v[202:205], v[86:89]
	v_mfma_f32_16x16x32_bf16 v[86:89], v[222:225], v[206:209], v[86:89]
	v_mfma_f32_16x16x32_bf16 v[70:73], v[218:221], v[210:213], v[70:73]
	v_mfma_f32_16x16x32_bf16 v[70:73], v[222:225], v[214:217], v[70:73]
	v_mfma_f32_16x16x32_bf16 v[114:117], v[226:229], v[186:189], v[114:117]
	v_mfma_f32_16x16x32_bf16 v[114:117], v[244:247], v[190:193], v[114:117]
	v_mfma_f32_16x16x32_bf16 v[98:101], v[226:229], v[194:197], v[98:101]
	v_mfma_f32_16x16x32_bf16 v[98:101], v[244:247], v[198:201], v[98:101]
	v_mfma_f32_16x16x32_bf16 v[82:85], v[226:229], v[202:205], v[82:85]
	v_mfma_f32_16x16x32_bf16 v[82:85], v[244:247], v[206:209], v[82:85]
	v_mfma_f32_16x16x32_bf16 v[66:69], v[226:229], v[210:213], v[66:69]
	v_mfma_f32_16x16x32_bf16 v[66:69], v[244:247], v[214:217], v[66:69]
	s_barrier
	ds_read_b128 v[186:189], v176 offset:49152
	ds_read_b128 v[190:193], v176 offset:50176
	ds_read_b128 v[194:197], v176 offset:51200
	ds_read_b128 v[198:201], v176 offset:52224
	ds_read_b128 v[202:205], v176 offset:53248
	ds_read_b128 v[206:209], v176 offset:54272
	ds_read_b128 v[210:213], v176 offset:55296
	ds_read_b128 v[214:217], v176 offset:56320
	s_add_u32 s98, s52, 0x80
	s_addc_u32 s99, s53, 0
	s_add_i32 s37, s37, s62
	s_mov_b32 m0, s37
	s_nop 0
	global_load_lds_dwordx4 v134, s[98:99]
	s_add_i32 m0, s37, 0x2000
	s_nop 0
	global_load_lds_dwordx4 v130, s[98:99]
	s_add_u32 s52, s52, 0x80080
	s_addc_u32 s53, s53, 0
	s_add_i32 s37, s38, s62
	s_mov_b32 m0, s37
	s_nop 0
	global_load_lds_dwordx4 v134, s[52:53]
	s_add_i32 m0, s37, 0x2000
	s_nop 0
	global_load_lds_dwordx4 v130, s[52:53]
	s_waitcnt vmcnt(4)
	s_waitcnt lgkmcnt(0)
	s_barrier
; #define PG8_BAR __builtin_amdgcn_s_barrier()
;     __device__ __forceinline__ void operator()(f32x4 (&acc)[2][2][4][2], const Unit& u, int wr, int wc, int fr, int fq) const {
;     ...
;         } else if (pn < 20 && lat) {
; #pragma unroll
;             for (int ai = 0; ai < 2; ++ai) { f32x4 c01[4], c23[4];
; #pragma unroll
;                 for (int m = 0; m < 4; ++m) { const int prow = (pmb - 1) * 4 + 2 * ai + wr, pcol = 16 * m + fr;
;                     const float2* tp = T128 + ((wc >> 1) ? pcol : prow) * 32 + 16 * (wc & 1) + 4 * fq; c01[m] = *(const f32x4*)tp; c23[m] = *(const f32x4*)(tp + 2); }
;                 __builtin_amdgcn_sched_barrier(0);
; #pragma unroll
;                 for (int m = 0; m < 4; ++m) {
;                     const float cs[4] = {c01[m][0], c01[m][2], c23[m][0], c23[m][2]}, sn[4] = {c01[m][1], c01[m][3], c23[m][1], c23[m][3]};
; #pragma unroll
;                     for (int bj = 0; bj < 2; ++bj) { float v[8];
; #pragma unroll
;                         for (int p = 0; p < 4; ++p) { const float x1 = EW_V(bj, 2 * p), x2 = EW_V(bj, 2 * p + 1); v[2 * p] = x1 * cs[p] - x2 * sn[p]; v[2 * p + 1] = x2 * cs[p] + x1 * sn[p]; }
;                         st8(EW_ZP(bj), v); } } }
;         } else if (pn < 24) {
; #pragma unroll
;             EW_ROWS {
; #pragma unroll
;                 for (int bj = 0; bj < 2; ++bj) { float v[8];
; #pragma unroll
;                     for (int e = 0; e < 8; ++e) v[e] = EW_V(bj, e);
;                     st8(EW_ZP(bj), v); } }
;         } else if (pn < 48) {
;             bf16_t* gt = GN + ((size_t)u.pm * 24 + (pn - 24)) * 65536 + ((size_t)(wr * 4 + wc) * 16 * 64 + lane) * 8;
; #pragma unroll
;             EW_ROWS {
; #pragma unroll
;                 for (int bj = 0; bj < 2; ++bj) { float v[8];
; #pragma unroll
;                     for (int e = 0; e < 8; ++e) v[e] = sigmoidf_(EW_V(bj, e));
;                     st8(gt + ((ai * 4 + m) * 2 + bj) * 512, v); } }
;         } else if (wc < 2) {
; #pragma unroll
;             EW_ROWS { const int prow = (pmb - 1) * 4 + 2 * ai + wr, pcol = 16 * m + fr; float v[8];
; #pragma unroll
;                 for (int e = 0; e < 8; ++e) v[e] = EW_V(0, e);
; template <class Epi, class Sched>
; __device__ __forceinline__ void gemm_phase(LAS unsigned char* lds, const Gemm g, const Sched& S, const Epi& E) {
;     ...
;             PG8_WAIT_V(6); PG8_BAR; PG8_MMA(1, 1, At, B1); PG8_BAR;
;         }
	v_mfma_f32_16x16x32_bf16 v[62:65], v[150:153], v[186:189], v[62:65]
	v_mfma_f32_16x16x32_bf16 v[62:65], v[154:157], v[190:193], v[62:65]
	v_mfma_f32_16x16x32_bf16 v[46:49], v[150:153], v[194:197], v[46:49]
	v_mfma_f32_16x16x32_bf16 v[46:49], v[154:157], v[198:201], v[46:49]
	v_mfma_f32_16x16x32_bf16 v[30:33], v[150:153], v[202:205], v[30:33]
	v_mfma_f32_16x16x32_bf16 v[30:33], v[154:157], v[206:209], v[30:33]
	v_mfma_f32_16x16x32_bf16 v[14:17], v[150:153], v[210:213], v[14:17]
	v_mfma_f32_16x16x32_bf16 v[14:17], v[154:157], v[214:217], v[14:17]
	v_mfma_f32_16x16x32_bf16 v[58:61], v[158:161], v[186:189], v[58:61]
	v_mfma_f32_16x16x32_bf16 v[58:61], v[162:165], v[190:193], v[58:61]
	v_mfma_f32_16x16x32_bf16 v[42:45], v[158:161], v[194:197], v[42:45]
	v_mfma_f32_16x16x32_bf16 v[42:45], v[162:165], v[198:201], v[42:45]
	v_mfma_f32_16x16x32_bf16 v[26:29], v[158:161], v[202:205], v[26:29]
	v_mfma_f32_16x16x32_bf16 v[26:29], v[162:165], v[206:209], v[26:29]
	v_mfma_f32_16x16x32_bf16 v[10:13], v[158:161], v[210:213], v[10:13]
	v_mfma_f32_16x16x32_bf16 v[10:13], v[162:165], v[214:217], v[10:13]
	v_mfma_f32_16x16x32_bf16 v[54:57], v[218:221], v[186:189], v[54:57]
	v_mfma_f32_16x16x32_bf16 v[54:57], v[222:225], v[190:193], v[54:57]
	v_mfma_f32_16x16x32_bf16 v[38:41], v[218:221], v[194:197], v[38:41]
	v_mfma_f32_16x16x32_bf16 v[38:41], v[222:225], v[198:201], v[38:41]
	v_mfma_f32_16x16x32_bf16 v[22:25], v[218:221], v[202:205], v[22:25]
	v_mfma_f32_16x16x32_bf16 v[22:25], v[222:225], v[206:209], v[22:25]
	v_mfma_f32_16x16x32_bf16 v[6:9], v[218:221], v[210:213], v[6:9]
	v_mfma_f32_16x16x32_bf16 v[6:9], v[222:225], v[214:217], v[6:9]
	v_mfma_f32_16x16x32_bf16 v[50:53], v[226:229], v[186:189], v[50:53]
	v_mfma_f32_16x16x32_bf16 v[50:53], v[244:247], v[190:193], v[50:53]
	v_mfma_f32_16x16x32_bf16 v[34:37], v[226:229], v[194:197], v[34:37]
	v_mfma_f32_16x16x32_bf16 v[34:37], v[244:247], v[198:201], v[34:37]
	v_mfma_f32_16x16x32_bf16 v[18:21], v[226:229], v[202:205], v[18:21]
	v_mfma_f32_16x16x32_bf16 v[18:21], v[244:247], v[206:209], v[18:21]
	v_mfma_f32_16x16x32_bf16 v[2:5], v[226:229], v[210:213], v[2:5]
	v_mfma_f32_16x16x32_bf16 v[2:5], v[244:247], v[214:217], v[2:5]
	s_add_i32 s36, s36, 2
	s_add_u32 s12, s12, 0x100
	s_addc_u32 s13, s13, 0
	s_add_u32 s29, s29, 0x100
	s_addc_u32 s30, s30, 0
	s_cmp_gt_u32 s36, 29
	s_barrier
	s_cbranch_scc0 .LBB0_381
	v_lshl_add_u32 v152, s0, 8, v169
	v_mov_b64_e32 v[150:151], s[16:17]
	v_mad_i64_i32 v[150:151], s[12:13], v152, s84, v[150:151]
	s_lshl_b32 s12, s33, 8
	s_ashr_i32 s13, s12, 31
	v_lshl_add_u64 v[150:151], s[12:13], 1, v[150:151]
	v_readlane_b32 s76, v255, 26
	v_ashrrev_i32_e32 v153, 31, v152
	v_lshl_add_u64 v[150:151], v[150:151], 0, v[178:179]
	s_cmp_gt_i32 s33, 3
	s_mov_b64 s[12:13], -1
	v_readlane_b32 s77, v255, 27
	s_mov_b64 s[36:37], s[74:75]
	v_mov_b32_e32 v230, 0x3727c5ac
	s_cbranch_scc0 .LBB0_446
	s_cmp_gt_u32 s33, 7
	s_cbranch_scc0 .LBB0_443
	s_cmp_gt_u32 s33, 11
	s_cbranch_scc0 .LBB0_424
	s_mul_hi_i32 s1, s0, 0x78787879
	s_lshr_b32 s12, s1, 31
	s_ashr_i32 s1, s1, 3
	s_add_i32 s1, s1, s12
	s_mul_i32 s1, s1, 17
	s_sub_i32 s1, s0, s1
	s_cmp_lg_u32 s1, 0
	s_cselect_b64 s[28:29], -1, 0
	s_cmp_lt_u32 s33, 20
	s_cselect_b64 s[12:13], -1, 0
	s_and_b64 s[12:13], s[12:13], s[28:29]
	s_andn2_b64 vcc, exec, s[12:13]
	s_mov_b64 s[12:13], -1
	s_cbranch_vccz .LBB0_421
	s_cmp_gt_u32 s33, 23
	s_cbranch_scc0 .LBB0_418
	s_cmp_gt_u32 s33, 47
	s_cbranch_scc0 .LBB0_415
	s_andn2_b64 vcc, exec, s[4:5]
	s_cbranch_vccnz .LBB0_414
	s_lshl_b32 s23, s1, 2
	v_cndmask_b32_e64 v154, 0, 1, s[28:29]
	v_cmp_ne_u32_e64 s[12:13], 1, v154
	s_andn2_b64 vcc, exec, s[28:29]
	s_add_i32 s23, s23, s79
	s_cbranch_vccnz .LBB0_391
	v_mov_b32_e32 v154, s23
	v_cndmask_b32_e64 v154, v168, v154, s[6:7]
	v_lshlrev_b32_e32 v154, 4, v154
	v_ashrrev_i32_e32 v155, 31, v154
	v_lshl_add_u64 v[154:155], v[154:155], 3, v[138:139]
	global_load_dwordx4 v[164:167], v[154:155], off offset:16
	global_load_dwordx4 v[156:159], v[154:155], off
	s_waitcnt vmcnt(0)
	v_pk_mul_f32 v[162:163], v[122:123], v[164:165] op_sel:[1,1] op_sel_hi:[0,1]
	v_pk_mul_f32 v[184:185], v[126:127], v[156:157] op_sel:[1,1] op_sel_hi:[0,1]
	v_pk_fma_f32 v[154:155], v[126:127], v[156:157], v[184:185] op_sel_hi:[1,0,1]
	v_pk_mul_f32 v[182:183], v[126:127], v[156:157]
	v_mov_b32_e32 v154, v159
	v_pk_mul_f32 v[160:161], v[128:129], v[154:155] op_sel:[1,0] op_sel_hi:[0,0]
	v_mul_f32_e32 v154, v125, v167
	v_pk_fma_f32 v[156:157], v[128:129], v[158:159], v[160:161] op_sel_hi:[1,0,1] neg_lo:[0,0,1] neg_hi:[0,0,1]
	v_pk_fma_f32 v[158:159], v[128:129], v[158:159], v[160:161] op_sel_hi:[1,0,1]
	v_pk_fma_f32 v[160:161], v[122:123], v[164:165], v[162:163] op_sel_hi:[1,0,1] neg_lo:[0,0,1] neg_hi:[0,0,1]
	v_pk_fma_f32 v[162:163], v[122:123], v[164:165], v[162:163] op_sel_hi:[1,0,1]
	v_pk_fma_f32 v[164:165], v[124:125], v[166:167], v[154:155] op_sel_hi:[1,1,0] neg_lo:[0,0,1] neg_hi:[0,0,1]
	v_mul_f32_e32 v154, v124, v167
	v_pk_fma_f32 v[166:167], v[124:125], v[166:167], v[154:155] op_sel:[1,0,0] op_sel_hi:[0,1,0]
	v_sub_f32_e32 v154, v182, v184
	s_branch .LBB0_392

; #define PG8_STAGE(bufoff, gbase, voff) do { _Pragma("unroll") for (int _i = 0; _i < 2; ++_i) \
;         __builtin_amdgcn_global_load_lds((const unsigned*)((const char*)(gbase) + (voff)[_i]), (LAS unsigned*)(lds + (bufoff) + ldsw + _i * 8192), 16, 0, 0); } while (0)
; #define PG8_LDA(dst, b, h) do { _Pragma("unroll") for (int m = 0; m < 4; ++m) _Pragma("unroll") for (int k = 0; k < 2; ++k) dst[m][k] = *(const LAS bf16x8*)(lds + PG8_SA(b, h) + aoff + m * 2048 + k * 1024); } while (0)
; #define PG8_LDB(dst, b, h) do { _Pragma("unroll") for (int n = 0; n < 2; ++n) _Pragma("unroll") for (int k = 0; k < 2; ++k) dst[n][k] = *(const LAS bf16x8*)(lds + PG8_SB(b, h) + boff + n * 2048 + k * 1024); } while (0)
; #define PG8_MMA(ai, bj, At, Bt) do { __builtin_amdgcn_s_setprio(1); _Pragma("unroll") for (int m = 0; m < 4; ++m) _Pragma("unroll") for (int n = 0; n < 2; ++n) _Pragma("unroll") for (int k = 0; k < 2; ++k) \
;         acc[ai][bj][m][n] = __builtin_amdgcn_mfma_f32_16x16x32_bf16(Bt[n][k], At[m][k], acc[ai][bj][m][n], 0, 0, 0); __builtin_amdgcn_s_setprio(0); } while (0)
; #define PG8_WAIT_L(n) asm volatile("s_waitcnt lgkmcnt(" #n ")" ::: "memory")
; #define PG8_BAR __builtin_amdgcn_s_barrier()
; template <class Epi, class Sched>
; __device__ __forceinline__ void gemm_phase(LAS unsigned char* lds, const Gemm g, const Sched& S, const Epi& E) {
;     ...
;         for (int t = 0; t < ntu; t += 2) {
;             const bool last = (t == ntu - 2);
;             const char* a1 = cA + (size_t)(t + 1) * kstep;
;             const char* a2 = last ? nA : cA + (size_t)(t + 2) * kstep; const char* b2 = last ? nB : cB + (size_t)(t + 2) * kstep;
;             const char* a3 = a2 + kstep; const char* b3 = b2 + kstep;
;             if (last && has_next) S.a_ready(nxt);
;             PG8_LDB(B0, 0, 0); PG8_SCHED; PG8_LDA(At, 0, 0); PG8_STAGE(PG8_SA(1, 1), a1 + hstepA, voffA);
;             PG8_WAIT_L(8); PG8_BAR; PG8_WAIT_L(0); PG8_MMA(0, 0, At, B0); PG8_BAR; PG8_SCHED;
;     ...
;         if (!E.keep(cur)) {
; #pragma unroll
;             for (int a = 0; a < 2; ++a)
; #pragma unroll
;                 for (int b = 0; b < 2; ++b)
; #pragma unroll
;                     for (int m = 0; m < 4; ++m)
; #pragma unroll
;                         for (int n = 0; n < 2; ++n) acc[a][b][m][n] = (f32x4){0.f, 0.f, 0.f, 0.f};
;         }
;         cur = nxt; cA = nA; cB = nB; ++ui;
.LBB0_570:
	s_ashr_i32 s51, s50, 31
	s_lshl_b64 s[28:29], s[50:51], 18
	s_add_u32 s54, s36, s28
	s_addc_u32 s55, s37, s29
	s_and_b64 s[6:7], s[6:7], exec
	s_cselect_b32 s28, s55, s59
	s_cselect_b32 s29, s54, s58
	s_add_u32 s30, s58, 0x100
	v_mov_b32_e32 v2, 0
	s_addc_u32 s51, s59, 0
	s_mov_b32 s76, -2
	v_mov_b32_e32 v3, v2
	v_mov_b32_e32 v4, v2
	v_mov_b32_e32 v5, v2
	v_mov_b32_e32 v6, v2
	v_mov_b32_e32 v7, v2
	v_mov_b32_e32 v8, v2
	v_mov_b32_e32 v9, v2
	v_mov_b32_e32 v10, v2
	v_mov_b32_e32 v11, v2
	v_mov_b32_e32 v12, v2
	v_mov_b32_e32 v13, v2
	v_mov_b32_e32 v14, v2
	v_mov_b32_e32 v15, v2
	v_mov_b32_e32 v16, v2
	v_mov_b32_e32 v17, v2
	v_mov_b32_e32 v18, v2
	v_mov_b32_e32 v19, v2
	v_mov_b32_e32 v20, v2
	v_mov_b32_e32 v21, v2
	v_mov_b32_e32 v22, v2
	v_mov_b32_e32 v23, v2
	v_mov_b32_e32 v24, v2
	v_mov_b32_e32 v25, v2
	v_mov_b32_e32 v26, v2
	v_mov_b32_e32 v27, v2
	v_mov_b32_e32 v28, v2
	v_mov_b32_e32 v29, v2
	v_mov_b32_e32 v30, v2
	v_mov_b32_e32 v31, v2
	v_mov_b32_e32 v32, v2
	v_mov_b32_e32 v33, v2
	v_mov_b32_e32 v34, v2
	v_mov_b32_e32 v35, v2
	v_mov_b32_e32 v36, v2
	v_mov_b32_e32 v37, v2
	v_mov_b32_e32 v38, v2
	v_mov_b32_e32 v39, v2
	v_mov_b32_e32 v40, v2
	v_mov_b32_e32 v41, v2
	v_mov_b32_e32 v42, v2
	v_mov_b32_e32 v43, v2
	v_mov_b32_e32 v44, v2
	v_mov_b32_e32 v45, v2
	v_mov_b32_e32 v46, v2
	v_mov_b32_e32 v47, v2
	v_mov_b32_e32 v48, v2
	v_mov_b32_e32 v49, v2
	v_mov_b32_e32 v50, v2
	v_mov_b32_e32 v51, v2
	v_mov_b32_e32 v52, v2
	v_mov_b32_e32 v53, v2
	v_mov_b32_e32 v54, v2
	v_mov_b32_e32 v55, v2
	v_mov_b32_e32 v56, v2
	v_mov_b32_e32 v57, v2
	v_mov_b32_e32 v58, v2
	v_mov_b32_e32 v59, v2
	v_mov_b32_e32 v60, v2
	v_mov_b32_e32 v61, v2
	v_mov_b32_e32 v62, v2
	v_mov_b32_e32 v63, v2
	v_mov_b32_e32 v64, v2
	v_mov_b32_e32 v65, v2
	v_mov_b32_e32 v66, v2
	v_mov_b32_e32 v67, v2
	v_mov_b32_e32 v68, v2
	v_mov_b32_e32 v69, v2
	v_mov_b32_e32 v70, v2
	v_mov_b32_e32 v71, v2
	v_mov_b32_e32 v72, v2
	v_mov_b32_e32 v73, v2
	v_mov_b32_e32 v74, v2
	v_mov_b32_e32 v75, v2
	v_mov_b32_e32 v76, v2
	v_mov_b32_e32 v77, v2
	v_mov_b32_e32 v78, v2
	v_mov_b32_e32 v79, v2
	v_mov_b32_e32 v80, v2
	v_mov_b32_e32 v81, v2
	v_mov_b32_e32 v82, v2
	v_mov_b32_e32 v83, v2
	v_mov_b32_e32 v84, v2
	v_mov_b32_e32 v85, v2
	v_mov_b32_e32 v86, v2
	v_mov_b32_e32 v87, v2
	v_mov_b32_e32 v88, v2
	v_mov_b32_e32 v89, v2
	v_mov_b32_e32 v90, v2
	v_mov_b32_e32 v91, v2
	v_mov_b32_e32 v92, v2
	v_mov_b32_e32 v93, v2
	v_mov_b32_e32 v94, v2
	v_mov_b32_e32 v95, v2
	v_mov_b32_e32 v96, v2
	v_mov_b32_e32 v97, v2
	v_mov_b32_e32 v98, v2
	v_mov_b32_e32 v99, v2
	v_mov_b32_e32 v100, v2
	v_mov_b32_e32 v101, v2
	v_mov_b32_e32 v102, v2
	v_mov_b32_e32 v103, v2
	v_mov_b32_e32 v104, v2
	v_mov_b32_e32 v105, v2
	v_mov_b32_e32 v106, v2
	v_mov_b32_e32 v107, v2
	v_mov_b32_e32 v108, v2
	v_mov_b32_e32 v109, v2
	v_mov_b32_e32 v110, v2
	v_mov_b32_e32 v111, v2
	v_mov_b32_e32 v112, v2
	v_mov_b32_e32 v113, v2
	v_mov_b32_e32 v114, v2
	v_mov_b32_e32 v115, v2
	v_mov_b32_e32 v116, v2
	v_mov_b32_e32 v117, v2
	v_mov_b32_e32 v118, v2
	v_mov_b32_e32 v119, v2
	v_mov_b32_e32 v120, v2
	v_mov_b32_e32 v121, v2
	v_mov_b32_e32 v122, v2
	v_mov_b32_e32 v123, v2
	v_mov_b32_e32 v124, v2
	v_mov_b32_e32 v125, v2
	v_mov_b32_e32 v126, v2
	v_mov_b32_e32 v127, v2
	v_mov_b32_e32 v128, v2
	v_mov_b32_e32 v129, v2
	v_add_u32_e32 v240, 0x10000, v197
.LBB0_571:
	s_add_u32 s6, s56, 0x100
	s_addc_u32 s7, s57, 0
	s_add_i32 s77, 0, 0x10000
	ds_read_b128 v[130:133], v240
	ds_read_b128 v[134:137], v240 offset:1024
	ds_read_b128 v[138:141], v240 offset:2048
	ds_read_b128 v[142:145], v240 offset:3072
	s_cmp_eq_u32 s76, 4
	s_cselect_b32 s63, s53, s7
	s_cselect_b32 s62, s52, s6
	s_cselect_b32 s59, s28, s51
	s_cselect_b32 s58, s29, s30
	ds_read_b128 v[164:167], v201
	ds_read_b128 v[168:171], v201 offset:1024
	ds_read_b128 v[172:175], v201 offset:2048
	ds_read_b128 v[186:189], v201 offset:3072
	ds_read_b128 v[202:205], v201 offset:4096
	ds_read_b128 v[206:209], v201 offset:5120
	ds_read_b128 v[210:213], v201 offset:6144
	ds_read_b128 v[214:217], v201 offset:7168
	s_add_u32 s98, s56, 0xffe7c000
	s_addc_u32 s99, s57, -1
	s_mov_b32 m0, s66
	s_nop 0
	global_load_lds_dwordx4 v160, s[98:99]
	s_mov_b32 m0, s67
	s_nop 0
	global_load_lds_dwordx4 v162, s[98:99]
	s_add_i32 m0, s38, 0xc000
	s_nop 0
	global_load_lds_dwordx4 v160, s[56:57]
	s_add_i32 m0, s38, 0xe000
	s_nop 0
	global_load_lds_dwordx4 v162, s[56:57]
	s_add_i32 s79, 0, 0x14000
	ds_read_b128 v[218:221], v240 offset:16384
	ds_read_b128 v[222:225], v240 offset:17408
	ds_read_b128 v[226:229], v240 offset:18432
	ds_read_b128 v[244:247], v240 offset:19456
	s_waitcnt lgkmcnt(0)
	s_barrier
; #define PG8_STAGE(bufoff, gbase, voff) do { _Pragma("unroll") for (int _i = 0; _i < 2; ++_i) \
;         __builtin_amdgcn_global_load_lds((const unsigned*)((const char*)(gbase) + (voff)[_i]), (LAS unsigned*)(lds + (bufoff) + ldsw + _i * 8192), 16, 0, 0); } while (0)
; #define PG8_LDA(dst, b, h) do { _Pragma("unroll") for (int m = 0; m < 4; ++m) _Pragma("unroll") for (int k = 0; k < 2; ++k) dst[m][k] = *(const LAS bf16x8*)(lds + PG8_SA(b, h) + aoff + m * 2048 + k * 1024); } while (0)
; #define PG8_LDB(dst, b, h) do { _Pragma("unroll") for (int n = 0; n < 2; ++n) _Pragma("unroll") for (int k = 0; k < 2; ++k) dst[n][k] = *(const LAS bf16x8*)(lds + PG8_SB(b, h) + boff + n * 2048 + k * 1024); } while (0)
; #define PG8_MMA(ai, bj, At, Bt) do { __builtin_amdgcn_s_setprio(1); _Pragma("unroll") for (int m = 0; m < 4; ++m) _Pragma("unroll") for (int n = 0; n < 2; ++n) _Pragma("unroll") for (int k = 0; k < 2; ++k) \
;         acc[ai][bj][m][n] = __builtin_amdgcn_mfma_f32_16x16x32_bf16(Bt[n][k], At[m][k], acc[ai][bj][m][n], 0, 0, 0); __builtin_amdgcn_s_setprio(0); } while (0)
; #define PG8_WAIT_V(n) asm volatile("s_waitcnt vmcnt(" #n ")" ::: "memory")
; #define PG8_WAIT_L(n) asm volatile("s_waitcnt lgkmcnt(" #n ")" ::: "memory")
; #define PG8_BAR __builtin_amdgcn_s_barrier()
; #define PG8_SCHED __builtin_amdgcn_sched_barrier(0)
; template <class Epi, class Sched>
; __device__ __forceinline__ void gemm_phase(LAS unsigned char* lds, const Gemm g, const Sched& S, const Epi& E) {
;     ...
;             PG8_WAIT_L(8); PG8_BAR; PG8_WAIT_L(0); PG8_MMA(0, 0, At, B0); PG8_BAR; PG8_SCHED;
;             PG8_LDB(B1, 0, 1); PG8_STAGE(PG8_SB(0, 0), b2, voffB);
;             PG8_BAR; PG8_WAIT_L(0); PG8_MMA(0, 1, At, B1); PG8_BAR;
;             PG8_LDA(At, 0, 1); PG8_STAGE(PG8_SA(0, 0), a2, voffA);
;             PG8_BAR; PG8_WAIT_L(0); PG8_MMA(1, 0, At, B0); PG8_BAR; PG8_SCHED;
;             PG8_STAGE(PG8_SB(0, 1), b2 + hstepB, voffB);
;             PG8_WAIT_V(6); PG8_BAR; PG8_MMA(1, 1, At, B1); PG8_BAR;
;             PG8_LDB(B0, 1, 0); PG8_SCHED; PG8_LDA(At, 1, 0); PG8_STAGE(PG8_SA(0, 1), a2 + hstepA, voffA);
	v_mfma_f32_16x16x32_bf16 v[126:129], v[130:133], v[164:167], v[126:129]
	v_mfma_f32_16x16x32_bf16 v[126:129], v[134:137], v[168:171], v[126:129]
	v_mfma_f32_16x16x32_bf16 v[118:121], v[130:133], v[172:175], v[118:121]
	v_mfma_f32_16x16x32_bf16 v[118:121], v[134:137], v[186:189], v[118:121]
	v_mfma_f32_16x16x32_bf16 v[110:113], v[130:133], v[202:205], v[110:113]
	v_mfma_f32_16x16x32_bf16 v[110:113], v[134:137], v[206:209], v[110:113]
	v_mfma_f32_16x16x32_bf16 v[102:105], v[130:133], v[210:213], v[102:105]
	v_mfma_f32_16x16x32_bf16 v[102:105], v[134:137], v[214:217], v[102:105]
	v_mfma_f32_16x16x32_bf16 v[122:125], v[138:141], v[164:167], v[122:125]
	v_mfma_f32_16x16x32_bf16 v[122:125], v[142:145], v[168:171], v[122:125]
	v_mfma_f32_16x16x32_bf16 v[114:117], v[138:141], v[172:175], v[114:117]
	v_mfma_f32_16x16x32_bf16 v[114:117], v[142:145], v[186:189], v[114:117]
	v_mfma_f32_16x16x32_bf16 v[106:109], v[138:141], v[202:205], v[106:109]
	v_mfma_f32_16x16x32_bf16 v[106:109], v[142:145], v[206:209], v[106:109]
	v_mfma_f32_16x16x32_bf16 v[98:101], v[138:141], v[210:213], v[98:101]
	v_mfma_f32_16x16x32_bf16 v[98:101], v[142:145], v[214:217], v[98:101]
	v_mfma_f32_16x16x32_bf16 v[94:97], v[218:221], v[164:167], v[94:97]
	v_mfma_f32_16x16x32_bf16 v[94:97], v[222:225], v[168:171], v[94:97]
	v_mfma_f32_16x16x32_bf16 v[86:89], v[218:221], v[172:175], v[86:89]
	v_mfma_f32_16x16x32_bf16 v[86:89], v[222:225], v[186:189], v[86:89]
	v_mfma_f32_16x16x32_bf16 v[78:81], v[218:221], v[202:205], v[78:81]
	v_mfma_f32_16x16x32_bf16 v[78:81], v[222:225], v[206:209], v[78:81]
	v_mfma_f32_16x16x32_bf16 v[70:73], v[218:221], v[210:213], v[70:73]
	v_mfma_f32_16x16x32_bf16 v[70:73], v[222:225], v[214:217], v[70:73]
	v_mfma_f32_16x16x32_bf16 v[90:93], v[226:229], v[164:167], v[90:93]
	v_mfma_f32_16x16x32_bf16 v[90:93], v[244:247], v[168:171], v[90:93]
	v_mfma_f32_16x16x32_bf16 v[82:85], v[226:229], v[172:175], v[82:85]
	v_mfma_f32_16x16x32_bf16 v[82:85], v[244:247], v[186:189], v[82:85]
	v_mfma_f32_16x16x32_bf16 v[74:77], v[226:229], v[202:205], v[74:77]
	v_mfma_f32_16x16x32_bf16 v[74:77], v[244:247], v[206:209], v[74:77]
	v_mfma_f32_16x16x32_bf16 v[66:69], v[226:229], v[210:213], v[66:69]
	v_mfma_f32_16x16x32_bf16 v[66:69], v[244:247], v[214:217], v[66:69]
	s_barrier
	ds_read_b128 v[164:167], v201 offset:16384
	ds_read_b128 v[168:171], v201 offset:17408
	ds_read_b128 v[172:175], v201 offset:18432
	ds_read_b128 v[186:189], v201 offset:19456
	ds_read_b128 v[202:205], v201 offset:20480
	ds_read_b128 v[206:209], v201 offset:21504
	ds_read_b128 v[210:213], v201 offset:22528
	ds_read_b128 v[214:217], v201 offset:23552
	s_add_i32 s56, s77, s33
	s_mov_b32 m0, s56
	s_nop 0
	global_load_lds_dwordx4 v152, s[58:59]
	s_add_i32 m0, s56, 0x2000
	s_nop 0
	global_load_lds_dwordx4 v148, s[58:59]
	s_add_u32 s56, s58, 0x20000
	s_addc_u32 s57, s59, 0
	s_add_i32 s77, s79, s33
	s_mov_b32 m0, s77
	s_nop 0
	global_load_lds_dwordx4 v152, s[56:57]
	s_add_i32 m0, s77, 0x2000
	s_nop 0
	global_load_lds_dwordx4 v148, s[56:57]
	s_waitcnt vmcnt(4)
	s_waitcnt lgkmcnt(0)
	s_barrier
	v_mfma_f32_16x16x32_bf16 v[62:65], v[130:133], v[164:167], v[62:65]
	v_mfma_f32_16x16x32_bf16 v[62:65], v[134:137], v[168:171], v[62:65]
	v_mfma_f32_16x16x32_bf16 v[54:57], v[130:133], v[172:175], v[54:57]
	v_mfma_f32_16x16x32_bf16 v[54:57], v[134:137], v[186:189], v[54:57]
	v_mfma_f32_16x16x32_bf16 v[46:49], v[130:133], v[202:205], v[46:49]
	v_mfma_f32_16x16x32_bf16 v[46:49], v[134:137], v[206:209], v[46:49]
	v_mfma_f32_16x16x32_bf16 v[38:41], v[130:133], v[210:213], v[38:41]
	v_mfma_f32_16x16x32_bf16 v[38:41], v[134:137], v[214:217], v[38:41]
	v_mfma_f32_16x16x32_bf16 v[58:61], v[138:141], v[164:167], v[58:61]
	v_mfma_f32_16x16x32_bf16 v[58:61], v[142:145], v[168:171], v[58:61]
	v_mfma_f32_16x16x32_bf16 v[50:53], v[138:141], v[172:175], v[50:53]
	v_mfma_f32_16x16x32_bf16 v[50:53], v[142:145], v[186:189], v[50:53]
	v_mfma_f32_16x16x32_bf16 v[42:45], v[138:141], v[202:205], v[42:45]
	v_mfma_f32_16x16x32_bf16 v[42:45], v[142:145], v[206:209], v[42:45]
	v_mfma_f32_16x16x32_bf16 v[34:37], v[138:141], v[210:213], v[34:37]
	v_mfma_f32_16x16x32_bf16 v[34:37], v[142:145], v[214:217], v[34:37]
	v_mfma_f32_16x16x32_bf16 v[30:33], v[218:221], v[164:167], v[30:33]
	v_mfma_f32_16x16x32_bf16 v[30:33], v[222:225], v[168:171], v[30:33]
	v_mfma_f32_16x16x32_bf16 v[22:25], v[218:221], v[172:175], v[22:25]
	v_mfma_f32_16x16x32_bf16 v[22:25], v[222:225], v[186:189], v[22:25]
	v_mfma_f32_16x16x32_bf16 v[14:17], v[218:221], v[202:205], v[14:17]
	v_mfma_f32_16x16x32_bf16 v[14:17], v[222:225], v[206:209], v[14:17]
	v_mfma_f32_16x16x32_bf16 v[6:9], v[218:221], v[210:213], v[6:9]
	v_mfma_f32_16x16x32_bf16 v[6:9], v[222:225], v[214:217], v[6:9]
	v_mfma_f32_16x16x32_bf16 v[26:29], v[226:229], v[164:167], v[26:29]
	v_mfma_f32_16x16x32_bf16 v[26:29], v[244:247], v[168:171], v[26:29]
	v_mfma_f32_16x16x32_bf16 v[18:21], v[226:229], v[172:175], v[18:21]
	v_mfma_f32_16x16x32_bf16 v[18:21], v[244:247], v[186:189], v[18:21]
	v_mfma_f32_16x16x32_bf16 v[10:13], v[226:229], v[202:205], v[10:13]
	v_mfma_f32_16x16x32_bf16 v[10:13], v[244:247], v[206:209], v[10:13]
	v_mfma_f32_16x16x32_bf16 v[2:5], v[226:229], v[210:213], v[2:5]
	v_mfma_f32_16x16x32_bf16 v[2:5], v[244:247], v[214:217], v[2:5]
	s_add_i32 s77, 0, 0x18000
	s_barrier
; #define PG8_STAGE(bufoff, gbase, voff) do { _Pragma("unroll") for (int _i = 0; _i < 2; ++_i) \
;         __builtin_amdgcn_global_load_lds((const unsigned*)((const char*)(gbase) + (voff)[_i]), (LAS unsigned*)(lds + (bufoff) + ldsw + _i * 8192), 16, 0, 0); } while (0)
; #define PG8_LDA(dst, b, h) do { _Pragma("unroll") for (int m = 0; m < 4; ++m) _Pragma("unroll") for (int k = 0; k < 2; ++k) dst[m][k] = *(const LAS bf16x8*)(lds + PG8_SA(b, h) + aoff + m * 2048 + k * 1024); } while (0)
; #define PG8_LDB(dst, b, h) do { _Pragma("unroll") for (int n = 0; n < 2; ++n) _Pragma("unroll") for (int k = 0; k < 2; ++k) dst[n][k] = *(const LAS bf16x8*)(lds + PG8_SB(b, h) + boff + n * 2048 + k * 1024); } while (0)
; #define PG8_MMA(ai, bj, At, Bt) do { __builtin_amdgcn_s_setprio(1); _Pragma("unroll") for (int m = 0; m < 4; ++m) _Pragma("unroll") for (int n = 0; n < 2; ++n) _Pragma("unroll") for (int k = 0; k < 2; ++k) \
;         acc[ai][bj][m][n] = __builtin_amdgcn_mfma_f32_16x16x32_bf16(Bt[n][k], At[m][k], acc[ai][bj][m][n], 0, 0, 0); __builtin_amdgcn_s_setprio(0); } while (0)
; #define PG8_WAIT_V(n) asm volatile("s_waitcnt vmcnt(" #n ")" ::: "memory")
; #define PG8_WAIT_L(n) asm volatile("s_waitcnt lgkmcnt(" #n ")" ::: "memory")
; #define PG8_BAR __builtin_amdgcn_s_barrier()
; #define PG8_SCHED __builtin_amdgcn_sched_barrier(0)
; template <class Epi, class Sched>
; __device__ __forceinline__ void gemm_phase(LAS unsigned char* lds, const Gemm g, const Sched& S, const Epi& E) {
;     ...
;             PG8_LDB(B0, 1, 0); PG8_SCHED; PG8_LDA(At, 1, 0); PG8_STAGE(PG8_SA(0, 1), a2 + hstepA, voffA);
;             PG8_WAIT_L(8); PG8_BAR; PG8_WAIT_L(0); PG8_MMA(0, 0, At, B0); PG8_BAR; PG8_SCHED;
;             PG8_LDB(B1, 1, 1); PG8_STAGE(PG8_SB(1, 0), b3, voffB);
;             PG8_BAR; PG8_WAIT_L(0); PG8_MMA(0, 1, At, B1); PG8_BAR;
;             PG8_LDA(At, 1, 1); PG8_STAGE(PG8_SA(1, 0), a3, voffA);
;             PG8_BAR; PG8_WAIT_L(0); PG8_MMA(1, 0, At, B0); PG8_BAR; PG8_SCHED;
;             PG8_STAGE(PG8_SB(1, 1), b3 + hstepB, voffB);
;             PG8_WAIT_V(6); PG8_BAR; PG8_MMA(1, 1, At, B1); PG8_BAR;
	ds_read_b128 v[130:133], v240 offset:32768
	ds_read_b128 v[134:137], v240 offset:33792
	ds_read_b128 v[138:141], v240 offset:34816
	ds_read_b128 v[142:145], v240 offset:35840
	ds_read_b128 v[164:167], v201 offset:32768
	ds_read_b128 v[168:171], v201 offset:33792
	ds_read_b128 v[172:175], v201 offset:34816
	ds_read_b128 v[186:189], v201 offset:35840
	ds_read_b128 v[202:205], v201 offset:36864
	ds_read_b128 v[206:209], v201 offset:37888
	ds_read_b128 v[210:213], v201 offset:38912
	ds_read_b128 v[214:217], v201 offset:39936
	s_mov_b32 m0, s38
	s_nop 0
	global_load_lds_dwordx4 v154, s[62:63]
	s_mov_b32 m0, s39
	s_nop 0
	global_load_lds_dwordx4 v150, s[62:63]
	s_add_u32 s56, s62, 0x184000
	s_addc_u32 s57, s63, 0
	s_mov_b32 m0, s46
	s_nop 0
	global_load_lds_dwordx4 v154, s[56:57]
	s_mov_b32 m0, s64
	s_nop 0
	global_load_lds_dwordx4 v150, s[56:57]
	s_add_i32 s62, 0, 0x1c000
	ds_read_b128 v[218:221], v240 offset:49152
	ds_read_b128 v[222:225], v240 offset:50176
	ds_read_b128 v[226:229], v240 offset:51200
	ds_read_b128 v[244:247], v240 offset:52224
	s_waitcnt lgkmcnt(0)
	s_barrier
	v_mfma_f32_16x16x32_bf16 v[126:129], v[130:133], v[164:167], v[126:129]
	v_mfma_f32_16x16x32_bf16 v[126:129], v[134:137], v[168:171], v[126:129]
	v_mfma_f32_16x16x32_bf16 v[118:121], v[130:133], v[172:175], v[118:121]
	v_mfma_f32_16x16x32_bf16 v[118:121], v[134:137], v[186:189], v[118:121]
	v_mfma_f32_16x16x32_bf16 v[110:113], v[130:133], v[202:205], v[110:113]
	v_mfma_f32_16x16x32_bf16 v[110:113], v[134:137], v[206:209], v[110:113]
	v_mfma_f32_16x16x32_bf16 v[102:105], v[130:133], v[210:213], v[102:105]
	v_mfma_f32_16x16x32_bf16 v[102:105], v[134:137], v[214:217], v[102:105]
	v_mfma_f32_16x16x32_bf16 v[122:125], v[138:141], v[164:167], v[122:125]
	v_mfma_f32_16x16x32_bf16 v[122:125], v[142:145], v[168:171], v[122:125]
	v_mfma_f32_16x16x32_bf16 v[114:117], v[138:141], v[172:175], v[114:117]
	v_mfma_f32_16x16x32_bf16 v[114:117], v[142:145], v[186:189], v[114:117]
	v_mfma_f32_16x16x32_bf16 v[106:109], v[138:141], v[202:205], v[106:109]
	v_mfma_f32_16x16x32_bf16 v[106:109], v[142:145], v[206:209], v[106:109]
	v_mfma_f32_16x16x32_bf16 v[98:101], v[138:141], v[210:213], v[98:101]
	v_mfma_f32_16x16x32_bf16 v[98:101], v[142:145], v[214:217], v[98:101]
	v_mfma_f32_16x16x32_bf16 v[94:97], v[218:221], v[164:167], v[94:97]
	v_mfma_f32_16x16x32_bf16 v[94:97], v[222:225], v[168:171], v[94:97]
	v_mfma_f32_16x16x32_bf16 v[86:89], v[218:221], v[172:175], v[86:89]
	v_mfma_f32_16x16x32_bf16 v[86:89], v[222:225], v[186:189], v[86:89]
	v_mfma_f32_16x16x32_bf16 v[78:81], v[218:221], v[202:205], v[78:81]
	v_mfma_f32_16x16x32_bf16 v[78:81], v[222:225], v[206:209], v[78:81]
	v_mfma_f32_16x16x32_bf16 v[70:73], v[218:221], v[210:213], v[70:73]
	v_mfma_f32_16x16x32_bf16 v[70:73], v[222:225], v[214:217], v[70:73]
	v_mfma_f32_16x16x32_bf16 v[90:93], v[226:229], v[164:167], v[90:93]
	v_mfma_f32_16x16x32_bf16 v[90:93], v[244:247], v[168:171], v[90:93]
	v_mfma_f32_16x16x32_bf16 v[82:85], v[226:229], v[172:175], v[82:85]
	v_mfma_f32_16x16x32_bf16 v[82:85], v[244:247], v[186:189], v[82:85]
	v_mfma_f32_16x16x32_bf16 v[74:77], v[226:229], v[202:205], v[74:77]
	v_mfma_f32_16x16x32_bf16 v[74:77], v[244:247], v[206:209], v[74:77]
	v_mfma_f32_16x16x32_bf16 v[66:69], v[226:229], v[210:213], v[66:69]
	v_mfma_f32_16x16x32_bf16 v[66:69], v[244:247], v[214:217], v[66:69]
	s_barrier
	ds_read_b128 v[164:167], v201 offset:49152
	ds_read_b128 v[168:171], v201 offset:50176
	ds_read_b128 v[172:175], v201 offset:51200
	ds_read_b128 v[186:189], v201 offset:52224
	ds_read_b128 v[202:205], v201 offset:53248
	ds_read_b128 v[206:209], v201 offset:54272
	ds_read_b128 v[210:213], v201 offset:55296
	ds_read_b128 v[214:217], v201 offset:56320
	s_add_u32 s98, s58, 0x80
	s_addc_u32 s99, s59, 0
	s_add_i32 s56, s77, s33
	s_mov_b32 m0, s56
	s_nop 0
	global_load_lds_dwordx4 v152, s[98:99]
	s_add_i32 m0, s56, 0x2000
	s_nop 0
	global_load_lds_dwordx4 v148, s[98:99]
	s_add_u32 s56, s58, 0x20080
	s_addc_u32 s57, s59, 0
	s_add_i32 s58, s62, s33
	s_mov_b32 m0, s58
	s_nop 0
	global_load_lds_dwordx4 v152, s[56:57]
	s_add_i32 m0, s58, 0x2000
	s_nop 0
	global_load_lds_dwordx4 v148, s[56:57]
	s_waitcnt vmcnt(4)
	s_waitcnt lgkmcnt(0)
	s_barrier
	v_mfma_f32_16x16x32_bf16 v[62:65], v[130:133], v[164:167], v[62:65]
	v_mfma_f32_16x16x32_bf16 v[62:65], v[134:137], v[168:171], v[62:65]
	v_mfma_f32_16x16x32_bf16 v[54:57], v[130:133], v[172:175], v[54:57]
	v_mfma_f32_16x16x32_bf16 v[54:57], v[134:137], v[186:189], v[54:57]
	v_mfma_f32_16x16x32_bf16 v[46:49], v[130:133], v[202:205], v[46:49]
	v_mfma_f32_16x16x32_bf16 v[46:49], v[134:137], v[206:209], v[46:49]
	v_mfma_f32_16x16x32_bf16 v[38:41], v[130:133], v[210:213], v[38:41]
	v_mfma_f32_16x16x32_bf16 v[38:41], v[134:137], v[214:217], v[38:41]
	v_mfma_f32_16x16x32_bf16 v[58:61], v[138:141], v[164:167], v[58:61]
	v_mfma_f32_16x16x32_bf16 v[58:61], v[142:145], v[168:171], v[58:61]
	v_mfma_f32_16x16x32_bf16 v[50:53], v[138:141], v[172:175], v[50:53]
	v_mfma_f32_16x16x32_bf16 v[50:53], v[142:145], v[186:189], v[50:53]
	v_mfma_f32_16x16x32_bf16 v[42:45], v[138:141], v[202:205], v[42:45]
	v_mfma_f32_16x16x32_bf16 v[42:45], v[142:145], v[206:209], v[42:45]
	v_mfma_f32_16x16x32_bf16 v[34:37], v[138:141], v[210:213], v[34:37]
	v_mfma_f32_16x16x32_bf16 v[34:37], v[142:145], v[214:217], v[34:37]
	v_mfma_f32_16x16x32_bf16 v[30:33], v[218:221], v[164:167], v[30:33]
	v_mfma_f32_16x16x32_bf16 v[30:33], v[222:225], v[168:171], v[30:33]
	v_mfma_f32_16x16x32_bf16 v[22:25], v[218:221], v[172:175], v[22:25]
	v_mfma_f32_16x16x32_bf16 v[22:25], v[222:225], v[186:189], v[22:25]
	v_mfma_f32_16x16x32_bf16 v[14:17], v[218:221], v[202:205], v[14:17]
	v_mfma_f32_16x16x32_bf16 v[14:17], v[222:225], v[206:209], v[14:17]
	v_mfma_f32_16x16x32_bf16 v[6:9], v[218:221], v[210:213], v[6:9]
	v_mfma_f32_16x16x32_bf16 v[6:9], v[222:225], v[214:217], v[6:9]
	v_mfma_f32_16x16x32_bf16 v[26:29], v[226:229], v[164:167], v[26:29]
	v_mfma_f32_16x16x32_bf16 v[26:29], v[244:247], v[168:171], v[26:29]
	v_mfma_f32_16x16x32_bf16 v[18:21], v[226:229], v[172:175], v[18:21]
	v_mfma_f32_16x16x32_bf16 v[18:21], v[244:247], v[186:189], v[18:21]
	v_mfma_f32_16x16x32_bf16 v[10:13], v[226:229], v[202:205], v[10:13]
	v_mfma_f32_16x16x32_bf16 v[10:13], v[244:247], v[206:209], v[10:13]
	v_mfma_f32_16x16x32_bf16 v[2:5], v[226:229], v[210:213], v[2:5]
	v_mfma_f32_16x16x32_bf16 v[2:5], v[244:247], v[214:217], v[2:5]
	s_add_i32 s76, s76, 2
	s_add_u32 s30, s30, 0x100
	s_addc_u32 s51, s51, 0
	s_cmp_gt_u32 s76, 5
	s_mov_b64 s[56:57], s[6:7]
	s_barrier
; __device__ __forceinline__ unsigned cvt_pk_bf16(float lo, float hi) { const f32x2_t v = {lo, hi}; return __builtin_bit_cast(unsigned, __builtin_convertvector(v, bf16x2_t)); }
; #define PG8_WAIT_V(n) asm volatile("s_waitcnt vmcnt(" #n ")" ::: "memory")
; #define PG8_BAR __builtin_amdgcn_s_barrier()
;     __device__ __forceinline__ void operator()(f32x4 (&acc)[2][2][4][2], const Unit& u, int wr, int wc, int fr, int fq) const {
;         const int row0 = u.pm * BM + wr * 64 + fr;
; #pragma unroll
;         for (int ai = 0; ai < 2; ++ai) {
;             f32x4 s0[4], s1[4]; float rstd[4];
; #pragma unroll
;             for (int m = 0; m < 4; ++m) { const float* sp = SSQ + (size_t)(row0 + ai * HALF + m * 16) * 16 + 8; s0[m] = *(const f32x4*)sp; s1[m] = *(const f32x4*)(sp + 4); }
; #pragma unroll
;             for (int m = 0; m < 4; ++m) rstd[m] = rsqrtf(((s0[m][0] + s0[m][1]) + (s0[m][2] + s0[m][3]) + (s1[m][0] + s1[m][1]) + (s1[m][2] + s1[m][3])) * (1.0f / 512.0f) + EPS);
;             if (u.pn < 4) {
; #pragma unroll
;                 for (int m = 0; m < 4; ++m)
; #pragma unroll
;                     for (int bj = 0; bj < 2; ++bj) { const int c0 = u.pn * BM + bj * HALF + wc * 32 + 8 * fq; const f32x4 v0 = acc[ai][bj][m][0] * rstd[m], v1 = acc[ai][bj][m][1] * rstd[m];
;                         u32x4 w; w.x = cvt_pk_bf16(v0[0], v0[1]); w.y = cvt_pk_bf16(v0[2], v0[3]); w.z = cvt_pk_bf16(v1[0], v1[1]); w.w = cvt_pk_bf16(v1[2], v1[3]);
;                         *(u32x4*)(KM + (size_t)(row0 + ai * HALF + m * 16) * 1536 + (c0 >> 7) * 192 + (c0 & 127)) = w; }
;             } else {
; #pragma unroll
;                 for (int m = 0; m < 4; ++m)
; #pragma unroll
;                     for (int bj = 0; bj < 2; ++bj) { const int c0 = u.pn * BM + bj * HALF + wc * 32 + 8 * fq; const f32x4 v0 = acc[ai][bj][m][0] * rstd[m], v1 = acc[ai][bj][m][1] * rstd[m];
;                         u32x4 w; w.x = cvt_pk_bf16(v0[0], v0[1]); w.y = cvt_pk_bf16(v0[2], v0[3]); w.z = cvt_pk_bf16(v1[0], v1[1]); w.w = cvt_pk_bf16(v1[2], v1[3]);
;                         *(u32x4*)(VM + (size_t)(row0 + ai * HALF + m * 16) * 1024 + (c0 - 1024)) = w; }
; template <class Epi, class Sched>
; __device__ __forceinline__ void gemm_phase(LAS unsigned char* lds, const Gemm g, const Sched& S, const Epi& E) {
;     ...
;             PG8_WAIT_V(6); PG8_BAR; PG8_MMA(1, 1, At, B1); PG8_BAR;
;         }
	s_cbranch_scc0 .LBB0_571
	v_lshl_add_u32 v164, s72, 8, v196
	v_ashrrev_i32_e32 v165, 31, v164
	v_lshlrev_b64 v[130:131], 6, v[164:165]
	v_readlane_b32 s76, v255, 26
	s_cmp_gt_i32 s71, 5
	v_lshl_add_u64 v[172:173], s[26:27], 0, v[130:131]
	s_mov_b64 s[6:7], -1
	v_or_b32_e32 v168, 16, v164
	v_or_b32_e32 v166, 32, v164
	v_or_b32_e32 v170, 48, v164
	v_readlane_b32 s77, v255, 27
	s_cbranch_scc0 .LBB0_582
	v_ashrrev_i32_e32 v169, 31, v168
	v_lshlrev_b64 v[130:131], 6, v[168:169]
	v_lshl_add_u64 v[130:131], s[26:27], 0, v[130:131]
	global_load_dwordx4 v[174:177], v[172:173], off offset:48
	global_load_dwordx4 v[186:189], v[172:173], off offset:32
	global_load_dwordx4 v[202:205], v[130:131], off offset:48
	global_load_dwordx4 v[206:209], v[130:131], off offset:32
	v_ashrrev_i32_e32 v167, 31, v166
	v_lshlrev_b64 v[130:131], 6, v[166:167]
	v_lshl_add_u64 v[130:131], s[26:27], 0, v[130:131]
	v_ashrrev_i32_e32 v171, 31, v170
	global_load_dwordx4 v[134:137], v[130:131], off offset:48
	global_load_dwordx4 v[138:141], v[130:131], off offset:32
	v_lshlrev_b64 v[130:131], 6, v[170:171]
	v_lshl_add_u64 v[142:143], s[26:27], 0, v[130:131]
	global_load_dwordx4 v[130:133], v[142:143], off offset:48
	s_nop 0
	global_load_dwordx4 v[142:145], v[142:143], off offset:32
	s_mov_b32 s6, 0x3727c5ac
	s_add_i32 s28, s71, -6
	s_cmp_gt_u32 s28, 3
	s_cselect_b64 s[56:57], -1, 0
	s_cmp_lt_u32 s28, 4
	v_lshl_or_b32 v178, s28, 8, v158
	s_waitcnt vmcnt(0)
	v_mov_b32_e32 v184, v176
	v_mov_b32_e32 v182, v187
	v_mov_b32_e32 v183, v188
	v_mov_b32_e32 v187, v189
	v_mov_b32_e32 v185, v174
	v_mov_b32_e32 v174, v177
	v_mov_b32_e32 v176, v207
	v_mov_b32_e32 v177, v208
	v_mov_b32_e32 v207, v209
	v_pk_add_f32 v[182:183], v[182:183], v[186:187]
	v_pk_add_f32 v[174:175], v[184:185], v[174:175]
	v_pk_add_f32 v[176:177], v[176:177], v[206:207]
	v_mov_b32_e32 v184, v204
	v_mov_b32_e32 v185, v202
	v_mov_b32_e32 v202, v205
	v_pk_add_f32 v[184:185], v[184:185], v[202:203]
	v_mov_b32_e32 v186, v176
	v_mov_b32_e32 v187, v182
	v_mov_b32_e32 v182, v177
	v_pk_add_f32 v[176:177], v[186:187], v[182:183]
	v_mov_b32_e32 v182, v185
	v_mov_b32_e32 v183, v175
	v_pk_add_f32 v[176:177], v[176:177], v[182:183]
	v_mov_b32_e32 v185, v174
	v_pk_add_f32 v[174:175], v[184:185], v[176:177]
	v_mov_b64_e32 v[186:187], s[6:7]
	v_pk_fma_f32 v[176:177], v[174:175], s[42:43], v[186:187] op_sel_hi:[1,0,0]
	v_mov_b32_e32 v182, v139
	v_mul_f32_e32 v174, 0x4b800000, v177
	v_cmp_gt_f32_e64 s[6:7], s85, v177
	v_mov_b32_e32 v183, v140
	v_mov_b32_e32 v139, v141
	v_mov_b32_e32 v140, v136
	v_mov_b32_e32 v141, v134
	v_mov_b32_e32 v134, v137
	v_mov_b32_e32 v136, v143
	v_mov_b32_e32 v137, v144
	v_mov_b32_e32 v143, v145
	v_cndmask_b32_e64 v174, v177, v174, s[6:7]
	v_pk_add_f32 v[138:139], v[182:183], v[138:139]
	v_pk_add_f32 v[134:135], v[140:141], v[134:135]
	v_pk_add_f32 v[136:137], v[136:137], v[142:143]
	v_mov_b32_e32 v140, v132
	v_mov_b32_e32 v141, v130
	v_mov_b32_e32 v130, v133
	v_rsq_f32_e32 v174, v174
	v_pk_add_f32 v[130:131], v[140:141], v[130:131]
	v_mov_b32_e32 v132, v136
	v_mov_b32_e32 v133, v138
	v_mov_b32_e32 v138, v137
	v_pk_add_f32 v[132:133], v[132:133], v[138:139]
	v_mov_b32_e32 v136, v131
	v_mov_b32_e32 v137, v135
	v_pk_add_f32 v[132:133], v[132:133], v[136:137]
	v_mov_b32_e32 v131, v134
	v_pk_add_f32 v[130:131], v[130:131], v[132:133]
	v_mul_f32_e32 v175, 0x45800000, v174
	v_pk_fma_f32 v[130:131], v[130:131], s[42:43], v[186:187] op_sel_hi:[1,0,0]
	v_cmp_gt_f32_e32 vcc, s85, v176
	v_cndmask_b32_e64 v174, v174, v175, s[6:7]
	v_mul_f32_e32 v175, 0x4b800000, v176
	v_mul_f32_e32 v132, 0x4b800000, v131
	v_cmp_gt_f32_e64 s[6:7], s85, v131
	v_cndmask_b32_e32 v175, v176, v175, vcc
	v_rsq_f32_e32 v175, v175
	v_cndmask_b32_e64 v131, v131, v132, s[6:7]
	v_rsq_f32_e32 v131, v131
	v_mul_f32_e32 v176, 0x45800000, v175
	v_cndmask_b32_e32 v176, v175, v176, vcc
	v_mul_f32_e32 v132, 0x45800000, v131
	v_cmp_gt_f32_e32 vcc, s85, v130
	v_cndmask_b32_e64 v138, v131, v132, s[6:7]
	v_mul_f32_e32 v131, 0x4b800000, v130
	v_cndmask_b32_e32 v130, v130, v131, vcc
	v_rsq_f32_e32 v130, v130
	v_pk_mul_f32 v[132:133], v[128:129], v[174:175] op_sel_hi:[1,0]
	v_pk_mul_f32 v[134:135], v[124:125], v[174:175] op_sel_hi:[1,0]
	v_pk_mul_f32 v[136:137], v[122:123], v[174:175] op_sel_hi:[1,0]
	v_mul_f32_e32 v131, 0x45800000, v130
	v_cndmask_b32_e32 v140, v130, v131, vcc
	v_pk_mul_f32 v[130:131], v[126:127], v[174:175] op_sel_hi:[1,0]
	v_pk_mul_f32 v[142:143], v[92:93], v[174:175] op_sel_hi:[1,0]
	v_cvt_pk_bf16_f32 v130, v130, v131
	v_cvt_pk_bf16_f32 v131, v132, v133
	v_cvt_pk_bf16_f32 v132, v136, v137
	v_cvt_pk_bf16_f32 v133, v134, v135
	v_pk_mul_f32 v[136:137], v[96:97], v[174:175] op_sel_hi:[1,0]
	v_pk_mul_f32 v[134:135], v[94:95], v[174:175] op_sel_hi:[1,0]
	v_pk_mul_f32 v[144:145], v[90:91], v[174:175] op_sel_hi:[1,0]
	v_cvt_pk_bf16_f32 v134, v134, v135
	v_cvt_pk_bf16_f32 v135, v136, v137
	v_cvt_pk_bf16_f32 v136, v144, v145
	v_cvt_pk_bf16_f32 v137, v142, v143
	s_mov_b64 s[6:7], -1
	s_cbranch_scc1 .LBB0_575
; __device__ __forceinline__ unsigned cvt_pk_bf16(float lo, float hi) { const f32x2_t v = {lo, hi}; return __builtin_bit_cast(unsigned, __builtin_convertvector(v, bf16x2_t)); }
;     __device__ __forceinline__ void operator()(f32x4 (&acc)[2][2][4][2], const Unit& u, int wr, int wc, int fr, int fq) const {
;     ...
;             } else {
; #pragma unroll
;                 for (int m = 0; m < 4; ++m)
; #pragma unroll
;                     for (int bj = 0; bj < 2; ++bj) { const int c0 = u.pn * BM + bj * HALF + wc * 32 + 8 * fq; const f32x4 v0 = acc[ai][bj][m][0] * rstd[m], v1 = acc[ai][bj][m][1] * rstd[m];
;                         u32x4 w; w.x = cvt_pk_bf16(v0[0], v0[1]); w.y = cvt_pk_bf16(v0[2], v0[3]); w.z = cvt_pk_bf16(v1[0], v1[1]); w.w = cvt_pk_bf16(v1[2], v1[3]);
;                         *(u32x4*)(VM + (size_t)(row0 + ai * HALF + m * 16) * 1024 + (c0 - 1024)) = w; }
	v_lshlrev_b64 v[142:143], 11, v[164:165]
	v_lshl_add_u64 v[142:143], s[24:25], 0, v[142:143]
	v_lshlrev_b64 v[174:175], 1, v[178:179]
	v_lshl_add_u64 v[142:143], v[142:143], 0, v[174:175]
	v_lshlrev_b64 v[182:183], 11, v[168:169]
	global_store_dwordx4 v[142:143], v[130:133], off offset:-2048
	global_store_dwordx4 v[142:143], v[134:137], off offset:-1792
	v_pk_mul_f32 v[144:145], v[120:121], v[176:177] op_sel_hi:[1,0]
	v_pk_mul_f32 v[142:143], v[118:119], v[176:177] op_sel_hi:[1,0]
	v_pk_mul_f32 v[184:185], v[116:117], v[176:177] op_sel_hi:[1,0]
	v_pk_mul_f32 v[186:187], v[114:115], v[176:177] op_sel_hi:[1,0]
	v_lshl_add_u64 v[182:183], s[24:25], 0, v[182:183]
	v_cvt_pk_bf16_f32 v142, v142, v143
	v_cvt_pk_bf16_f32 v143, v144, v145
	v_cvt_pk_bf16_f32 v144, v186, v187
	v_cvt_pk_bf16_f32 v145, v184, v185
	v_lshl_add_u64 v[182:183], v[182:183], 0, v[174:175]
	global_store_dwordx4 v[182:183], v[142:145], off offset:-2048
	v_pk_mul_f32 v[184:185], v[84:85], v[176:177] op_sel_hi:[1,0]
	v_pk_mul_f32 v[186:187], v[82:83], v[176:177] op_sel_hi:[1,0]
	v_pk_mul_f32 v[144:145], v[88:89], v[176:177] op_sel_hi:[1,0]
	v_pk_mul_f32 v[142:143], v[86:87], v[176:177] op_sel_hi:[1,0]
	s_mov_b64 s[6:7], 0
	v_cvt_pk_bf16_f32 v142, v142, v143
	v_cvt_pk_bf16_f32 v143, v144, v145
	v_cvt_pk_bf16_f32 v144, v186, v187
	v_cvt_pk_bf16_f32 v145, v184, v185
	global_store_dwordx4 v[182:183], v[142:145], off offset:-1792
	v_lshlrev_b64 v[182:183], 11, v[166:167]
	v_pk_mul_f32 v[184:185], v[108:109], v[138:139] op_sel_hi:[1,0]
	v_pk_mul_f32 v[144:145], v[112:113], v[138:139] op_sel_hi:[1,0]
	v_pk_mul_f32 v[142:143], v[110:111], v[138:139] op_sel_hi:[1,0]
	v_pk_mul_f32 v[186:187], v[106:107], v[138:139] op_sel_hi:[1,0]
	v_lshl_add_u64 v[182:183], s[24:25], 0, v[182:183]
	v_cvt_pk_bf16_f32 v142, v142, v143
	v_cvt_pk_bf16_f32 v143, v144, v145
	v_cvt_pk_bf16_f32 v144, v186, v187
	v_cvt_pk_bf16_f32 v145, v184, v185
	v_lshl_add_u64 v[182:183], v[182:183], 0, v[174:175]
	global_store_dwordx4 v[182:183], v[142:145], off offset:-2048
	v_pk_mul_f32 v[184:185], v[76:77], v[138:139] op_sel_hi:[1,0]
	v_pk_mul_f32 v[186:187], v[74:75], v[138:139] op_sel_hi:[1,0]
	v_pk_mul_f32 v[144:145], v[80:81], v[138:139] op_sel_hi:[1,0]
	v_pk_mul_f32 v[142:143], v[78:79], v[138:139] op_sel_hi:[1,0]
	s_nop 0
	v_cvt_pk_bf16_f32 v142, v142, v143
	v_cvt_pk_bf16_f32 v143, v144, v145
	v_cvt_pk_bf16_f32 v144, v186, v187
	v_cvt_pk_bf16_f32 v145, v184, v185
	global_store_dwordx4 v[182:183], v[142:145], off offset:-1792
	v_lshlrev_b64 v[182:183], 11, v[170:171]
	v_pk_mul_f32 v[184:185], v[100:101], v[140:141] op_sel_hi:[1,0]
	v_pk_mul_f32 v[144:145], v[104:105], v[140:141] op_sel_hi:[1,0]
	v_pk_mul_f32 v[142:143], v[102:103], v[140:141] op_sel_hi:[1,0]
	v_pk_mul_f32 v[186:187], v[98:99], v[140:141] op_sel_hi:[1,0]
	v_lshl_add_u64 v[182:183], s[24:25], 0, v[182:183]
	v_cvt_pk_bf16_f32 v142, v142, v143
	v_cvt_pk_bf16_f32 v143, v144, v145
	v_cvt_pk_bf16_f32 v144, v186, v187
	v_cvt_pk_bf16_f32 v145, v184, v185
	v_lshl_add_u64 v[174:175], v[182:183], 0, v[174:175]
	global_store_dwordx4 v[174:175], v[142:145], off offset:-2048
	v_pk_mul_f32 v[182:183], v[68:69], v[140:141] op_sel_hi:[1,0]
	v_pk_mul_f32 v[184:185], v[66:67], v[140:141] op_sel_hi:[1,0]
	v_pk_mul_f32 v[144:145], v[72:73], v[140:141] op_sel_hi:[1,0]
	v_pk_mul_f32 v[142:143], v[70:71], v[140:141] op_sel_hi:[1,0]
	s_nop 0
	v_cvt_pk_bf16_f32 v142, v142, v143
	v_cvt_pk_bf16_f32 v143, v144, v145
	v_cvt_pk_bf16_f32 v144, v184, v185
	v_cvt_pk_bf16_f32 v145, v182, v183
	global_store_dwordx4 v[174:175], v[142:145], off offset:-1792

; #define PG8_STAGE(bufoff, gbase, voff) do { _Pragma("unroll") for (int _i = 0; _i < 2; ++_i) \
;         __builtin_amdgcn_global_load_lds((const unsigned*)((const char*)(gbase) + (voff)[_i]), (LAS unsigned*)(lds + (bufoff) + ldsw + _i * 8192), 16, 0, 0); } while (0)
; #define PG8_LDA(dst, b, h) do { _Pragma("unroll") for (int m = 0; m < 4; ++m) _Pragma("unroll") for (int k = 0; k < 2; ++k) dst[m][k] = *(const LAS bf16x8*)(lds + PG8_SA(b, h) + aoff + m * 2048 + k * 1024); } while (0)
; #define PG8_LDB(dst, b, h) do { _Pragma("unroll") for (int n = 0; n < 2; ++n) _Pragma("unroll") for (int k = 0; k < 2; ++k) dst[n][k] = *(const LAS bf16x8*)(lds + PG8_SB(b, h) + boff + n * 2048 + k * 1024); } while (0)
; #define PG8_BAR __builtin_amdgcn_s_barrier()
; template <class Epi, class Sched>
; __device__ __forceinline__ void gemm_phase(LAS unsigned char* lds, const Gemm g, const Sched& S, const Epi& E) {
;     ...
;         const bool has_next = S.next(ui + 1, nxt);
;         const char* nA = has_next ? (const char*)g.A + (size_t)nxt.seg * g.segA + (size_t)nxt.pm * tstepA : cA;
;         const char* nB = has_next ? (const char*)g.Bt + (size_t)nxt.seg * g.segB + (size_t)nxt.pn * tstepB : cB;
;         const int ntu = cur.nt ? cur.nt : nt;
;         for (int t = 0; t < ntu; t += 2) {
;             const bool last = (t == ntu - 2);
;             const char* a1 = cA + (size_t)(t + 1) * kstep;
;             const char* a2 = last ? nA : cA + (size_t)(t + 2) * kstep; const char* b2 = last ? nB : cB + (size_t)(t + 2) * kstep;
;             const char* a3 = a2 + kstep; const char* b3 = b2 + kstep;
;             if (last && has_next) S.a_ready(nxt);
;             PG8_LDB(B0, 0, 0); PG8_SCHED; PG8_LDA(At, 0, 0); PG8_STAGE(PG8_SA(1, 1), a1 + hstepA, voffA);
;             PG8_WAIT_L(8); PG8_BAR; PG8_WAIT_L(0); PG8_MMA(0, 0, At, B0); PG8_BAR; PG8_SCHED;
;             PG8_LDB(B1, 0, 1); PG8_STAGE(PG8_SB(0, 0), b2, voffB);
;             PG8_BAR; PG8_WAIT_L(0); PG8_MMA(0, 1, At, B1); PG8_BAR;
;             PG8_LDA(At, 0, 1); PG8_STAGE(PG8_SA(0, 0), a2, voffA);
;             PG8_BAR; PG8_WAIT_L(0); PG8_MMA(1, 0, At, B0); PG8_BAR; PG8_SCHED;
;             PG8_STAGE(PG8_SB(0, 1), b2 + hstepB, voffB);
;             PG8_WAIT_V(6); PG8_BAR; PG8_MMA(1, 1, At, B1); PG8_BAR;
;             PG8_LDB(B0, 1, 0); PG8_SCHED; PG8_LDA(At, 1, 0); PG8_STAGE(PG8_SA(0, 1), a2 + hstepA, voffA);
.LBB0_870:
	s_lshl_b64 s[28:29], s[54:55], 22
	s_add_u32 s6, s38, s28
	s_addc_u32 s7, s72, s29
	s_ashr_i32 s63, s62, 31
	s_lshl_b64 s[28:29], s[62:63], 19
	s_add_u32 s70, s6, s28
	s_addc_u32 s71, s7, s29
	s_and_b64 s[28:29], s[52:53], exec
	s_cselect_b32 s13, s71, s27
	s_cselect_b32 s21, s70, s26
	s_cmp_lg_u32 s1, 0
	s_cselect_b64 vcc, -1, 0
	s_cmp_eq_u32 s1, 0
	s_cselect_b64 s[64:65], -1, 0
	s_and_b64 s[6:7], s[64:65], exec
	s_cselect_b32 s1, 16, s1
	s_add_i32 s23, s1, -2
	s_add_u32 s68, s68, 0x40080
	s_addc_u32 s69, s69, 0
	s_add_u32 s55, s26, 0x100
	s_mov_b32 s28, 0
	s_addc_u32 s59, s27, 0
	v_add_u32_e32 v240, 0x10000, v207
.LBB0_871:
	s_add_i32 s63, s28, 2
	s_add_u32 s6, s68, 0xfffc0080
	s_addc_u32 s7, s69, -1
	s_add_i32 s35, 0, 0x10000
	ds_read_b128 v[130:133], v240
	ds_read_b128 v[134:137], v240 offset:1024
	ds_read_b128 v[138:141], v240 offset:2048
	ds_read_b128 v[142:145], v240 offset:3072
	s_cmp_eq_u32 s23, s28
	s_cselect_b32 s28, s24, s6
	s_cselect_b32 s29, s25, s7
	s_cselect_b32 s27, s13, s59
	s_cselect_b32 s26, s21, s55
	ds_read_b128 v[146:149], v209
	ds_read_b128 v[150:153], v209 offset:1024
	ds_read_b128 v[154:157], v209 offset:2048
	ds_read_b128 v[158:161], v209 offset:3072
	ds_read_b128 v[162:165], v209 offset:4096
	ds_read_b128 v[182:185], v209 offset:5120
	ds_read_b128 v[192:195], v209 offset:6144
	ds_read_b128 v[196:199], v209 offset:7168
	s_add_u32 s98, s68, 0xfffc0000
	s_addc_u32 s99, s69, -1
	s_mov_b32 m0, s76
	s_nop 0
	global_load_lds_dwordx4 v188, s[98:99]
	s_mov_b32 m0, s77
	s_nop 0
	global_load_lds_dwordx4 v190, s[98:99]
	s_add_i32 m0, s79, 0xc000
	s_nop 0
	global_load_lds_dwordx4 v188, s[68:69]
	s_add_i32 m0, s79, 0xe000
	s_nop 0
	global_load_lds_dwordx4 v190, s[68:69]
	s_add_i32 s37, 0, 0x14000
	ds_read_b128 v[200:203], v240 offset:16384
	ds_read_b128 v[210:213], v240 offset:17408
	ds_read_b128 v[214:217], v240 offset:18432
	ds_read_b128 v[218:221], v240 offset:19456
	s_waitcnt lgkmcnt(0)
	s_barrier
	v_mfma_f32_16x16x32_bf16 v[126:129], v[130:133], v[146:149], v[126:129]
	v_mfma_f32_16x16x32_bf16 v[126:129], v[134:137], v[150:153], v[126:129]
	v_mfma_f32_16x16x32_bf16 v[118:121], v[130:133], v[154:157], v[118:121]
	v_mfma_f32_16x16x32_bf16 v[118:121], v[134:137], v[158:161], v[118:121]
	v_mfma_f32_16x16x32_bf16 v[110:113], v[130:133], v[162:165], v[110:113]
	v_mfma_f32_16x16x32_bf16 v[110:113], v[134:137], v[182:185], v[110:113]
	v_mfma_f32_16x16x32_bf16 v[102:105], v[130:133], v[192:195], v[102:105]
	v_mfma_f32_16x16x32_bf16 v[102:105], v[134:137], v[196:199], v[102:105]
	v_mfma_f32_16x16x32_bf16 v[122:125], v[138:141], v[146:149], v[122:125]
	v_mfma_f32_16x16x32_bf16 v[122:125], v[142:145], v[150:153], v[122:125]
	v_mfma_f32_16x16x32_bf16 v[114:117], v[138:141], v[154:157], v[114:117]
	v_mfma_f32_16x16x32_bf16 v[114:117], v[142:145], v[158:161], v[114:117]
	v_mfma_f32_16x16x32_bf16 v[106:109], v[138:141], v[162:165], v[106:109]
	v_mfma_f32_16x16x32_bf16 v[106:109], v[142:145], v[182:185], v[106:109]
	v_mfma_f32_16x16x32_bf16 v[98:101], v[138:141], v[192:195], v[98:101]
	v_mfma_f32_16x16x32_bf16 v[98:101], v[142:145], v[196:199], v[98:101]
	v_mfma_f32_16x16x32_bf16 v[94:97], v[200:203], v[146:149], v[94:97]
	v_mfma_f32_16x16x32_bf16 v[94:97], v[210:213], v[150:153], v[94:97]
	v_mfma_f32_16x16x32_bf16 v[86:89], v[200:203], v[154:157], v[86:89]
	v_mfma_f32_16x16x32_bf16 v[86:89], v[210:213], v[158:161], v[86:89]
	v_mfma_f32_16x16x32_bf16 v[78:81], v[200:203], v[162:165], v[78:81]
	v_mfma_f32_16x16x32_bf16 v[78:81], v[210:213], v[182:185], v[78:81]
	v_mfma_f32_16x16x32_bf16 v[70:73], v[200:203], v[192:195], v[70:73]
	v_mfma_f32_16x16x32_bf16 v[70:73], v[210:213], v[196:199], v[70:73]
	v_mfma_f32_16x16x32_bf16 v[90:93], v[214:217], v[146:149], v[90:93]
	v_mfma_f32_16x16x32_bf16 v[90:93], v[218:221], v[150:153], v[90:93]
	v_mfma_f32_16x16x32_bf16 v[82:85], v[214:217], v[154:157], v[82:85]
	v_mfma_f32_16x16x32_bf16 v[82:85], v[218:221], v[158:161], v[82:85]
	v_mfma_f32_16x16x32_bf16 v[74:77], v[214:217], v[162:165], v[74:77]
	v_mfma_f32_16x16x32_bf16 v[74:77], v[218:221], v[182:185], v[74:77]
	v_mfma_f32_16x16x32_bf16 v[66:69], v[214:217], v[192:195], v[66:69]
	v_mfma_f32_16x16x32_bf16 v[66:69], v[218:221], v[196:199], v[66:69]
	s_barrier
	ds_read_b128 v[146:149], v209 offset:16384
	ds_read_b128 v[150:153], v209 offset:17408
	ds_read_b128 v[154:157], v209 offset:18432
	ds_read_b128 v[158:161], v209 offset:19456
	ds_read_b128 v[162:165], v209 offset:20480
	ds_read_b128 v[182:185], v209 offset:21504
	ds_read_b128 v[192:195], v209 offset:22528
	ds_read_b128 v[196:199], v209 offset:23552
	s_add_i32 s6, s35, s89
	s_mov_b32 m0, s6
	s_nop 0
	global_load_lds_dwordx4 v178, s[26:27]
	s_add_i32 m0, s6, 0x2000
	s_nop 0
	global_load_lds_dwordx4 v172, s[26:27]
	s_add_u32 s6, s26, 0x40000
	s_addc_u32 s7, s27, 0
	s_add_i32 s35, s37, s89
	s_mov_b32 m0, s35
	s_nop 0
	global_load_lds_dwordx4 v178, s[6:7]
	s_add_i32 m0, s35, 0x2000
	s_nop 0
	global_load_lds_dwordx4 v172, s[6:7]
	s_waitcnt vmcnt(4)
	s_waitcnt lgkmcnt(0)
	s_barrier
; #define PG8_STAGE(bufoff, gbase, voff) do { _Pragma("unroll") for (int _i = 0; _i < 2; ++_i) \
;         __builtin_amdgcn_global_load_lds((const unsigned*)((const char*)(gbase) + (voff)[_i]), (LAS unsigned*)(lds + (bufoff) + ldsw + _i * 8192), 16, 0, 0); } while (0)
; #define PG8_LDA(dst, b, h) do { _Pragma("unroll") for (int m = 0; m < 4; ++m) _Pragma("unroll") for (int k = 0; k < 2; ++k) dst[m][k] = *(const LAS bf16x8*)(lds + PG8_SA(b, h) + aoff + m * 2048 + k * 1024); } while (0)
; #define PG8_LDB(dst, b, h) do { _Pragma("unroll") for (int n = 0; n < 2; ++n) _Pragma("unroll") for (int k = 0; k < 2; ++k) dst[n][k] = *(const LAS bf16x8*)(lds + PG8_SB(b, h) + boff + n * 2048 + k * 1024); } while (0)
; #define PG8_MMA(ai, bj, At, Bt) do { __builtin_amdgcn_s_setprio(1); _Pragma("unroll") for (int m = 0; m < 4; ++m) _Pragma("unroll") for (int n = 0; n < 2; ++n) _Pragma("unroll") for (int k = 0; k < 2; ++k) \
;         acc[ai][bj][m][n] = __builtin_amdgcn_mfma_f32_16x16x32_bf16(Bt[n][k], At[m][k], acc[ai][bj][m][n], 0, 0, 0); __builtin_amdgcn_s_setprio(0); } while (0)
; #define PG8_WAIT_V(n) asm volatile("s_waitcnt vmcnt(" #n ")" ::: "memory")
; #define PG8_WAIT_L(n) asm volatile("s_waitcnt lgkmcnt(" #n ")" ::: "memory")
; #define PG8_BAR __builtin_amdgcn_s_barrier()
; #define PG8_SCHED __builtin_amdgcn_sched_barrier(0)
; template <class Epi, class Sched>
; __device__ __forceinline__ void gemm_phase(LAS unsigned char* lds, const Gemm g, const Sched& S, const Epi& E) {
;     ...
;             PG8_WAIT_V(6); PG8_BAR; PG8_MMA(1, 1, At, B1); PG8_BAR;
;             PG8_LDB(B0, 1, 0); PG8_SCHED; PG8_LDA(At, 1, 0); PG8_STAGE(PG8_SA(0, 1), a2 + hstepA, voffA);
;             PG8_WAIT_L(8); PG8_BAR; PG8_WAIT_L(0); PG8_MMA(0, 0, At, B0); PG8_BAR; PG8_SCHED;
;             PG8_LDB(B1, 1, 1); PG8_STAGE(PG8_SB(1, 0), b3, voffB);
;             PG8_BAR; PG8_WAIT_L(0); PG8_MMA(0, 1, At, B1); PG8_BAR;
;             PG8_LDA(At, 1, 1); PG8_STAGE(PG8_SA(1, 0), a3, voffA);
;             PG8_BAR; PG8_WAIT_L(0); PG8_MMA(1, 0, At, B0); PG8_BAR; PG8_SCHED;
;             PG8_STAGE(PG8_SB(1, 1), b3 + hstepB, voffB);
;             PG8_WAIT_V(6); PG8_BAR; PG8_MMA(1, 1, At, B1); PG8_BAR;
	v_mfma_f32_16x16x32_bf16 v[62:65], v[130:133], v[146:149], v[62:65]
	v_mfma_f32_16x16x32_bf16 v[62:65], v[134:137], v[150:153], v[62:65]
	v_mfma_f32_16x16x32_bf16 v[54:57], v[130:133], v[154:157], v[54:57]
	v_mfma_f32_16x16x32_bf16 v[54:57], v[134:137], v[158:161], v[54:57]
	v_mfma_f32_16x16x32_bf16 v[46:49], v[130:133], v[162:165], v[46:49]
	v_mfma_f32_16x16x32_bf16 v[46:49], v[134:137], v[182:185], v[46:49]
	v_mfma_f32_16x16x32_bf16 v[38:41], v[130:133], v[192:195], v[38:41]
	v_mfma_f32_16x16x32_bf16 v[38:41], v[134:137], v[196:199], v[38:41]
	v_mfma_f32_16x16x32_bf16 v[58:61], v[138:141], v[146:149], v[58:61]
	v_mfma_f32_16x16x32_bf16 v[58:61], v[142:145], v[150:153], v[58:61]
	v_mfma_f32_16x16x32_bf16 v[50:53], v[138:141], v[154:157], v[50:53]
	v_mfma_f32_16x16x32_bf16 v[50:53], v[142:145], v[158:161], v[50:53]
	v_mfma_f32_16x16x32_bf16 v[42:45], v[138:141], v[162:165], v[42:45]
	v_mfma_f32_16x16x32_bf16 v[42:45], v[142:145], v[182:185], v[42:45]
	v_mfma_f32_16x16x32_bf16 v[34:37], v[138:141], v[192:195], v[34:37]
	v_mfma_f32_16x16x32_bf16 v[34:37], v[142:145], v[196:199], v[34:37]
	v_mfma_f32_16x16x32_bf16 v[30:33], v[200:203], v[146:149], v[30:33]
	v_mfma_f32_16x16x32_bf16 v[30:33], v[210:213], v[150:153], v[30:33]
	v_mfma_f32_16x16x32_bf16 v[22:25], v[200:203], v[154:157], v[22:25]
	v_mfma_f32_16x16x32_bf16 v[22:25], v[210:213], v[158:161], v[22:25]
	v_mfma_f32_16x16x32_bf16 v[14:17], v[200:203], v[162:165], v[14:17]
	v_mfma_f32_16x16x32_bf16 v[14:17], v[210:213], v[182:185], v[14:17]
	v_mfma_f32_16x16x32_bf16 v[6:9], v[200:203], v[192:195], v[6:9]
	v_mfma_f32_16x16x32_bf16 v[6:9], v[210:213], v[196:199], v[6:9]
	v_mfma_f32_16x16x32_bf16 v[26:29], v[214:217], v[146:149], v[26:29]
	v_mfma_f32_16x16x32_bf16 v[26:29], v[218:221], v[150:153], v[26:29]
	v_mfma_f32_16x16x32_bf16 v[18:21], v[214:217], v[154:157], v[18:21]
	v_mfma_f32_16x16x32_bf16 v[18:21], v[218:221], v[158:161], v[18:21]
	v_mfma_f32_16x16x32_bf16 v[10:13], v[214:217], v[162:165], v[10:13]
	v_mfma_f32_16x16x32_bf16 v[10:13], v[218:221], v[182:185], v[10:13]
	v_mfma_f32_16x16x32_bf16 v[2:5], v[214:217], v[192:195], v[2:5]
	v_mfma_f32_16x16x32_bf16 v[2:5], v[218:221], v[196:199], v[2:5]
	s_add_i32 s35, 0, 0x18000
	s_barrier
	ds_read_b128 v[130:133], v240 offset:32768
	ds_read_b128 v[134:137], v240 offset:33792
	ds_read_b128 v[138:141], v240 offset:34816
	ds_read_b128 v[142:145], v240 offset:35840
	ds_read_b128 v[146:149], v209 offset:32768
	ds_read_b128 v[150:153], v209 offset:33792
	ds_read_b128 v[154:157], v209 offset:34816
	ds_read_b128 v[158:161], v209 offset:35840
	ds_read_b128 v[162:165], v209 offset:36864
	ds_read_b128 v[182:185], v209 offset:37888
	ds_read_b128 v[192:195], v209 offset:38912
	ds_read_b128 v[196:199], v209 offset:39936
	s_mov_b32 m0, s79
	s_nop 0
	global_load_lds_dwordx4 v168, s[28:29]
	s_mov_b32 m0, s46
	s_nop 0
	global_load_lds_dwordx4 v170, s[28:29]
	s_add_u32 s6, s28, 0x40000
	s_addc_u32 s7, s29, 0
	s_mov_b32 m0, s33
	s_nop 0
	global_load_lds_dwordx4 v168, s[6:7]
	s_mov_b32 m0, s83
	s_nop 0
	global_load_lds_dwordx4 v170, s[6:7]
	s_add_i32 s28, 0, 0x1c000
	ds_read_b128 v[200:203], v240 offset:49152
	ds_read_b128 v[210:213], v240 offset:50176
	ds_read_b128 v[214:217], v240 offset:51200
	ds_read_b128 v[218:221], v240 offset:52224
	s_waitcnt lgkmcnt(0)
	s_barrier
	v_mfma_f32_16x16x32_bf16 v[126:129], v[130:133], v[146:149], v[126:129]
	v_mfma_f32_16x16x32_bf16 v[126:129], v[134:137], v[150:153], v[126:129]
	v_mfma_f32_16x16x32_bf16 v[118:121], v[130:133], v[154:157], v[118:121]
	v_mfma_f32_16x16x32_bf16 v[118:121], v[134:137], v[158:161], v[118:121]
	v_mfma_f32_16x16x32_bf16 v[110:113], v[130:133], v[162:165], v[110:113]
	v_mfma_f32_16x16x32_bf16 v[110:113], v[134:137], v[182:185], v[110:113]
	v_mfma_f32_16x16x32_bf16 v[102:105], v[130:133], v[192:195], v[102:105]
	v_mfma_f32_16x16x32_bf16 v[102:105], v[134:137], v[196:199], v[102:105]
	v_mfma_f32_16x16x32_bf16 v[122:125], v[138:141], v[146:149], v[122:125]
	v_mfma_f32_16x16x32_bf16 v[122:125], v[142:145], v[150:153], v[122:125]
	v_mfma_f32_16x16x32_bf16 v[114:117], v[138:141], v[154:157], v[114:117]
	v_mfma_f32_16x16x32_bf16 v[114:117], v[142:145], v[158:161], v[114:117]
	v_mfma_f32_16x16x32_bf16 v[106:109], v[138:141], v[162:165], v[106:109]
	v_mfma_f32_16x16x32_bf16 v[106:109], v[142:145], v[182:185], v[106:109]
	v_mfma_f32_16x16x32_bf16 v[98:101], v[138:141], v[192:195], v[98:101]
	v_mfma_f32_16x16x32_bf16 v[98:101], v[142:145], v[196:199], v[98:101]
	v_mfma_f32_16x16x32_bf16 v[94:97], v[200:203], v[146:149], v[94:97]
	v_mfma_f32_16x16x32_bf16 v[94:97], v[210:213], v[150:153], v[94:97]
	v_mfma_f32_16x16x32_bf16 v[86:89], v[200:203], v[154:157], v[86:89]
	v_mfma_f32_16x16x32_bf16 v[86:89], v[210:213], v[158:161], v[86:89]
	v_mfma_f32_16x16x32_bf16 v[78:81], v[200:203], v[162:165], v[78:81]
	v_mfma_f32_16x16x32_bf16 v[78:81], v[210:213], v[182:185], v[78:81]
	v_mfma_f32_16x16x32_bf16 v[70:73], v[200:203], v[192:195], v[70:73]
	v_mfma_f32_16x16x32_bf16 v[70:73], v[210:213], v[196:199], v[70:73]
	v_mfma_f32_16x16x32_bf16 v[90:93], v[214:217], v[146:149], v[90:93]
	v_mfma_f32_16x16x32_bf16 v[90:93], v[218:221], v[150:153], v[90:93]
	v_mfma_f32_16x16x32_bf16 v[82:85], v[214:217], v[154:157], v[82:85]
	v_mfma_f32_16x16x32_bf16 v[82:85], v[218:221], v[158:161], v[82:85]
	v_mfma_f32_16x16x32_bf16 v[74:77], v[214:217], v[162:165], v[74:77]
	v_mfma_f32_16x16x32_bf16 v[74:77], v[218:221], v[182:185], v[74:77]
	v_mfma_f32_16x16x32_bf16 v[66:69], v[214:217], v[192:195], v[66:69]
	v_mfma_f32_16x16x32_bf16 v[66:69], v[218:221], v[196:199], v[66:69]
	s_barrier
; __device__ __forceinline__ unsigned cvt_pk_bf16(float lo, float hi) { const f32x2_t v = {lo, hi}; return __builtin_bit_cast(unsigned, __builtin_convertvector(v, bf16x2_t)); }
; #define PG8_WAIT_V(n) asm volatile("s_waitcnt vmcnt(" #n ")" ::: "memory")
; #define PG8_WAIT_L(n) asm volatile("s_waitcnt lgkmcnt(" #n ")" ::: "memory")
; #define PG8_BAR __builtin_amdgcn_s_barrier()
;     __device__ __forceinline__ void operator()(f32x4 (&acc)[2][2][4][2], const Unit& u, int wr, int wc, int fr, int fq) const {
;         const int row0 = u.pm * BM + wr * 64 + fr, col0 = u.pn * BM + wc * 32 + 8 * fq;
;         const bf16_t* gl = G + ((size_t)u.pm * 24 + u.pn) * 65536 + ((size_t)(wr * 4 + wc) * 16 * 64 + fq * 16 + fr) * 8;
;         if (u.nt) {
;             const int tile = (u.pm - 64) * 8 + u.pn, w = wr * 4 + wc;
;             const auto rsrc = __builtin_amdgcn_make_buffer_rsrc((void*)PM, 0, 96 * 131072, 0x00020000);
;             const unsigned pbase = (unsigned)(tile * 3) * 131072u + (unsigned)((w * 16 * 64 + fq * 16 + fr) * 16);
; #pragma unroll
;             for (int ai = 0; ai < 2; ++ai) {
;                 u32x4 ra[4][2];
; #pragma unroll
;                 for (int m = 0; m < 4; ++m)
; #pragma unroll
;                     for (int bj = 0; bj < 2; ++bj) ra[m][bj] = *(const u32x4*)(gl + (size_t)u.seg * 8 * 65536 + ((ai * 4 + m) * 2 + bj) * 512);
; #pragma unroll
;                 for (int m = 0; m < 4; ++m)
; #pragma unroll
;                     for (int bj = 0; bj < 2; ++bj) { float f[8]; unpack8(ra[m][bj], f);
;                         const f32x4 v0 = acc[ai][bj][m][0], v1 = acc[ai][bj][m][1];
;                         u32x4 wv; wv.x = cvt_pk_bf16(v0[0] * f[0], v0[1] * f[1]); wv.y = cvt_pk_bf16(v0[2] * f[2], v0[3] * f[3]); wv.z = cvt_pk_bf16(v1[0] * f[4], v1[1] * f[5]); wv.w = cvt_pk_bf16(v1[2] * f[6], v1[3] * f[7]);
;                         __builtin_amdgcn_raw_buffer_store_b128(wv, rsrc, pbase + (unsigned)u.seg * 131072u + (unsigned)(((ai * 4 + m) * 2 + bj) * 1024), 0,   16); }
; template <class Epi, class Sched>
; __device__ __forceinline__ void gemm_phase(LAS unsigned char* lds, const Gemm g, const Sched& S, const Epi& E) {
;     ...
;             PG8_BAR; PG8_WAIT_L(0); PG8_MMA(1, 0, At, B0); PG8_BAR; PG8_SCHED;
;             PG8_STAGE(PG8_SB(1, 1), b3 + hstepB, voffB);
;             PG8_WAIT_V(6); PG8_BAR; PG8_MMA(1, 1, At, B1); PG8_BAR;
;         }
	ds_read_b128 v[146:149], v209 offset:49152
	ds_read_b128 v[150:153], v209 offset:50176
	ds_read_b128 v[154:157], v209 offset:51200
	ds_read_b128 v[158:161], v209 offset:52224
	ds_read_b128 v[162:165], v209 offset:53248
	ds_read_b128 v[182:185], v209 offset:54272
	ds_read_b128 v[192:195], v209 offset:55296
	ds_read_b128 v[196:199], v209 offset:56320
	s_add_u32 s98, s26, 0x80
	s_addc_u32 s99, s27, 0
	s_add_i32 s6, s35, s89
	s_mov_b32 m0, s6
	s_nop 0
	global_load_lds_dwordx4 v178, s[98:99]
	s_add_i32 m0, s6, 0x2000
	s_nop 0
	global_load_lds_dwordx4 v172, s[98:99]
	s_add_u32 s6, s26, 0x40080
	s_addc_u32 s7, s27, 0
	s_add_i32 s26, s28, s89
	s_mov_b32 m0, s26
	s_nop 0
	global_load_lds_dwordx4 v178, s[6:7]
	s_add_i32 m0, s26, 0x2000
	s_nop 0
	global_load_lds_dwordx4 v172, s[6:7]
	s_waitcnt vmcnt(4)
	s_waitcnt lgkmcnt(0)
	s_barrier
	v_mfma_f32_16x16x32_bf16 v[62:65], v[130:133], v[146:149], v[62:65]
	v_mfma_f32_16x16x32_bf16 v[62:65], v[134:137], v[150:153], v[62:65]
	v_mfma_f32_16x16x32_bf16 v[54:57], v[130:133], v[154:157], v[54:57]
	v_mfma_f32_16x16x32_bf16 v[54:57], v[134:137], v[158:161], v[54:57]
	v_mfma_f32_16x16x32_bf16 v[46:49], v[130:133], v[162:165], v[46:49]
	v_mfma_f32_16x16x32_bf16 v[46:49], v[134:137], v[182:185], v[46:49]
	v_mfma_f32_16x16x32_bf16 v[38:41], v[130:133], v[192:195], v[38:41]
	v_mfma_f32_16x16x32_bf16 v[38:41], v[134:137], v[196:199], v[38:41]
	v_mfma_f32_16x16x32_bf16 v[58:61], v[138:141], v[146:149], v[58:61]
	v_mfma_f32_16x16x32_bf16 v[58:61], v[142:145], v[150:153], v[58:61]
	v_mfma_f32_16x16x32_bf16 v[50:53], v[138:141], v[154:157], v[50:53]
	v_mfma_f32_16x16x32_bf16 v[50:53], v[142:145], v[158:161], v[50:53]
	v_mfma_f32_16x16x32_bf16 v[42:45], v[138:141], v[162:165], v[42:45]
	v_mfma_f32_16x16x32_bf16 v[42:45], v[142:145], v[182:185], v[42:45]
	v_mfma_f32_16x16x32_bf16 v[34:37], v[138:141], v[192:195], v[34:37]
	v_mfma_f32_16x16x32_bf16 v[34:37], v[142:145], v[196:199], v[34:37]
	v_mfma_f32_16x16x32_bf16 v[30:33], v[200:203], v[146:149], v[30:33]
	v_mfma_f32_16x16x32_bf16 v[30:33], v[210:213], v[150:153], v[30:33]
	v_mfma_f32_16x16x32_bf16 v[22:25], v[200:203], v[154:157], v[22:25]
	v_mfma_f32_16x16x32_bf16 v[22:25], v[210:213], v[158:161], v[22:25]
	v_mfma_f32_16x16x32_bf16 v[14:17], v[200:203], v[162:165], v[14:17]
	v_mfma_f32_16x16x32_bf16 v[14:17], v[210:213], v[182:185], v[14:17]
	v_mfma_f32_16x16x32_bf16 v[6:9], v[200:203], v[192:195], v[6:9]
	v_mfma_f32_16x16x32_bf16 v[6:9], v[210:213], v[196:199], v[6:9]
	v_mfma_f32_16x16x32_bf16 v[26:29], v[214:217], v[146:149], v[26:29]
	v_mfma_f32_16x16x32_bf16 v[26:29], v[218:221], v[150:153], v[26:29]
	v_mfma_f32_16x16x32_bf16 v[18:21], v[214:217], v[154:157], v[18:21]
	v_mfma_f32_16x16x32_bf16 v[18:21], v[218:221], v[158:161], v[18:21]
	v_mfma_f32_16x16x32_bf16 v[10:13], v[214:217], v[162:165], v[10:13]
	v_mfma_f32_16x16x32_bf16 v[10:13], v[218:221], v[182:185], v[10:13]
	v_mfma_f32_16x16x32_bf16 v[2:5], v[214:217], v[192:195], v[2:5]
	v_mfma_f32_16x16x32_bf16 v[2:5], v[218:221], v[196:199], v[2:5]
	s_add_u32 s68, s68, 0x100
	s_addc_u32 s69, s69, 0
	s_add_u32 s55, s55, 0x100
	s_addc_u32 s59, s59, 0
	s_cmp_ge_i32 s63, s1
	s_mov_b32 s28, s63
	s_barrier
	s_cbranch_scc0 .LBB0_871
	s_lshl_b64 s[6:7], s[66:67], 17
	v_lshl_add_u32 v210, s20, 8, v206
	v_lshl_or_b32 v194, s12, 8, v167
	v_lshl_add_u64 v[192:193], v[176:177], 0, s[6:7]
	s_andn2_b64 vcc, exec, vcc
	s_mov_b64 s[26:27], -1
	s_cbranch_vccnz .LBB0_880
	s_ashr_i32 s23, s22, 31
	s_lshl_b64 s[6:7], s[22:23], 20
	v_lshl_add_u64 v[158:159], v[192:193], 0, s[6:7]
	global_load_dwordx4 v[162:165], v[158:159], off
	global_load_dwordx4 v[154:157], v[158:159], off offset:1024
	global_load_dwordx4 v[150:153], v[158:159], off offset:2048
	global_load_dwordx4 v[146:149], v[158:159], off offset:3072
	v_add_co_u32_e32 v130, vcc, s48, v158
	s_movk_i32 s6, 0x2000
	s_nop 0
	v_addc_co_u32_e32 v131, vcc, 0, v159, vcc
	v_add_co_u32_e32 v160, vcc, s6, v158
	s_lshl_b32 s1, s20, 3
	s_nop 0
	v_addc_co_u32_e32 v161, vcc, 0, v159, vcc
	global_load_dwordx4 v[142:145], v[160:161], off offset:-4096
	global_load_dwordx4 v[138:141], v[130:131], off offset:1024
	global_load_dwordx4 v[134:137], v[130:131], off offset:2048
	s_nop 0
	global_load_dwordx4 v[130:133], v[130:131], off offset:3072
	s_add_i32 s1, s12, s1
	s_addk_i32 s1, 0xfe00
	s_mul_i32 s12, s1, 0x60000
	s_lshl_b32 s6, s22, 17
	s_add_i32 s12, s12, s6
	s_movk_i32 s6, 0x3000
	s_waitcnt vmcnt(0)
; __device__ __forceinline__ unsigned cvt_pk_bf16(float lo, float hi) { const f32x2_t v = {lo, hi}; return __builtin_bit_cast(unsigned, __builtin_convertvector(v, bf16x2_t)); }
;     __device__ __forceinline__ void operator()(f32x4 (&acc)[2][2][4][2], const Unit& u, int wr, int wc, int fr, int fq) const {
;     ...
;             for (int ai = 0; ai < 2; ++ai) {
;                 u32x4 ra[4][2];
; #pragma unroll
;                 for (int m = 0; m < 4; ++m)
; #pragma unroll
;                     for (int bj = 0; bj < 2; ++bj) ra[m][bj] = *(const u32x4*)(gl + (size_t)u.seg * 8 * 65536 + ((ai * 4 + m) * 2 + bj) * 512);
; #pragma unroll
;                 for (int m = 0; m < 4; ++m)
; #pragma unroll
;                     for (int bj = 0; bj < 2; ++bj) { float f[8]; unpack8(ra[m][bj], f);
;                         const f32x4 v0 = acc[ai][bj][m][0], v1 = acc[ai][bj][m][1];
;                         u32x4 wv; wv.x = cvt_pk_bf16(v0[0] * f[0], v0[1] * f[1]); wv.y = cvt_pk_bf16(v0[2] * f[2], v0[3] * f[3]); wv.z = cvt_pk_bf16(v1[0] * f[4], v1[1] * f[5]); wv.w = cvt_pk_bf16(v1[2] * f[6], v1[3] * f[7]);
;                         __builtin_amdgcn_raw_buffer_store_b128(wv, rsrc, pbase + (unsigned)u.seg * 131072u + (unsigned)(((ai * 4 + m) * 2 + bj) * 1024), 0,   16); }
	v_lshlrev_b32_e32 v182, 16, v162
	v_and_b32_e32 v183, 0xffff0000, v162
	v_lshlrev_b32_e32 v162, 16, v163
	v_and_b32_e32 v163, 0xffff0000, v163
	v_pk_mul_f32 v[182:183], v[126:127], v[182:183]
	v_pk_mul_f32 v[162:163], v[128:129], v[162:163]
	v_cvt_pk_bf16_f32 v182, v182, v183
	v_cvt_pk_bf16_f32 v183, v162, v163
	v_lshlrev_b32_e32 v162, 16, v164
	v_and_b32_e32 v163, 0xffff0000, v164
	v_pk_mul_f32 v[162:163], v[122:123], v[162:163]
	v_lshlrev_b32_e32 v164, 16, v154
	v_cvt_pk_bf16_f32 v184, v162, v163
	v_lshlrev_b32_e32 v162, 16, v165
	v_and_b32_e32 v163, 0xffff0000, v165
	v_and_b32_e32 v165, 0xffff0000, v154
	v_pk_mul_f32 v[164:165], v[94:95], v[164:165]
	v_pk_mul_f32 v[162:163], v[124:125], v[162:163]
	v_cvt_pk_bf16_f32 v154, v164, v165
	v_lshlrev_b32_e32 v164, 16, v155
	v_and_b32_e32 v165, 0xffff0000, v155
	v_pk_mul_f32 v[164:165], v[96:97], v[164:165]
	v_cvt_pk_bf16_f32 v185, v162, v163
	v_cvt_pk_bf16_f32 v155, v164, v165
	v_lshlrev_b32_e32 v164, 16, v156
	v_and_b32_e32 v165, 0xffff0000, v156
	v_pk_mul_f32 v[164:165], v[90:91], v[164:165]
	v_add_u32_e32 v162, s12, v208
	v_cvt_pk_bf16_f32 v156, v164, v165
	v_lshlrev_b32_e32 v164, 16, v157
	v_and_b32_e32 v165, 0xffff0000, v157
	v_pk_mul_f32 v[164:165], v[92:93], v[164:165]
	v_add_u32_e32 v1, 0x1000, v162
	v_cvt_pk_bf16_f32 v157, v164, v165
	buffer_store_dwordx4 v[154:157], v162, s[16:19], 0 offen offset:1024 sc1
	buffer_store_dwordx4 v[182:185], v162, s[16:19], 0 offen sc1
	s_nop 0
	v_lshlrev_b32_e32 v154, 16, v150
	v_and_b32_e32 v155, 0xffff0000, v150
	v_pk_mul_f32 v[154:155], v[118:119], v[154:155]
	s_nop 0
	v_cvt_pk_bf16_f32 v150, v154, v155
	v_lshlrev_b32_e32 v154, 16, v151
	v_and_b32_e32 v155, 0xffff0000, v151
	v_pk_mul_f32 v[154:155], v[120:121], v[154:155]
	s_nop 0
	v_cvt_pk_bf16_f32 v151, v154, v155
	v_lshlrev_b32_e32 v154, 16, v152
	v_and_b32_e32 v155, 0xffff0000, v152
	v_pk_mul_f32 v[154:155], v[114:115], v[154:155]
	s_nop 0
	v_cvt_pk_bf16_f32 v152, v154, v155
	v_lshlrev_b32_e32 v154, 16, v153
	v_and_b32_e32 v155, 0xffff0000, v153
	v_pk_mul_f32 v[154:155], v[116:117], v[154:155]
	s_nop 0
	v_cvt_pk_bf16_f32 v153, v154, v155
	buffer_store_dwordx4 v[150:153], v162, s[16:19], 0 offen offset:2048 sc1
	s_nop 1
	v_lshlrev_b32_e32 v150, 16, v146
	v_and_b32_e32 v151, 0xffff0000, v146
	v_pk_mul_f32 v[150:151], v[86:87], v[150:151]
	s_nop 0
	v_cvt_pk_bf16_f32 v146, v150, v151
	v_lshlrev_b32_e32 v150, 16, v147
	v_and_b32_e32 v151, 0xffff0000, v147
	v_pk_mul_f32 v[150:151], v[88:89], v[150:151]
	s_nop 0
	v_cvt_pk_bf16_f32 v147, v150, v151
	v_lshlrev_b32_e32 v150, 16, v148
	v_and_b32_e32 v151, 0xffff0000, v148
	v_pk_mul_f32 v[150:151], v[82:83], v[150:151]
	s_nop 0
	v_cvt_pk_bf16_f32 v148, v150, v151
	v_lshlrev_b32_e32 v150, 16, v149
	v_and_b32_e32 v151, 0xffff0000, v149
	v_pk_mul_f32 v[150:151], v[84:85], v[150:151]
	s_nop 0
	v_cvt_pk_bf16_f32 v149, v150, v151
	buffer_store_dwordx4 v[146:149], v162, s[16:19], 0 offen offset:3072 sc1
	s_nop 1
	v_lshlrev_b32_e32 v146, 16, v142
	v_and_b32_e32 v147, 0xffff0000, v142
	v_pk_mul_f32 v[146:147], v[110:111], v[146:147]
	s_nop 0
	v_cvt_pk_bf16_f32 v142, v146, v147
	v_lshlrev_b32_e32 v146, 16, v143
	v_and_b32_e32 v147, 0xffff0000, v143
	v_pk_mul_f32 v[146:147], v[112:113], v[146:147]
	s_nop 0
	v_cvt_pk_bf16_f32 v143, v146, v147
	v_lshlrev_b32_e32 v146, 16, v144
	v_and_b32_e32 v147, 0xffff0000, v144
	v_pk_mul_f32 v[146:147], v[106:107], v[146:147]
	s_nop 0
	v_cvt_pk_bf16_f32 v144, v146, v147
	v_lshlrev_b32_e32 v146, 16, v145
	v_and_b32_e32 v147, 0xffff0000, v145
	v_pk_mul_f32 v[146:147], v[108:109], v[146:147]
	s_nop 0
	v_cvt_pk_bf16_f32 v145, v146, v147
	buffer_store_dwordx4 v[142:145], v1, s[16:19], 0 offen sc1
	s_nop 1
	v_lshlrev_b32_e32 v142, 16, v138
	v_and_b32_e32 v143, 0xffff0000, v138
	v_pk_mul_f32 v[142:143], v[78:79], v[142:143]
	s_nop 0
	v_cvt_pk_bf16_f32 v138, v142, v143
	v_lshlrev_b32_e32 v142, 16, v139
	v_and_b32_e32 v143, 0xffff0000, v139
	v_pk_mul_f32 v[142:143], v[80:81], v[142:143]
	s_nop 0
	v_cvt_pk_bf16_f32 v139, v142, v143
	v_lshlrev_b32_e32 v142, 16, v140
	v_and_b32_e32 v143, 0xffff0000, v140
	v_pk_mul_f32 v[142:143], v[74:75], v[142:143]
	s_nop 0
	v_cvt_pk_bf16_f32 v140, v142, v143
	v_lshlrev_b32_e32 v142, 16, v141
	v_and_b32_e32 v143, 0xffff0000, v141
	v_pk_mul_f32 v[142:143], v[76:77], v[142:143]
	s_nop 0
	v_cvt_pk_bf16_f32 v141, v142, v143
	buffer_store_dwordx4 v[138:141], v1, s[16:19], 0 offen offset:1024 sc1
	s_nop 1
	v_lshlrev_b32_e32 v138, 16, v134
	v_and_b32_e32 v139, 0xffff0000, v134
	v_pk_mul_f32 v[138:139], v[102:103], v[138:139]
	s_nop 0
	v_cvt_pk_bf16_f32 v134, v138, v139
	v_lshlrev_b32_e32 v138, 16, v135
	v_and_b32_e32 v139, 0xffff0000, v135
	v_pk_mul_f32 v[138:139], v[104:105], v[138:139]
	s_nop 0
	v_cvt_pk_bf16_f32 v135, v138, v139
	v_lshlrev_b32_e32 v138, 16, v136
	v_and_b32_e32 v139, 0xffff0000, v136
	v_pk_mul_f32 v[138:139], v[98:99], v[138:139]
	s_nop 0
	v_cvt_pk_bf16_f32 v136, v138, v139
	v_lshlrev_b32_e32 v138, 16, v137
	v_and_b32_e32 v139, 0xffff0000, v137
	v_pk_mul_f32 v[138:139], v[100:101], v[138:139]
	s_nop 0
	v_cvt_pk_bf16_f32 v137, v138, v139
	buffer_store_dwordx4 v[134:137], v1, s[16:19], 0 offen offset:2048 sc1
	s_nop 1
	v_lshlrev_b32_e32 v134, 16, v130
	v_and_b32_e32 v135, 0xffff0000, v130
	v_pk_mul_f32 v[134:135], v[70:71], v[134:135]
	s_nop 0
	v_cvt_pk_bf16_f32 v130, v134, v135
	v_lshlrev_b32_e32 v134, 16, v131
	v_and_b32_e32 v135, 0xffff0000, v131
	v_pk_mul_f32 v[134:135], v[72:73], v[134:135]
	s_nop 0
	v_cvt_pk_bf16_f32 v131, v134, v135
	v_lshlrev_b32_e32 v134, 16, v132
	v_and_b32_e32 v135, 0xffff0000, v132
	v_pk_mul_f32 v[134:135], v[66:67], v[134:135]
	s_nop 0
	v_cvt_pk_bf16_f32 v132, v134, v135
	v_lshlrev_b32_e32 v134, 16, v133
	v_and_b32_e32 v135, 0xffff0000, v133
	v_pk_mul_f32 v[134:135], v[68:69], v[134:135]
	s_nop 0
	v_cvt_pk_bf16_f32 v133, v134, v135
	buffer_store_dwordx4 v[130:133], v1, s[16:19], 0 offen offset:3072 sc1
	global_load_dwordx4 v[134:137], v[160:161], off
	global_load_dwordx4 v[138:141], v[160:161], off offset:1024
	global_load_dwordx4 v[142:145], v[160:161], off offset:2048
	global_load_dwordx4 v[146:149], v[160:161], off offset:3072
	v_add_co_u32_e32 v130, vcc, s6, v158
	v_add_u32_e32 v1, 0x2000, v162
	s_nop 0
	v_addc_co_u32_e32 v131, vcc, 0, v159, vcc
	global_load_dwordx4 v[150:153], v[130:131], off
	global_load_dwordx4 v[154:157], v[130:131], off offset:1024
	global_load_dwordx4 v[158:161], v[130:131], off offset:2048
	s_nop 0
	global_load_dwordx4 v[130:133], v[130:131], off offset:3072
	s_waitcnt vmcnt(0)
; __device__ __forceinline__ unsigned cvt_pk_bf16(float lo, float hi) { const f32x2_t v = {lo, hi}; return __builtin_bit_cast(unsigned, __builtin_convertvector(v, bf16x2_t)); }
;     __device__ __forceinline__ void operator()(f32x4 (&acc)[2][2][4][2], const Unit& u, int wr, int wc, int fr, int fq) const {
;     ...
; #pragma unroll
;             for (int ai = 0; ai < 2; ++ai) {
;                 u32x4 ra[4][2];
; #pragma unroll
;                 for (int m = 0; m < 4; ++m)
; #pragma unroll
;                     for (int bj = 0; bj < 2; ++bj) ra[m][bj] = *(const u32x4*)(gl + (size_t)u.seg * 8 * 65536 + ((ai * 4 + m) * 2 + bj) * 512);
; #pragma unroll
;                 for (int m = 0; m < 4; ++m)
; #pragma unroll
;                     for (int bj = 0; bj < 2; ++bj) { float f[8]; unpack8(ra[m][bj], f);
;                         const f32x4 v0 = acc[ai][bj][m][0], v1 = acc[ai][bj][m][1];
;                         u32x4 wv; wv.x = cvt_pk_bf16(v0[0] * f[0], v0[1] * f[1]); wv.y = cvt_pk_bf16(v0[2] * f[2], v0[3] * f[3]); wv.z = cvt_pk_bf16(v1[0] * f[4], v1[1] * f[5]); wv.w = cvt_pk_bf16(v1[2] * f[6], v1[3] * f[7]);
;                         __builtin_amdgcn_raw_buffer_store_b128(wv, rsrc, pbase + (unsigned)u.seg * 131072u + (unsigned)(((ai * 4 + m) * 2 + bj) * 1024), 0,   16); }
;             }
;             asm volatile("s_waitcnt vmcnt(0)" ::: "memory");
;             unsigned old = 0; if ((fq | fr) == 0) old = __hip_atomic_fetch_add(cnt + tile * 8 + w, 1u, __ATOMIC_RELAXED, __HIP_MEMORY_SCOPE_AGENT);
	v_lshlrev_b32_e32 v164, 16, v134
	v_and_b32_e32 v165, 0xffff0000, v134
	v_pk_mul_f32 v[164:165], v[62:63], v[164:165]
	s_nop 0
	v_cvt_pk_bf16_f32 v134, v164, v165
	v_lshlrev_b32_e32 v164, 16, v135
	v_and_b32_e32 v165, 0xffff0000, v135
	v_pk_mul_f32 v[164:165], v[64:65], v[164:165]
	s_nop 0
	v_cvt_pk_bf16_f32 v135, v164, v165
	v_lshlrev_b32_e32 v164, 16, v136
	v_and_b32_e32 v165, 0xffff0000, v136
	v_pk_mul_f32 v[164:165], v[58:59], v[164:165]
	s_nop 0
	v_cvt_pk_bf16_f32 v136, v164, v165
	v_lshlrev_b32_e32 v164, 16, v137
	v_and_b32_e32 v165, 0xffff0000, v137
	v_pk_mul_f32 v[164:165], v[60:61], v[164:165]
	s_nop 0
	v_cvt_pk_bf16_f32 v137, v164, v165
	buffer_store_dwordx4 v[134:137], v1, s[16:19], 0 offen sc1
	s_nop 1
	v_lshlrev_b32_e32 v134, 16, v138
	v_and_b32_e32 v135, 0xffff0000, v138
	v_lshlrev_b32_e32 v136, 16, v139
	v_and_b32_e32 v137, 0xffff0000, v139
	v_pk_mul_f32 v[134:135], v[30:31], v[134:135]
	v_pk_mul_f32 v[136:137], v[32:33], v[136:137]
	v_cvt_pk_bf16_f32 v134, v134, v135
	v_cvt_pk_bf16_f32 v135, v136, v137
	v_lshlrev_b32_e32 v136, 16, v140
	v_and_b32_e32 v137, 0xffff0000, v140
	v_lshlrev_b32_e32 v138, 16, v141
	v_and_b32_e32 v139, 0xffff0000, v141
	v_pk_mul_f32 v[136:137], v[26:27], v[136:137]
	v_pk_mul_f32 v[138:139], v[28:29], v[138:139]
	v_cvt_pk_bf16_f32 v136, v136, v137
	v_cvt_pk_bf16_f32 v137, v138, v139
	buffer_store_dwordx4 v[134:137], v1, s[16:19], 0 offen offset:1024 sc1
	v_lshlrev_b32_e32 v138, 16, v145
	v_and_b32_e32 v139, 0xffff0000, v145
	v_lshlrev_b32_e32 v134, 16, v142
	v_and_b32_e32 v135, 0xffff0000, v142
	v_lshlrev_b32_e32 v136, 16, v143
	v_and_b32_e32 v137, 0xffff0000, v143
	v_pk_mul_f32 v[134:135], v[54:55], v[134:135]
	v_pk_mul_f32 v[136:137], v[56:57], v[136:137]
	v_cvt_pk_bf16_f32 v134, v134, v135
	v_cvt_pk_bf16_f32 v135, v136, v137
	v_lshlrev_b32_e32 v136, 16, v144
	v_and_b32_e32 v137, 0xffff0000, v144
	v_pk_mul_f32 v[136:137], v[50:51], v[136:137]
	v_pk_mul_f32 v[138:139], v[52:53], v[138:139]
	v_cvt_pk_bf16_f32 v136, v136, v137
	v_cvt_pk_bf16_f32 v137, v138, v139
	buffer_store_dwordx4 v[134:137], v1, s[16:19], 0 offen offset:2048 sc1
	v_lshlrev_b32_e32 v138, 16, v149
	v_and_b32_e32 v139, 0xffff0000, v149
	v_lshlrev_b32_e32 v134, 16, v146
	v_and_b32_e32 v135, 0xffff0000, v146
	v_lshlrev_b32_e32 v136, 16, v147
	v_and_b32_e32 v137, 0xffff0000, v147
	v_pk_mul_f32 v[134:135], v[22:23], v[134:135]
	v_pk_mul_f32 v[136:137], v[24:25], v[136:137]
	v_cvt_pk_bf16_f32 v134, v134, v135
	v_cvt_pk_bf16_f32 v135, v136, v137
	v_lshlrev_b32_e32 v136, 16, v148
	v_and_b32_e32 v137, 0xffff0000, v148
	v_pk_mul_f32 v[136:137], v[18:19], v[136:137]
	v_pk_mul_f32 v[138:139], v[20:21], v[138:139]
	v_cvt_pk_bf16_f32 v136, v136, v137
	v_cvt_pk_bf16_f32 v137, v138, v139
	buffer_store_dwordx4 v[134:137], v1, s[16:19], 0 offen offset:3072 sc1
	v_lshlrev_b32_e32 v138, 16, v153
	v_and_b32_e32 v139, 0xffff0000, v153
	v_lshlrev_b32_e32 v134, 16, v150
	v_and_b32_e32 v135, 0xffff0000, v150
	v_lshlrev_b32_e32 v136, 16, v151
	v_and_b32_e32 v137, 0xffff0000, v151
	v_pk_mul_f32 v[134:135], v[46:47], v[134:135]
	v_pk_mul_f32 v[136:137], v[48:49], v[136:137]
	v_cvt_pk_bf16_f32 v134, v134, v135
	v_cvt_pk_bf16_f32 v135, v136, v137
	v_lshlrev_b32_e32 v136, 16, v152
	v_and_b32_e32 v137, 0xffff0000, v152
	v_pk_mul_f32 v[136:137], v[42:43], v[136:137]
	v_pk_mul_f32 v[138:139], v[44:45], v[138:139]
	v_cvt_pk_bf16_f32 v136, v136, v137
	v_cvt_pk_bf16_f32 v137, v138, v139
	v_add_u32_e32 v1, 0x3000, v162
	buffer_store_dwordx4 v[134:137], v1, s[16:19], 0 offen sc1
	v_lshlrev_b32_e32 v138, 16, v157
	v_and_b32_e32 v139, 0xffff0000, v157
	v_lshlrev_b32_e32 v134, 16, v154
	v_and_b32_e32 v135, 0xffff0000, v154
	v_lshlrev_b32_e32 v136, 16, v155
	v_and_b32_e32 v137, 0xffff0000, v155
	v_pk_mul_f32 v[134:135], v[14:15], v[134:135]
	v_pk_mul_f32 v[136:137], v[16:17], v[136:137]
	v_cvt_pk_bf16_f32 v134, v134, v135
	v_cvt_pk_bf16_f32 v135, v136, v137
	v_lshlrev_b32_e32 v136, 16, v156
	v_and_b32_e32 v137, 0xffff0000, v156
	v_pk_mul_f32 v[136:137], v[10:11], v[136:137]
	v_pk_mul_f32 v[138:139], v[12:13], v[138:139]
	v_cvt_pk_bf16_f32 v136, v136, v137
	v_cvt_pk_bf16_f32 v137, v138, v139
	buffer_store_dwordx4 v[134:137], v1, s[16:19], 0 offen offset:1024 sc1
	v_lshlrev_b32_e32 v138, 16, v161
	v_and_b32_e32 v139, 0xffff0000, v161
	v_lshlrev_b32_e32 v134, 16, v158
	v_and_b32_e32 v135, 0xffff0000, v158
	v_lshlrev_b32_e32 v136, 16, v159
	v_and_b32_e32 v137, 0xffff0000, v159
	v_pk_mul_f32 v[134:135], v[38:39], v[134:135]
	v_pk_mul_f32 v[136:137], v[40:41], v[136:137]
	v_cvt_pk_bf16_f32 v134, v134, v135
	v_cvt_pk_bf16_f32 v135, v136, v137
	v_lshlrev_b32_e32 v136, 16, v160
	v_and_b32_e32 v137, 0xffff0000, v160
	v_pk_mul_f32 v[136:137], v[34:35], v[136:137]
	v_pk_mul_f32 v[138:139], v[36:37], v[138:139]
	v_cvt_pk_bf16_f32 v136, v136, v137
	v_cvt_pk_bf16_f32 v137, v138, v139
	buffer_store_dwordx4 v[134:137], v1, s[16:19], 0 offen offset:2048 sc1
	s_nop 1
	v_lshlrev_b32_e32 v134, 16, v130
	v_and_b32_e32 v135, 0xffff0000, v130
	v_pk_mul_f32 v[134:135], v[6:7], v[134:135]
	s_nop 0
	v_cvt_pk_bf16_f32 v130, v134, v135
	v_lshlrev_b32_e32 v134, 16, v131
	v_and_b32_e32 v135, 0xffff0000, v131
	v_pk_mul_f32 v[134:135], v[8:9], v[134:135]
	s_nop 0
	v_cvt_pk_bf16_f32 v131, v134, v135
	v_lshlrev_b32_e32 v134, 16, v132
	v_and_b32_e32 v135, 0xffff0000, v132
	v_pk_mul_f32 v[134:135], v[2:3], v[134:135]
	s_nop 0
	v_cvt_pk_bf16_f32 v132, v134, v135
	v_lshlrev_b32_e32 v134, 16, v133
	v_and_b32_e32 v135, 0xffff0000, v133
	v_pk_mul_f32 v[134:135], v[4:5], v[134:135]
	s_nop 0
	v_cvt_pk_bf16_f32 v133, v134, v135
	buffer_store_dwordx4 v[130:133], v1, s[16:19], 0 offen offset:3072 sc1
	s_waitcnt vmcnt(0)
	s_nop 1
	v_mov_b32_e32 v130, 0
	s_and_saveexec_b64 s[12:13], s[4:5]
	s_cbranch_execz .LBB0_877
	s_mov_b64 s[26:27], exec
	v_mbcnt_lo_u32_b32 v1, s26, 0
	v_mbcnt_hi_u32_b32 v130, s27, v1
	v_cmp_eq_u32_e32 vcc, 0, v130
	s_and_saveexec_b64 s[20:21], vcc
	s_cbranch_execz .LBB0_876
	s_lshl_b32 s6, s1, 3
	s_ashr_i32 s7, s6, 31
	s_lshl_b64 s[6:7], s[6:7], 2
	v_readlane_b32 s23, v255, 36
	s_add_u32 s6, s23, s6
	v_readlane_b32 s23, v255, 37
	s_addc_u32 s7, s23, s7
	s_bcnt1_i32_b64 s23, s[26:27]
	v_mov_b32_e32 v1, s23
	global_atomic_add v131, v179, v1, s[6:7] sc0

; #define PG8_STAGE(bufoff, gbase, voff) do { _Pragma("unroll") for (int _i = 0; _i < 2; ++_i) \
;         __builtin_amdgcn_global_load_lds((const unsigned*)((const char*)(gbase) + (voff)[_i]), (LAS unsigned*)(lds + (bufoff) + ldsw + _i * 8192), 16, 0, 0); } while (0)
; #define PG8_LDA(dst, b, h) do { _Pragma("unroll") for (int m = 0; m < 4; ++m) _Pragma("unroll") for (int k = 0; k < 2; ++k) dst[m][k] = *(const LAS bf16x8*)(lds + PG8_SA(b, h) + aoff + m * 2048 + k * 1024); } while (0)
; #define PG8_LDB(dst, b, h) do { _Pragma("unroll") for (int n = 0; n < 2; ++n) _Pragma("unroll") for (int k = 0; k < 2; ++k) dst[n][k] = *(const LAS bf16x8*)(lds + PG8_SB(b, h) + boff + n * 2048 + k * 1024); } while (0)
; #define PG8_MMA(ai, bj, At, Bt) do { __builtin_amdgcn_s_setprio(1); _Pragma("unroll") for (int m = 0; m < 4; ++m) _Pragma("unroll") for (int n = 0; n < 2; ++n) _Pragma("unroll") for (int k = 0; k < 2; ++k) \
;         acc[ai][bj][m][n] = __builtin_amdgcn_mfma_f32_16x16x32_bf16(Bt[n][k], At[m][k], acc[ai][bj][m][n], 0, 0, 0); __builtin_amdgcn_s_setprio(0); } while (0)
; #define PG8_WAIT_L(n) asm volatile("s_waitcnt lgkmcnt(" #n ")" ::: "memory")
; #define PG8_BAR __builtin_amdgcn_s_barrier()
; #define PG8_SCHED __builtin_amdgcn_sched_barrier(0)
; template <class Epi, class Sched>
; __device__ __forceinline__ void gemm_phase(LAS unsigned char* lds, const Gemm g, const Sched& S, const Epi& E) {
;     ...
;         for (int t = 0; t < ntu; t += 2) {
;             const bool last = (t == ntu - 2);
;             const char* a1 = cA + (size_t)(t + 1) * kstep;
;             const char* a2 = last ? nA : cA + (size_t)(t + 2) * kstep; const char* b2 = last ? nB : cB + (size_t)(t + 2) * kstep;
;             const char* a3 = a2 + kstep; const char* b3 = b2 + kstep;
;             if (last && has_next) S.a_ready(nxt);
;             PG8_LDB(B0, 0, 0); PG8_SCHED; PG8_LDA(At, 0, 0); PG8_STAGE(PG8_SA(1, 1), a1 + hstepA, voffA);
;             PG8_WAIT_L(8); PG8_BAR; PG8_WAIT_L(0); PG8_MMA(0, 0, At, B0); PG8_BAR; PG8_SCHED;
;     ...
;         if (!E.keep(cur)) {
; #pragma unroll
;             for (int a = 0; a < 2; ++a)
; #pragma unroll
;                 for (int b = 0; b < 2; ++b)
; #pragma unroll
;                     for (int m = 0; m < 4; ++m)
; #pragma unroll
;                         for (int n = 0; n < 2; ++n) acc[a][b][m][n] = (f32x4){0.f, 0.f, 0.f, 0.f};
.LBB0_983:
	s_cmp_lg_u32 s28, 0
	s_cselect_b64 s[50:51], -1, 0
	s_and_b64 s[56:57], s[50:51], exec
	s_cselect_b32 s17, s28, 32
	s_cmp_lt_i32 s17, 1
	s_cbranch_scc1 .LBB0_987
	s_add_i32 s21, s17, -2
	s_add_u32 s70, s54, 0x100
	v_mov_b32_e32 v2, 0
	s_addc_u32 s71, s55, 0
	s_mov_b32 s28, 0
	v_mov_b32_e32 v3, v2
	v_mov_b32_e32 v4, v2
	v_mov_b32_e32 v5, v2
	v_mov_b32_e32 v6, v2
	v_mov_b32_e32 v7, v2
	v_mov_b32_e32 v8, v2
	v_mov_b32_e32 v9, v2
	v_mov_b32_e32 v18, v2
	v_mov_b32_e32 v19, v2
	v_mov_b32_e32 v20, v2
	v_mov_b32_e32 v21, v2
	v_mov_b32_e32 v22, v2
	v_mov_b32_e32 v23, v2
	v_mov_b32_e32 v24, v2
	v_mov_b32_e32 v25, v2
	v_mov_b32_e32 v34, v2
	v_mov_b32_e32 v35, v2
	v_mov_b32_e32 v36, v2
	v_mov_b32_e32 v37, v2
	v_mov_b32_e32 v38, v2
	v_mov_b32_e32 v39, v2
	v_mov_b32_e32 v40, v2
	v_mov_b32_e32 v41, v2
	v_mov_b32_e32 v50, v2
	v_mov_b32_e32 v51, v2
	v_mov_b32_e32 v52, v2
	v_mov_b32_e32 v53, v2
	v_mov_b32_e32 v54, v2
	v_mov_b32_e32 v55, v2
	v_mov_b32_e32 v56, v2
	v_mov_b32_e32 v57, v2
	v_mov_b32_e32 v10, v2
	v_mov_b32_e32 v11, v2
	v_mov_b32_e32 v12, v2
	v_mov_b32_e32 v13, v2
	v_mov_b32_e32 v14, v2
	v_mov_b32_e32 v15, v2
	v_mov_b32_e32 v16, v2
	v_mov_b32_e32 v17, v2
	v_mov_b32_e32 v26, v2
	v_mov_b32_e32 v27, v2
	v_mov_b32_e32 v28, v2
	v_mov_b32_e32 v29, v2
	v_mov_b32_e32 v30, v2
	v_mov_b32_e32 v31, v2
	v_mov_b32_e32 v32, v2
	v_mov_b32_e32 v33, v2
	v_mov_b32_e32 v42, v2
	v_mov_b32_e32 v43, v2
	v_mov_b32_e32 v44, v2
	v_mov_b32_e32 v45, v2
	v_mov_b32_e32 v46, v2
	v_mov_b32_e32 v47, v2
	v_mov_b32_e32 v48, v2
	v_mov_b32_e32 v49, v2
	v_mov_b32_e32 v58, v2
	v_mov_b32_e32 v59, v2
	v_mov_b32_e32 v60, v2
	v_mov_b32_e32 v61, v2
	v_mov_b32_e32 v62, v2
	v_mov_b32_e32 v63, v2
	v_mov_b32_e32 v64, v2
	v_mov_b32_e32 v65, v2
	v_mov_b32_e32 v66, v2
	v_mov_b32_e32 v67, v2
	v_mov_b32_e32 v68, v2
	v_mov_b32_e32 v69, v2
	v_mov_b32_e32 v70, v2
	v_mov_b32_e32 v71, v2
	v_mov_b32_e32 v72, v2
	v_mov_b32_e32 v73, v2
	v_mov_b32_e32 v82, v2
	v_mov_b32_e32 v83, v2
	v_mov_b32_e32 v84, v2
	v_mov_b32_e32 v85, v2
	v_mov_b32_e32 v86, v2
	v_mov_b32_e32 v87, v2
	v_mov_b32_e32 v88, v2
	v_mov_b32_e32 v89, v2
	v_mov_b32_e32 v98, v2
	v_mov_b32_e32 v99, v2
	v_mov_b32_e32 v100, v2
	v_mov_b32_e32 v101, v2
	v_mov_b32_e32 v102, v2
	v_mov_b32_e32 v103, v2
	v_mov_b32_e32 v104, v2
	v_mov_b32_e32 v105, v2
	v_mov_b32_e32 v114, v2
	v_mov_b32_e32 v115, v2
	v_mov_b32_e32 v116, v2
	v_mov_b32_e32 v117, v2
	v_mov_b32_e32 v118, v2
	v_mov_b32_e32 v119, v2
	v_mov_b32_e32 v120, v2
	v_mov_b32_e32 v121, v2
	v_mov_b32_e32 v74, v2
	v_mov_b32_e32 v75, v2
	v_mov_b32_e32 v76, v2
	v_mov_b32_e32 v77, v2
	v_mov_b32_e32 v78, v2
	v_mov_b32_e32 v79, v2
	v_mov_b32_e32 v80, v2
	v_mov_b32_e32 v81, v2
	v_mov_b32_e32 v90, v2
	v_mov_b32_e32 v91, v2
	v_mov_b32_e32 v92, v2
	v_mov_b32_e32 v93, v2
	v_mov_b32_e32 v94, v2
	v_mov_b32_e32 v95, v2
	v_mov_b32_e32 v96, v2
	v_mov_b32_e32 v97, v2
	v_mov_b32_e32 v106, v2
	v_mov_b32_e32 v107, v2
	v_mov_b32_e32 v108, v2
	v_mov_b32_e32 v109, v2
	v_mov_b32_e32 v110, v2
	v_mov_b32_e32 v111, v2
	v_mov_b32_e32 v112, v2
	v_mov_b32_e32 v113, v2
	v_mov_b32_e32 v122, v2
	v_mov_b32_e32 v123, v2
	v_mov_b32_e32 v124, v2
	v_mov_b32_e32 v125, v2
	v_mov_b32_e32 v126, v2
	v_mov_b32_e32 v127, v2
	v_mov_b32_e32 v128, v2
	v_mov_b32_e32 v129, v2
	v_add_u32_e32 v240, 0x10000, v141
.LBB0_985:
	s_add_i32 s72, s28, 2
	s_add_u32 s54, s52, 0x100
	s_addc_u32 s55, s53, 0
	s_add_i32 s35, 0, 0x10000
	ds_read_b128 v[144:147], v240
	ds_read_b128 v[148:151], v240 offset:1024
	ds_read_b128 v[152:155], v240 offset:2048
	ds_read_b128 v[156:159], v240 offset:3072
	s_cmp_eq_u32 s21, s28
	s_cselect_b32 s28, s24, s54
	s_cselect_b32 s29, s25, s55
	s_cselect_b32 s57, s27, s71
	s_cselect_b32 s56, s26, s70
	ds_read_b128 v[160:163], v143
	ds_read_b128 v[164:167], v143 offset:1024
	ds_read_b128 v[168:171], v143 offset:2048
	ds_read_b128 v[172:175], v143 offset:3072
	ds_read_b128 v[182:185], v143 offset:4096
	ds_read_b128 v[186:189], v143 offset:5120
	ds_read_b128 v[190:193], v143 offset:6144
	ds_read_b128 v[194:197], v143 offset:7168
	s_add_u32 s98, s52, 0xfff7c000
	s_addc_u32 s99, s53, -1
	s_mov_b32 m0, s62
	s_nop 0
	global_load_lds_dwordx4 v136, s[98:99]
	s_mov_b32 m0, s63
	s_nop 0
	global_load_lds_dwordx4 v138, s[98:99]
	s_add_i32 m0, s9, 0xc000
	s_nop 0
	global_load_lds_dwordx4 v136, s[52:53]
	s_add_i32 m0, s9, 0xe000
	s_nop 0
	global_load_lds_dwordx4 v138, s[52:53]
	s_add_i32 s76, 0, 0x14000
	ds_read_b128 v[198:201], v240 offset:16384
	ds_read_b128 v[202:205], v240 offset:17408
	ds_read_b128 v[206:209], v240 offset:18432
	ds_read_b128 v[210:213], v240 offset:19456
	s_waitcnt lgkmcnt(0)
	s_barrier
; #define PG8_STAGE(bufoff, gbase, voff) do { _Pragma("unroll") for (int _i = 0; _i < 2; ++_i) \
;         __builtin_amdgcn_global_load_lds((const unsigned*)((const char*)(gbase) + (voff)[_i]), (LAS unsigned*)(lds + (bufoff) + ldsw + _i * 8192), 16, 0, 0); } while (0)
; #define PG8_LDA(dst, b, h) do { _Pragma("unroll") for (int m = 0; m < 4; ++m) _Pragma("unroll") for (int k = 0; k < 2; ++k) dst[m][k] = *(const LAS bf16x8*)(lds + PG8_SA(b, h) + aoff + m * 2048 + k * 1024); } while (0)
; #define PG8_LDB(dst, b, h) do { _Pragma("unroll") for (int n = 0; n < 2; ++n) _Pragma("unroll") for (int k = 0; k < 2; ++k) dst[n][k] = *(const LAS bf16x8*)(lds + PG8_SB(b, h) + boff + n * 2048 + k * 1024); } while (0)
; #define PG8_MMA(ai, bj, At, Bt) do { __builtin_amdgcn_s_setprio(1); _Pragma("unroll") for (int m = 0; m < 4; ++m) _Pragma("unroll") for (int n = 0; n < 2; ++n) _Pragma("unroll") for (int k = 0; k < 2; ++k) \
;         acc[ai][bj][m][n] = __builtin_amdgcn_mfma_f32_16x16x32_bf16(Bt[n][k], At[m][k], acc[ai][bj][m][n], 0, 0, 0); __builtin_amdgcn_s_setprio(0); } while (0)
; #define PG8_WAIT_V(n) asm volatile("s_waitcnt vmcnt(" #n ")" ::: "memory")
; #define PG8_WAIT_L(n) asm volatile("s_waitcnt lgkmcnt(" #n ")" ::: "memory")
; #define PG8_BAR __builtin_amdgcn_s_barrier()
; #define PG8_SCHED __builtin_amdgcn_sched_barrier(0)
; template <class Epi, class Sched>
; __device__ __forceinline__ void gemm_phase(LAS unsigned char* lds, const Gemm g, const Sched& S, const Epi& E) {
;     ...
;             PG8_WAIT_L(8); PG8_BAR; PG8_WAIT_L(0); PG8_MMA(0, 0, At, B0); PG8_BAR; PG8_SCHED;
;             PG8_LDB(B1, 0, 1); PG8_STAGE(PG8_SB(0, 0), b2, voffB);
;             PG8_BAR; PG8_WAIT_L(0); PG8_MMA(0, 1, At, B1); PG8_BAR;
;             PG8_LDA(At, 0, 1); PG8_STAGE(PG8_SA(0, 0), a2, voffA);
;             PG8_BAR; PG8_WAIT_L(0); PG8_MMA(1, 0, At, B0); PG8_BAR; PG8_SCHED;
;             PG8_STAGE(PG8_SB(0, 1), b2 + hstepB, voffB);
;             PG8_WAIT_V(6); PG8_BAR; PG8_MMA(1, 1, At, B1); PG8_BAR;
;             PG8_LDB(B0, 1, 0); PG8_SCHED; PG8_LDA(At, 1, 0); PG8_STAGE(PG8_SA(0, 1), a2 + hstepA, voffA);
	v_mfma_f32_16x16x32_bf16 v[126:129], v[144:147], v[160:163], v[126:129]
	v_mfma_f32_16x16x32_bf16 v[126:129], v[148:151], v[164:167], v[126:129]
	v_mfma_f32_16x16x32_bf16 v[110:113], v[144:147], v[168:171], v[110:113]
	v_mfma_f32_16x16x32_bf16 v[110:113], v[148:151], v[172:175], v[110:113]
	v_mfma_f32_16x16x32_bf16 v[94:97], v[144:147], v[182:185], v[94:97]
	v_mfma_f32_16x16x32_bf16 v[94:97], v[148:151], v[186:189], v[94:97]
	v_mfma_f32_16x16x32_bf16 v[78:81], v[144:147], v[190:193], v[78:81]
	v_mfma_f32_16x16x32_bf16 v[78:81], v[148:151], v[194:197], v[78:81]
	v_mfma_f32_16x16x32_bf16 v[122:125], v[152:155], v[160:163], v[122:125]
	v_mfma_f32_16x16x32_bf16 v[122:125], v[156:159], v[164:167], v[122:125]
	v_mfma_f32_16x16x32_bf16 v[106:109], v[152:155], v[168:171], v[106:109]
	v_mfma_f32_16x16x32_bf16 v[106:109], v[156:159], v[172:175], v[106:109]
	v_mfma_f32_16x16x32_bf16 v[90:93], v[152:155], v[182:185], v[90:93]
	v_mfma_f32_16x16x32_bf16 v[90:93], v[156:159], v[186:189], v[90:93]
	v_mfma_f32_16x16x32_bf16 v[74:77], v[152:155], v[190:193], v[74:77]
	v_mfma_f32_16x16x32_bf16 v[74:77], v[156:159], v[194:197], v[74:77]
	v_mfma_f32_16x16x32_bf16 v[118:121], v[198:201], v[160:163], v[118:121]
	v_mfma_f32_16x16x32_bf16 v[118:121], v[202:205], v[164:167], v[118:121]
	v_mfma_f32_16x16x32_bf16 v[102:105], v[198:201], v[168:171], v[102:105]
	v_mfma_f32_16x16x32_bf16 v[102:105], v[202:205], v[172:175], v[102:105]
	v_mfma_f32_16x16x32_bf16 v[86:89], v[198:201], v[182:185], v[86:89]
	v_mfma_f32_16x16x32_bf16 v[86:89], v[202:205], v[186:189], v[86:89]
	v_mfma_f32_16x16x32_bf16 v[70:73], v[198:201], v[190:193], v[70:73]
	v_mfma_f32_16x16x32_bf16 v[70:73], v[202:205], v[194:197], v[70:73]
	v_mfma_f32_16x16x32_bf16 v[114:117], v[206:209], v[160:163], v[114:117]
	v_mfma_f32_16x16x32_bf16 v[114:117], v[210:213], v[164:167], v[114:117]
	v_mfma_f32_16x16x32_bf16 v[98:101], v[206:209], v[168:171], v[98:101]
	v_mfma_f32_16x16x32_bf16 v[98:101], v[210:213], v[172:175], v[98:101]
	v_mfma_f32_16x16x32_bf16 v[82:85], v[206:209], v[182:185], v[82:85]
	v_mfma_f32_16x16x32_bf16 v[82:85], v[210:213], v[186:189], v[82:85]
	v_mfma_f32_16x16x32_bf16 v[66:69], v[206:209], v[190:193], v[66:69]
	v_mfma_f32_16x16x32_bf16 v[66:69], v[210:213], v[194:197], v[66:69]
	s_barrier
	ds_read_b128 v[160:163], v143 offset:16384
	ds_read_b128 v[164:167], v143 offset:17408
	ds_read_b128 v[168:171], v143 offset:18432
	ds_read_b128 v[172:175], v143 offset:19456
	ds_read_b128 v[182:185], v143 offset:20480
	ds_read_b128 v[186:189], v143 offset:21504
	ds_read_b128 v[190:193], v143 offset:22528
	ds_read_b128 v[194:197], v143 offset:23552
	s_add_i32 s35, s35, s46
	s_mov_b32 m0, s35
	s_nop 0
	global_load_lds_dwordx4 v178, s[56:57]
	s_add_i32 m0, s35, 0x2000
	s_nop 0
	global_load_lds_dwordx4 v134, s[56:57]
	s_add_u32 s52, s56, 0x80000
	s_addc_u32 s53, s57, 0
	s_add_i32 s35, s76, s46
	s_mov_b32 m0, s35
	s_nop 0
	global_load_lds_dwordx4 v178, s[52:53]
	s_add_i32 m0, s35, 0x2000
	s_nop 0
	global_load_lds_dwordx4 v134, s[52:53]
	s_waitcnt vmcnt(4)
	s_waitcnt lgkmcnt(0)
	s_barrier
	v_mfma_f32_16x16x32_bf16 v[62:65], v[144:147], v[160:163], v[62:65]
	v_mfma_f32_16x16x32_bf16 v[62:65], v[148:151], v[164:167], v[62:65]
	v_mfma_f32_16x16x32_bf16 v[46:49], v[144:147], v[168:171], v[46:49]
	v_mfma_f32_16x16x32_bf16 v[46:49], v[148:151], v[172:175], v[46:49]
	v_mfma_f32_16x16x32_bf16 v[30:33], v[144:147], v[182:185], v[30:33]
	v_mfma_f32_16x16x32_bf16 v[30:33], v[148:151], v[186:189], v[30:33]
	v_mfma_f32_16x16x32_bf16 v[14:17], v[144:147], v[190:193], v[14:17]
	v_mfma_f32_16x16x32_bf16 v[14:17], v[148:151], v[194:197], v[14:17]
	v_mfma_f32_16x16x32_bf16 v[58:61], v[152:155], v[160:163], v[58:61]
	v_mfma_f32_16x16x32_bf16 v[58:61], v[156:159], v[164:167], v[58:61]
	v_mfma_f32_16x16x32_bf16 v[42:45], v[152:155], v[168:171], v[42:45]
	v_mfma_f32_16x16x32_bf16 v[42:45], v[156:159], v[172:175], v[42:45]
	v_mfma_f32_16x16x32_bf16 v[26:29], v[152:155], v[182:185], v[26:29]
	v_mfma_f32_16x16x32_bf16 v[26:29], v[156:159], v[186:189], v[26:29]
	v_mfma_f32_16x16x32_bf16 v[10:13], v[152:155], v[190:193], v[10:13]
	v_mfma_f32_16x16x32_bf16 v[10:13], v[156:159], v[194:197], v[10:13]
	v_mfma_f32_16x16x32_bf16 v[54:57], v[198:201], v[160:163], v[54:57]
	v_mfma_f32_16x16x32_bf16 v[54:57], v[202:205], v[164:167], v[54:57]
	v_mfma_f32_16x16x32_bf16 v[38:41], v[198:201], v[168:171], v[38:41]
	v_mfma_f32_16x16x32_bf16 v[38:41], v[202:205], v[172:175], v[38:41]
	v_mfma_f32_16x16x32_bf16 v[22:25], v[198:201], v[182:185], v[22:25]
	v_mfma_f32_16x16x32_bf16 v[22:25], v[202:205], v[186:189], v[22:25]
	v_mfma_f32_16x16x32_bf16 v[6:9], v[198:201], v[190:193], v[6:9]
	v_mfma_f32_16x16x32_bf16 v[6:9], v[202:205], v[194:197], v[6:9]
	v_mfma_f32_16x16x32_bf16 v[50:53], v[206:209], v[160:163], v[50:53]
	v_mfma_f32_16x16x32_bf16 v[50:53], v[210:213], v[164:167], v[50:53]
	v_mfma_f32_16x16x32_bf16 v[34:37], v[206:209], v[168:171], v[34:37]
	v_mfma_f32_16x16x32_bf16 v[34:37], v[210:213], v[172:175], v[34:37]
	v_mfma_f32_16x16x32_bf16 v[18:21], v[206:209], v[182:185], v[18:21]
	v_mfma_f32_16x16x32_bf16 v[18:21], v[210:213], v[186:189], v[18:21]
	v_mfma_f32_16x16x32_bf16 v[2:5], v[206:209], v[190:193], v[2:5]
	v_mfma_f32_16x16x32_bf16 v[2:5], v[210:213], v[194:197], v[2:5]
	s_add_i32 s35, 0, 0x18000
	s_barrier
; #define PG8_STAGE(bufoff, gbase, voff) do { _Pragma("unroll") for (int _i = 0; _i < 2; ++_i) \
;         __builtin_amdgcn_global_load_lds((const unsigned*)((const char*)(gbase) + (voff)[_i]), (LAS unsigned*)(lds + (bufoff) + ldsw + _i * 8192), 16, 0, 0); } while (0)
; #define PG8_LDA(dst, b, h) do { _Pragma("unroll") for (int m = 0; m < 4; ++m) _Pragma("unroll") for (int k = 0; k < 2; ++k) dst[m][k] = *(const LAS bf16x8*)(lds + PG8_SA(b, h) + aoff + m * 2048 + k * 1024); } while (0)
; #define PG8_LDB(dst, b, h) do { _Pragma("unroll") for (int n = 0; n < 2; ++n) _Pragma("unroll") for (int k = 0; k < 2; ++k) dst[n][k] = *(const LAS bf16x8*)(lds + PG8_SB(b, h) + boff + n * 2048 + k * 1024); } while (0)
; #define PG8_MMA(ai, bj, At, Bt) do { __builtin_amdgcn_s_setprio(1); _Pragma("unroll") for (int m = 0; m < 4; ++m) _Pragma("unroll") for (int n = 0; n < 2; ++n) _Pragma("unroll") for (int k = 0; k < 2; ++k) \
;         acc[ai][bj][m][n] = __builtin_amdgcn_mfma_f32_16x16x32_bf16(Bt[n][k], At[m][k], acc[ai][bj][m][n], 0, 0, 0); __builtin_amdgcn_s_setprio(0); } while (0)
; #define PG8_WAIT_V(n) asm volatile("s_waitcnt vmcnt(" #n ")" ::: "memory")
; #define PG8_WAIT_L(n) asm volatile("s_waitcnt lgkmcnt(" #n ")" ::: "memory")
; #define PG8_BAR __builtin_amdgcn_s_barrier()
; #define PG8_SCHED __builtin_amdgcn_sched_barrier(0)
; template <class Epi, class Sched>
; __device__ __forceinline__ void gemm_phase(LAS unsigned char* lds, const Gemm g, const Sched& S, const Epi& E) {
;     ...
;             PG8_LDB(B0, 1, 0); PG8_SCHED; PG8_LDA(At, 1, 0); PG8_STAGE(PG8_SA(0, 1), a2 + hstepA, voffA);
;             PG8_WAIT_L(8); PG8_BAR; PG8_WAIT_L(0); PG8_MMA(0, 0, At, B0); PG8_BAR; PG8_SCHED;
;             PG8_LDB(B1, 1, 1); PG8_STAGE(PG8_SB(1, 0), b3, voffB);
;             PG8_BAR; PG8_WAIT_L(0); PG8_MMA(0, 1, At, B1); PG8_BAR;
;             PG8_LDA(At, 1, 1); PG8_STAGE(PG8_SA(1, 0), a3, voffA);
;             PG8_BAR; PG8_WAIT_L(0); PG8_MMA(1, 0, At, B0); PG8_BAR; PG8_SCHED;
;             PG8_STAGE(PG8_SB(1, 1), b3 + hstepB, voffB);
;             PG8_WAIT_V(6); PG8_BAR; PG8_MMA(1, 1, At, B1); PG8_BAR;
;         }
	ds_read_b128 v[144:147], v240 offset:32768
	ds_read_b128 v[148:151], v240 offset:33792
	ds_read_b128 v[152:155], v240 offset:34816
	ds_read_b128 v[156:159], v240 offset:35840
	ds_read_b128 v[160:163], v143 offset:32768
	ds_read_b128 v[164:167], v143 offset:33792
	ds_read_b128 v[168:171], v143 offset:34816
	ds_read_b128 v[172:175], v143 offset:35840
	ds_read_b128 v[182:185], v143 offset:36864
	ds_read_b128 v[186:189], v143 offset:37888
	ds_read_b128 v[190:193], v143 offset:38912
	ds_read_b128 v[194:197], v143 offset:39936
	s_mov_b32 m0, s9
	s_nop 0
	global_load_lds_dwordx4 v130, s[28:29]
	s_mov_b32 m0, s11
	s_nop 0
	global_load_lds_dwordx4 v132, s[28:29]
	s_add_u32 s28, s28, 0x84000
	s_addc_u32 s29, s29, 0
	s_mov_b32 m0, s58
	s_nop 0
	global_load_lds_dwordx4 v130, s[28:29]
	s_mov_b32 m0, s59
	s_nop 0
	global_load_lds_dwordx4 v132, s[28:29]
	s_add_i32 s52, 0, 0x1c000
	ds_read_b128 v[198:201], v240 offset:49152
	ds_read_b128 v[202:205], v240 offset:50176
	ds_read_b128 v[206:209], v240 offset:51200
	ds_read_b128 v[210:213], v240 offset:52224
	s_waitcnt lgkmcnt(0)
	s_barrier
	v_mfma_f32_16x16x32_bf16 v[126:129], v[144:147], v[160:163], v[126:129]
	v_mfma_f32_16x16x32_bf16 v[126:129], v[148:151], v[164:167], v[126:129]
	v_mfma_f32_16x16x32_bf16 v[110:113], v[144:147], v[168:171], v[110:113]
	v_mfma_f32_16x16x32_bf16 v[110:113], v[148:151], v[172:175], v[110:113]
	v_mfma_f32_16x16x32_bf16 v[94:97], v[144:147], v[182:185], v[94:97]
	v_mfma_f32_16x16x32_bf16 v[94:97], v[148:151], v[186:189], v[94:97]
	v_mfma_f32_16x16x32_bf16 v[78:81], v[144:147], v[190:193], v[78:81]
	v_mfma_f32_16x16x32_bf16 v[78:81], v[148:151], v[194:197], v[78:81]
	v_mfma_f32_16x16x32_bf16 v[122:125], v[152:155], v[160:163], v[122:125]
	v_mfma_f32_16x16x32_bf16 v[122:125], v[156:159], v[164:167], v[122:125]
	v_mfma_f32_16x16x32_bf16 v[106:109], v[152:155], v[168:171], v[106:109]
	v_mfma_f32_16x16x32_bf16 v[106:109], v[156:159], v[172:175], v[106:109]
	v_mfma_f32_16x16x32_bf16 v[90:93], v[152:155], v[182:185], v[90:93]
	v_mfma_f32_16x16x32_bf16 v[90:93], v[156:159], v[186:189], v[90:93]
	v_mfma_f32_16x16x32_bf16 v[74:77], v[152:155], v[190:193], v[74:77]
	v_mfma_f32_16x16x32_bf16 v[74:77], v[156:159], v[194:197], v[74:77]
	v_mfma_f32_16x16x32_bf16 v[118:121], v[198:201], v[160:163], v[118:121]
	v_mfma_f32_16x16x32_bf16 v[118:121], v[202:205], v[164:167], v[118:121]
	v_mfma_f32_16x16x32_bf16 v[102:105], v[198:201], v[168:171], v[102:105]
	v_mfma_f32_16x16x32_bf16 v[102:105], v[202:205], v[172:175], v[102:105]
	v_mfma_f32_16x16x32_bf16 v[86:89], v[198:201], v[182:185], v[86:89]
	v_mfma_f32_16x16x32_bf16 v[86:89], v[202:205], v[186:189], v[86:89]
	v_mfma_f32_16x16x32_bf16 v[70:73], v[198:201], v[190:193], v[70:73]
	v_mfma_f32_16x16x32_bf16 v[70:73], v[202:205], v[194:197], v[70:73]
	v_mfma_f32_16x16x32_bf16 v[114:117], v[206:209], v[160:163], v[114:117]
	v_mfma_f32_16x16x32_bf16 v[114:117], v[210:213], v[164:167], v[114:117]
	v_mfma_f32_16x16x32_bf16 v[98:101], v[206:209], v[168:171], v[98:101]
	v_mfma_f32_16x16x32_bf16 v[98:101], v[210:213], v[172:175], v[98:101]
	v_mfma_f32_16x16x32_bf16 v[82:85], v[206:209], v[182:185], v[82:85]
	v_mfma_f32_16x16x32_bf16 v[82:85], v[210:213], v[186:189], v[82:85]
	v_mfma_f32_16x16x32_bf16 v[66:69], v[206:209], v[190:193], v[66:69]
	v_mfma_f32_16x16x32_bf16 v[66:69], v[210:213], v[194:197], v[66:69]
	s_barrier
	ds_read_b128 v[160:163], v143 offset:49152
	ds_read_b128 v[164:167], v143 offset:50176
	ds_read_b128 v[168:171], v143 offset:51200
	ds_read_b128 v[172:175], v143 offset:52224
	ds_read_b128 v[182:185], v143 offset:53248
	ds_read_b128 v[186:189], v143 offset:54272
	ds_read_b128 v[190:193], v143 offset:55296
	ds_read_b128 v[194:197], v143 offset:56320
	s_add_u32 s98, s56, 0x80
	s_addc_u32 s99, s57, 0
	s_add_i32 s28, s35, s46
	s_mov_b32 m0, s28
	s_nop 0
	global_load_lds_dwordx4 v178, s[98:99]
	s_add_i32 m0, s28, 0x2000
	s_nop 0
	global_load_lds_dwordx4 v134, s[98:99]
	s_add_u32 s28, s56, 0x80080
	s_addc_u32 s29, s57, 0
	s_add_i32 s35, s52, s46
	s_mov_b32 m0, s35
	s_nop 0
	global_load_lds_dwordx4 v178, s[28:29]
	s_add_i32 m0, s35, 0x2000
	s_nop 0
	global_load_lds_dwordx4 v134, s[28:29]
	s_waitcnt vmcnt(4)
	s_waitcnt lgkmcnt(0)
	s_barrier
	v_mfma_f32_16x16x32_bf16 v[62:65], v[144:147], v[160:163], v[62:65]
	v_mfma_f32_16x16x32_bf16 v[62:65], v[148:151], v[164:167], v[62:65]
	v_mfma_f32_16x16x32_bf16 v[46:49], v[144:147], v[168:171], v[46:49]
	v_mfma_f32_16x16x32_bf16 v[46:49], v[148:151], v[172:175], v[46:49]
	v_mfma_f32_16x16x32_bf16 v[30:33], v[144:147], v[182:185], v[30:33]
	v_mfma_f32_16x16x32_bf16 v[30:33], v[148:151], v[186:189], v[30:33]
	v_mfma_f32_16x16x32_bf16 v[14:17], v[144:147], v[190:193], v[14:17]
	v_mfma_f32_16x16x32_bf16 v[14:17], v[148:151], v[194:197], v[14:17]
	v_mfma_f32_16x16x32_bf16 v[58:61], v[152:155], v[160:163], v[58:61]
	v_mfma_f32_16x16x32_bf16 v[58:61], v[156:159], v[164:167], v[58:61]
	v_mfma_f32_16x16x32_bf16 v[42:45], v[152:155], v[168:171], v[42:45]
	v_mfma_f32_16x16x32_bf16 v[42:45], v[156:159], v[172:175], v[42:45]
	v_mfma_f32_16x16x32_bf16 v[26:29], v[152:155], v[182:185], v[26:29]
	v_mfma_f32_16x16x32_bf16 v[26:29], v[156:159], v[186:189], v[26:29]
	v_mfma_f32_16x16x32_bf16 v[10:13], v[152:155], v[190:193], v[10:13]
	v_mfma_f32_16x16x32_bf16 v[10:13], v[156:159], v[194:197], v[10:13]
	v_mfma_f32_16x16x32_bf16 v[54:57], v[198:201], v[160:163], v[54:57]
	v_mfma_f32_16x16x32_bf16 v[54:57], v[202:205], v[164:167], v[54:57]
	v_mfma_f32_16x16x32_bf16 v[38:41], v[198:201], v[168:171], v[38:41]
	v_mfma_f32_16x16x32_bf16 v[38:41], v[202:205], v[172:175], v[38:41]
	v_mfma_f32_16x16x32_bf16 v[22:25], v[198:201], v[182:185], v[22:25]
	v_mfma_f32_16x16x32_bf16 v[22:25], v[202:205], v[186:189], v[22:25]
	v_mfma_f32_16x16x32_bf16 v[6:9], v[198:201], v[190:193], v[6:9]
	v_mfma_f32_16x16x32_bf16 v[6:9], v[202:205], v[194:197], v[6:9]
	v_mfma_f32_16x16x32_bf16 v[50:53], v[206:209], v[160:163], v[50:53]
	v_mfma_f32_16x16x32_bf16 v[50:53], v[210:213], v[164:167], v[50:53]
	v_mfma_f32_16x16x32_bf16 v[34:37], v[206:209], v[168:171], v[34:37]
	v_mfma_f32_16x16x32_bf16 v[34:37], v[210:213], v[172:175], v[34:37]
	v_mfma_f32_16x16x32_bf16 v[18:21], v[206:209], v[182:185], v[18:21]
	v_mfma_f32_16x16x32_bf16 v[18:21], v[210:213], v[186:189], v[18:21]
	v_mfma_f32_16x16x32_bf16 v[2:5], v[206:209], v[190:193], v[2:5]
	v_mfma_f32_16x16x32_bf16 v[2:5], v[210:213], v[194:197], v[2:5]
	s_add_u32 s70, s70, 0x100
	s_addc_u32 s71, s71, 0
	s_cmp_ge_i32 s72, s17
	s_mov_b64 s[52:53], s[54:55]
	s_mov_b32 s28, s72
	s_barrier
	s_cbranch_scc0 .LBB0_985
	v_readlane_b32 s70, v255, 24
	v_readlane_b32 s76, v255, 26
	v_readlane_b32 s71, v255, 25
	v_readlane_b32 s77, v255, 27
	s_andn2_b64 vcc, exec, s[50:51]
	s_mov_b64 s[28:29], s[12:13]
	s_cbranch_vccnz .LBB0_967
	s_branch .LBB0_966

; #define PG8_STAGE(bufoff, gbase, voff) do { _Pragma("unroll") for (int _i = 0; _i < 2; ++_i) \
;         __builtin_amdgcn_global_load_lds((const unsigned*)((const char*)(gbase) + (voff)[_i]), (LAS unsigned*)(lds + (bufoff) + ldsw + _i * 8192), 16, 0, 0); } while (0)
; #define PG8_LDA(dst, b, h) do { _Pragma("unroll") for (int m = 0; m < 4; ++m) _Pragma("unroll") for (int k = 0; k < 2; ++k) dst[m][k] = *(const LAS bf16x8*)(lds + PG8_SA(b, h) + aoff + m * 2048 + k * 1024); } while (0)
; #define PG8_LDB(dst, b, h) do { _Pragma("unroll") for (int n = 0; n < 2; ++n) _Pragma("unroll") for (int k = 0; k < 2; ++k) dst[n][k] = *(const LAS bf16x8*)(lds + PG8_SB(b, h) + boff + n * 2048 + k * 1024); } while (0)
; #define PG8_SCHED __builtin_amdgcn_sched_barrier(0)
; template <class Epi, class Sched>
; __device__ __forceinline__ void gemm_phase(LAS unsigned char* lds, const Gemm g, const Sched& S, const Epi& E) {
;     ...
;         const bool has_next = S.next(ui + 1, nxt);
;         const char* nA = has_next ? (const char*)g.A + (size_t)nxt.seg * g.segA + (size_t)nxt.pm * tstepA : cA;
;         const char* nB = has_next ? (const char*)g.Bt + (size_t)nxt.seg * g.segB + (size_t)nxt.pn * tstepB : cB;
;         const int ntu = cur.nt ? cur.nt : nt;
;         for (int t = 0; t < ntu; t += 2) {
;             const bool last = (t == ntu - 2);
;             const char* a1 = cA + (size_t)(t + 1) * kstep;
;             const char* a2 = last ? nA : cA + (size_t)(t + 2) * kstep; const char* b2 = last ? nB : cB + (size_t)(t + 2) * kstep;
;             const char* a3 = a2 + kstep; const char* b3 = b2 + kstep;
;             if (last && has_next) S.a_ready(nxt);
;             PG8_LDB(B0, 0, 0); PG8_SCHED; PG8_LDA(At, 0, 0); PG8_STAGE(PG8_SA(1, 1), a1 + hstepA, voffA);
;     ...
;             for (int a = 0; a < 2; ++a)
; #pragma unroll
;                 for (int b = 0; b < 2; ++b)
; #pragma unroll
;                     for (int m = 0; m < 4; ++m)
; #pragma unroll
;                         for (int n = 0; n < 2; ++n) acc[a][b][m][n] = (f32x4){0.f, 0.f, 0.f, 0.f};
.LBB0_1139:
	v_mov_b64_e32 v[2:3], s[30:31]
	s_ashr_i32 s13, s12, 31
	v_cmp_lt_i64_e32 vcc, s[16:17], v[2:3]
	s_lshl_b64 s[16:17], s[12:13], 20
	s_add_u32 s16, s36, s16
	s_addc_u32 s17, s37, s17
	s_and_b64 s[20:21], vcc, exec
	s_cselect_b32 s13, s17, s27
	s_cselect_b32 s57, s16, s26
	s_ashr_i32 s11, s10, 31
	s_lshl_b64 s[20:21], s[10:11], 20
	s_add_u32 s20, s38, s20
	s_addc_u32 s21, s39, s21
	s_and_b64 s[28:29], vcc, exec
	s_cselect_b32 s11, s21, s51
	s_cselect_b32 s58, s20, s50
	s_add_u32 s26, s26, 0x80080
	s_addc_u32 s27, s27, 0
	s_add_u32 s59, s50, 0x100
	v_mov_b32_e32 v2, 0
	s_addc_u32 s62, s51, 0
	s_mov_b32 s63, -2
	v_mov_b32_e32 v3, v2
	v_mov_b32_e32 v4, v2
	v_mov_b32_e32 v5, v2
	v_mov_b32_e32 v10, v2
	v_mov_b32_e32 v11, v2
	v_mov_b32_e32 v12, v2
	v_mov_b32_e32 v13, v2
	v_mov_b32_e32 v18, v2
	v_mov_b32_e32 v19, v2
	v_mov_b32_e32 v20, v2
	v_mov_b32_e32 v21, v2
	v_mov_b32_e32 v26, v2
	v_mov_b32_e32 v27, v2
	v_mov_b32_e32 v28, v2
	v_mov_b32_e32 v29, v2
	v_mov_b32_e32 v34, v2
	v_mov_b32_e32 v35, v2
	v_mov_b32_e32 v36, v2
	v_mov_b32_e32 v37, v2
	v_mov_b32_e32 v42, v2
	v_mov_b32_e32 v43, v2
	v_mov_b32_e32 v44, v2
	v_mov_b32_e32 v45, v2
	v_mov_b32_e32 v50, v2
	v_mov_b32_e32 v51, v2
	v_mov_b32_e32 v52, v2
	v_mov_b32_e32 v53, v2
	v_mov_b32_e32 v58, v2
	v_mov_b32_e32 v59, v2
	v_mov_b32_e32 v60, v2
	v_mov_b32_e32 v61, v2
	v_mov_b32_e32 v6, v2
	v_mov_b32_e32 v7, v2
	v_mov_b32_e32 v8, v2
	v_mov_b32_e32 v9, v2
	v_mov_b32_e32 v14, v2
	v_mov_b32_e32 v15, v2
	v_mov_b32_e32 v16, v2
	v_mov_b32_e32 v17, v2
	v_mov_b32_e32 v22, v2
	v_mov_b32_e32 v23, v2
	v_mov_b32_e32 v24, v2
	v_mov_b32_e32 v25, v2
	v_mov_b32_e32 v30, v2
	v_mov_b32_e32 v31, v2
	v_mov_b32_e32 v32, v2
	v_mov_b32_e32 v33, v2
	v_mov_b32_e32 v38, v2
	v_mov_b32_e32 v39, v2
	v_mov_b32_e32 v40, v2
	v_mov_b32_e32 v41, v2
	v_mov_b32_e32 v46, v2
	v_mov_b32_e32 v47, v2
	v_mov_b32_e32 v48, v2
	v_mov_b32_e32 v49, v2
	v_mov_b32_e32 v54, v2
	v_mov_b32_e32 v55, v2
	v_mov_b32_e32 v56, v2
	v_mov_b32_e32 v57, v2
	v_mov_b32_e32 v62, v2
	v_mov_b32_e32 v63, v2
	v_mov_b32_e32 v64, v2
	v_mov_b32_e32 v65, v2
	v_mov_b32_e32 v66, v2
	v_mov_b32_e32 v67, v2
	v_mov_b32_e32 v68, v2
	v_mov_b32_e32 v69, v2
	v_mov_b32_e32 v74, v2
	v_mov_b32_e32 v75, v2
	v_mov_b32_e32 v76, v2
	v_mov_b32_e32 v77, v2
	v_mov_b32_e32 v82, v2
	v_mov_b32_e32 v83, v2
	v_mov_b32_e32 v84, v2
	v_mov_b32_e32 v85, v2
	v_mov_b32_e32 v90, v2
	v_mov_b32_e32 v91, v2
	v_mov_b32_e32 v92, v2
	v_mov_b32_e32 v93, v2
	v_mov_b32_e32 v98, v2
	v_mov_b32_e32 v99, v2
	v_mov_b32_e32 v100, v2
	v_mov_b32_e32 v101, v2
	v_mov_b32_e32 v106, v2
	v_mov_b32_e32 v107, v2
	v_mov_b32_e32 v108, v2
	v_mov_b32_e32 v109, v2
	v_mov_b32_e32 v114, v2
	v_mov_b32_e32 v115, v2
	v_mov_b32_e32 v116, v2
	v_mov_b32_e32 v117, v2
	v_mov_b32_e32 v122, v2
	v_mov_b32_e32 v123, v2
	v_mov_b32_e32 v124, v2
	v_mov_b32_e32 v125, v2
	v_mov_b32_e32 v70, v2
	v_mov_b32_e32 v71, v2
	v_mov_b32_e32 v72, v2
	v_mov_b32_e32 v73, v2
	v_mov_b32_e32 v78, v2
	v_mov_b32_e32 v79, v2
	v_mov_b32_e32 v80, v2
	v_mov_b32_e32 v81, v2
	v_mov_b32_e32 v86, v2
	v_mov_b32_e32 v87, v2
	v_mov_b32_e32 v88, v2
	v_mov_b32_e32 v89, v2
	v_mov_b32_e32 v94, v2
	v_mov_b32_e32 v95, v2
	v_mov_b32_e32 v96, v2
	v_mov_b32_e32 v97, v2
	v_mov_b32_e32 v102, v2
	v_mov_b32_e32 v103, v2
	v_mov_b32_e32 v104, v2
	v_mov_b32_e32 v105, v2
	v_mov_b32_e32 v110, v2
	v_mov_b32_e32 v111, v2
	v_mov_b32_e32 v112, v2
	v_mov_b32_e32 v113, v2
	v_mov_b32_e32 v118, v2
	v_mov_b32_e32 v119, v2
	v_mov_b32_e32 v120, v2
	v_mov_b32_e32 v121, v2
	v_mov_b32_e32 v126, v2
	v_mov_b32_e32 v127, v2
	v_mov_b32_e32 v128, v2
	v_mov_b32_e32 v129, v2
	v_add_u32_e32 v240, 0x10000, v143
.LBB0_1140:
	s_add_u32 s28, s26, 0xfff80080
	s_addc_u32 s29, s27, -1
	s_add_i32 s35, 0, 0x10000
	ds_read_b128 v[146:149], v240
	ds_read_b128 v[150:153], v240 offset:1024
	ds_read_b128 v[154:157], v240 offset:2048
	ds_read_b128 v[158:161], v240 offset:3072
	s_cmp_eq_u32 s63, 28
	s_cselect_b32 s29, s13, s29
	s_cselect_b32 s28, s57, s28
	s_cselect_b32 s51, s11, s62
	s_cselect_b32 s50, s58, s59
	ds_read_b128 v[162:165], v145
	ds_read_b128 v[166:169], v145 offset:1024
	ds_read_b128 v[170:173], v145 offset:2048
	ds_read_b128 v[174:177], v145 offset:3072
	ds_read_b128 v[182:185], v145 offset:4096
	ds_read_b128 v[186:189], v145 offset:5120
	ds_read_b128 v[190:193], v145 offset:6144
	ds_read_b128 v[194:197], v145 offset:7168
	s_add_u32 s98, s26, 0xfff80000
	s_addc_u32 s99, s27, -1
	s_mov_b32 m0, s54
	s_nop 0
	global_load_lds_dwordx4 v136, s[98:99]
	s_mov_b32 m0, s55
	s_nop 0
	global_load_lds_dwordx4 v138, s[98:99]
	s_add_i32 m0, s23, 0xc000
	s_nop 0
	global_load_lds_dwordx4 v136, s[26:27]
	s_add_i32 m0, s23, 0xe000
	s_nop 0
	global_load_lds_dwordx4 v138, s[26:27]
	s_add_i32 s66, 0, 0x14000
	ds_read_b128 v[198:201], v240 offset:16384
	ds_read_b128 v[202:205], v240 offset:17408
	ds_read_b128 v[206:209], v240 offset:18432
	ds_read_b128 v[210:213], v240 offset:19456
	s_waitcnt lgkmcnt(0)
	s_barrier
; #define PG8_STAGE(bufoff, gbase, voff) do { _Pragma("unroll") for (int _i = 0; _i < 2; ++_i) \
;         __builtin_amdgcn_global_load_lds((const unsigned*)((const char*)(gbase) + (voff)[_i]), (LAS unsigned*)(lds + (bufoff) + ldsw + _i * 8192), 16, 0, 0); } while (0)
; #define PG8_LDA(dst, b, h) do { _Pragma("unroll") for (int m = 0; m < 4; ++m) _Pragma("unroll") for (int k = 0; k < 2; ++k) dst[m][k] = *(const LAS bf16x8*)(lds + PG8_SA(b, h) + aoff + m * 2048 + k * 1024); } while (0)
; #define PG8_LDB(dst, b, h) do { _Pragma("unroll") for (int n = 0; n < 2; ++n) _Pragma("unroll") for (int k = 0; k < 2; ++k) dst[n][k] = *(const LAS bf16x8*)(lds + PG8_SB(b, h) + boff + n * 2048 + k * 1024); } while (0)
; #define PG8_MMA(ai, bj, At, Bt) do { __builtin_amdgcn_s_setprio(1); _Pragma("unroll") for (int m = 0; m < 4; ++m) _Pragma("unroll") for (int n = 0; n < 2; ++n) _Pragma("unroll") for (int k = 0; k < 2; ++k) \
;         acc[ai][bj][m][n] = __builtin_amdgcn_mfma_f32_16x16x32_bf16(Bt[n][k], At[m][k], acc[ai][bj][m][n], 0, 0, 0); __builtin_amdgcn_s_setprio(0); } while (0)
; #define PG8_WAIT_V(n) asm volatile("s_waitcnt vmcnt(" #n ")" ::: "memory")
; #define PG8_WAIT_L(n) asm volatile("s_waitcnt lgkmcnt(" #n ")" ::: "memory")
; #define PG8_BAR __builtin_amdgcn_s_barrier()
; #define PG8_SCHED __builtin_amdgcn_sched_barrier(0)
; template <class Epi, class Sched>
; __device__ __forceinline__ void gemm_phase(LAS unsigned char* lds, const Gemm g, const Sched& S, const Epi& E) {
;     ...
;             PG8_WAIT_L(8); PG8_BAR; PG8_WAIT_L(0); PG8_MMA(0, 0, At, B0); PG8_BAR; PG8_SCHED;
;             PG8_LDB(B1, 0, 1); PG8_STAGE(PG8_SB(0, 0), b2, voffB);
;             PG8_BAR; PG8_WAIT_L(0); PG8_MMA(0, 1, At, B1); PG8_BAR;
;             PG8_LDA(At, 0, 1); PG8_STAGE(PG8_SA(0, 0), a2, voffA);
;             PG8_BAR; PG8_WAIT_L(0); PG8_MMA(1, 0, At, B0); PG8_BAR; PG8_SCHED;
;             PG8_STAGE(PG8_SB(0, 1), b2 + hstepB, voffB);
;             PG8_WAIT_V(6); PG8_BAR; PG8_MMA(1, 1, At, B1); PG8_BAR;
;             PG8_LDB(B0, 1, 0); PG8_SCHED; PG8_LDA(At, 1, 0); PG8_STAGE(PG8_SA(0, 1), a2 + hstepA, voffA);
	v_mfma_f32_16x16x32_bf16 v[126:129], v[146:149], v[162:165], v[126:129]
	v_mfma_f32_16x16x32_bf16 v[126:129], v[150:153], v[166:169], v[126:129]
	v_mfma_f32_16x16x32_bf16 v[110:113], v[146:149], v[170:173], v[110:113]
	v_mfma_f32_16x16x32_bf16 v[110:113], v[150:153], v[174:177], v[110:113]
	v_mfma_f32_16x16x32_bf16 v[94:97], v[146:149], v[182:185], v[94:97]
	v_mfma_f32_16x16x32_bf16 v[94:97], v[150:153], v[186:189], v[94:97]
	v_mfma_f32_16x16x32_bf16 v[78:81], v[146:149], v[190:193], v[78:81]
	v_mfma_f32_16x16x32_bf16 v[78:81], v[150:153], v[194:197], v[78:81]
	v_mfma_f32_16x16x32_bf16 v[118:121], v[154:157], v[162:165], v[118:121]
	v_mfma_f32_16x16x32_bf16 v[118:121], v[158:161], v[166:169], v[118:121]
	v_mfma_f32_16x16x32_bf16 v[102:105], v[154:157], v[170:173], v[102:105]
	v_mfma_f32_16x16x32_bf16 v[102:105], v[158:161], v[174:177], v[102:105]
	v_mfma_f32_16x16x32_bf16 v[86:89], v[154:157], v[182:185], v[86:89]
	v_mfma_f32_16x16x32_bf16 v[86:89], v[158:161], v[186:189], v[86:89]
	v_mfma_f32_16x16x32_bf16 v[70:73], v[154:157], v[190:193], v[70:73]
	v_mfma_f32_16x16x32_bf16 v[70:73], v[158:161], v[194:197], v[70:73]
	v_mfma_f32_16x16x32_bf16 v[122:125], v[198:201], v[162:165], v[122:125]
	v_mfma_f32_16x16x32_bf16 v[122:125], v[202:205], v[166:169], v[122:125]
	v_mfma_f32_16x16x32_bf16 v[106:109], v[198:201], v[170:173], v[106:109]
	v_mfma_f32_16x16x32_bf16 v[106:109], v[202:205], v[174:177], v[106:109]
	v_mfma_f32_16x16x32_bf16 v[90:93], v[198:201], v[182:185], v[90:93]
	v_mfma_f32_16x16x32_bf16 v[90:93], v[202:205], v[186:189], v[90:93]
	v_mfma_f32_16x16x32_bf16 v[74:77], v[198:201], v[190:193], v[74:77]
	v_mfma_f32_16x16x32_bf16 v[74:77], v[202:205], v[194:197], v[74:77]
	v_mfma_f32_16x16x32_bf16 v[114:117], v[206:209], v[162:165], v[114:117]
	v_mfma_f32_16x16x32_bf16 v[114:117], v[210:213], v[166:169], v[114:117]
	v_mfma_f32_16x16x32_bf16 v[98:101], v[206:209], v[170:173], v[98:101]
	v_mfma_f32_16x16x32_bf16 v[98:101], v[210:213], v[174:177], v[98:101]
	v_mfma_f32_16x16x32_bf16 v[82:85], v[206:209], v[182:185], v[82:85]
	v_mfma_f32_16x16x32_bf16 v[82:85], v[210:213], v[186:189], v[82:85]
	v_mfma_f32_16x16x32_bf16 v[66:69], v[206:209], v[190:193], v[66:69]
	v_mfma_f32_16x16x32_bf16 v[66:69], v[210:213], v[194:197], v[66:69]
	s_barrier
	ds_read_b128 v[162:165], v145 offset:16384
	ds_read_b128 v[166:169], v145 offset:17408
	ds_read_b128 v[170:173], v145 offset:18432
	ds_read_b128 v[174:177], v145 offset:19456
	ds_read_b128 v[182:185], v145 offset:20480
	ds_read_b128 v[186:189], v145 offset:21504
	ds_read_b128 v[190:193], v145 offset:22528
	ds_read_b128 v[194:197], v145 offset:23552
	s_add_i32 s35, s35, s46
	s_mov_b32 m0, s35
	s_nop 0
	global_load_lds_dwordx4 v178, s[50:51]
	s_add_i32 m0, s35, 0x2000
	s_nop 0
	global_load_lds_dwordx4 v134, s[50:51]
	s_add_u32 s64, s50, 0x80000
	s_addc_u32 s65, s51, 0
	s_add_i32 s35, s66, s46
	s_mov_b32 m0, s35
	s_nop 0
	global_load_lds_dwordx4 v178, s[64:65]
	s_add_i32 m0, s35, 0x2000
	s_nop 0
	global_load_lds_dwordx4 v134, s[64:65]
	s_waitcnt vmcnt(4)
	s_waitcnt lgkmcnt(0)
	s_barrier
	v_mfma_f32_16x16x32_bf16 v[62:65], v[146:149], v[162:165], v[62:65]
	v_mfma_f32_16x16x32_bf16 v[62:65], v[150:153], v[166:169], v[62:65]
	v_mfma_f32_16x16x32_bf16 v[46:49], v[146:149], v[170:173], v[46:49]
	v_mfma_f32_16x16x32_bf16 v[46:49], v[150:153], v[174:177], v[46:49]
	v_mfma_f32_16x16x32_bf16 v[30:33], v[146:149], v[182:185], v[30:33]
	v_mfma_f32_16x16x32_bf16 v[30:33], v[150:153], v[186:189], v[30:33]
	v_mfma_f32_16x16x32_bf16 v[14:17], v[146:149], v[190:193], v[14:17]
	v_mfma_f32_16x16x32_bf16 v[14:17], v[150:153], v[194:197], v[14:17]
	v_mfma_f32_16x16x32_bf16 v[54:57], v[154:157], v[162:165], v[54:57]
	v_mfma_f32_16x16x32_bf16 v[54:57], v[158:161], v[166:169], v[54:57]
	v_mfma_f32_16x16x32_bf16 v[38:41], v[154:157], v[170:173], v[38:41]
	v_mfma_f32_16x16x32_bf16 v[38:41], v[158:161], v[174:177], v[38:41]
	v_mfma_f32_16x16x32_bf16 v[22:25], v[154:157], v[182:185], v[22:25]
	v_mfma_f32_16x16x32_bf16 v[22:25], v[158:161], v[186:189], v[22:25]
	v_mfma_f32_16x16x32_bf16 v[6:9], v[154:157], v[190:193], v[6:9]
	v_mfma_f32_16x16x32_bf16 v[6:9], v[158:161], v[194:197], v[6:9]
	v_mfma_f32_16x16x32_bf16 v[58:61], v[198:201], v[162:165], v[58:61]
	v_mfma_f32_16x16x32_bf16 v[58:61], v[202:205], v[166:169], v[58:61]
	v_mfma_f32_16x16x32_bf16 v[42:45], v[198:201], v[170:173], v[42:45]
	v_mfma_f32_16x16x32_bf16 v[42:45], v[202:205], v[174:177], v[42:45]
	v_mfma_f32_16x16x32_bf16 v[26:29], v[198:201], v[182:185], v[26:29]
	v_mfma_f32_16x16x32_bf16 v[26:29], v[202:205], v[186:189], v[26:29]
	v_mfma_f32_16x16x32_bf16 v[10:13], v[198:201], v[190:193], v[10:13]
	v_mfma_f32_16x16x32_bf16 v[10:13], v[202:205], v[194:197], v[10:13]
	v_mfma_f32_16x16x32_bf16 v[50:53], v[206:209], v[162:165], v[50:53]
	v_mfma_f32_16x16x32_bf16 v[50:53], v[210:213], v[166:169], v[50:53]
	v_mfma_f32_16x16x32_bf16 v[34:37], v[206:209], v[170:173], v[34:37]
	v_mfma_f32_16x16x32_bf16 v[34:37], v[210:213], v[174:177], v[34:37]
	v_mfma_f32_16x16x32_bf16 v[18:21], v[206:209], v[182:185], v[18:21]
	v_mfma_f32_16x16x32_bf16 v[18:21], v[210:213], v[186:189], v[18:21]
	v_mfma_f32_16x16x32_bf16 v[2:5], v[206:209], v[190:193], v[2:5]
	v_mfma_f32_16x16x32_bf16 v[2:5], v[210:213], v[194:197], v[2:5]
	s_add_i32 s35, 0, 0x18000
	s_barrier
; #define PG8_STAGE(bufoff, gbase, voff) do { _Pragma("unroll") for (int _i = 0; _i < 2; ++_i) \
;         __builtin_amdgcn_global_load_lds((const unsigned*)((const char*)(gbase) + (voff)[_i]), (LAS unsigned*)(lds + (bufoff) + ldsw + _i * 8192), 16, 0, 0); } while (0)
; #define PG8_LDA(dst, b, h) do { _Pragma("unroll") for (int m = 0; m < 4; ++m) _Pragma("unroll") for (int k = 0; k < 2; ++k) dst[m][k] = *(const LAS bf16x8*)(lds + PG8_SA(b, h) + aoff + m * 2048 + k * 1024); } while (0)
; #define PG8_LDB(dst, b, h) do { _Pragma("unroll") for (int n = 0; n < 2; ++n) _Pragma("unroll") for (int k = 0; k < 2; ++k) dst[n][k] = *(const LAS bf16x8*)(lds + PG8_SB(b, h) + boff + n * 2048 + k * 1024); } while (0)
; #define PG8_MMA(ai, bj, At, Bt) do { __builtin_amdgcn_s_setprio(1); _Pragma("unroll") for (int m = 0; m < 4; ++m) _Pragma("unroll") for (int n = 0; n < 2; ++n) _Pragma("unroll") for (int k = 0; k < 2; ++k) \
;         acc[ai][bj][m][n] = __builtin_amdgcn_mfma_f32_16x16x32_bf16(Bt[n][k], At[m][k], acc[ai][bj][m][n], 0, 0, 0); __builtin_amdgcn_s_setprio(0); } while (0)
; #define PG8_WAIT_V(n) asm volatile("s_waitcnt vmcnt(" #n ")" ::: "memory")
; #define PG8_WAIT_L(n) asm volatile("s_waitcnt lgkmcnt(" #n ")" ::: "memory")
; #define PG8_BAR __builtin_amdgcn_s_barrier()
; #define PG8_SCHED __builtin_amdgcn_sched_barrier(0)
; template <class Epi, class Sched>
; __device__ __forceinline__ void gemm_phase(LAS unsigned char* lds, const Gemm g, const Sched& S, const Epi& E) {
;     ...
;             PG8_LDB(B0, 1, 0); PG8_SCHED; PG8_LDA(At, 1, 0); PG8_STAGE(PG8_SA(0, 1), a2 + hstepA, voffA);
;             PG8_WAIT_L(8); PG8_BAR; PG8_WAIT_L(0); PG8_MMA(0, 0, At, B0); PG8_BAR; PG8_SCHED;
;             PG8_LDB(B1, 1, 1); PG8_STAGE(PG8_SB(1, 0), b3, voffB);
;             PG8_BAR; PG8_WAIT_L(0); PG8_MMA(0, 1, At, B1); PG8_BAR;
;             PG8_LDA(At, 1, 1); PG8_STAGE(PG8_SA(1, 0), a3, voffA);
;             PG8_BAR; PG8_WAIT_L(0); PG8_MMA(1, 0, At, B0); PG8_BAR; PG8_SCHED;
;             PG8_STAGE(PG8_SB(1, 1), b3 + hstepB, voffB);
;             PG8_WAIT_V(6); PG8_BAR; PG8_MMA(1, 1, At, B1); PG8_BAR;
;         }
	ds_read_b128 v[146:149], v240 offset:32768
	ds_read_b128 v[150:153], v240 offset:33792
	ds_read_b128 v[154:157], v240 offset:34816
	ds_read_b128 v[158:161], v240 offset:35840
	ds_read_b128 v[162:165], v145 offset:32768
	ds_read_b128 v[166:169], v145 offset:33792
	ds_read_b128 v[170:173], v145 offset:34816
	ds_read_b128 v[174:177], v145 offset:35840
	ds_read_b128 v[182:185], v145 offset:36864
	ds_read_b128 v[186:189], v145 offset:37888
	ds_read_b128 v[190:193], v145 offset:38912
	ds_read_b128 v[194:197], v145 offset:39936
	s_mov_b32 m0, s23
	s_nop 0
	global_load_lds_dwordx4 v130, s[28:29]
	s_mov_b32 m0, s25
	s_nop 0
	global_load_lds_dwordx4 v132, s[28:29]
	s_add_u32 s28, s28, 0x80000
	s_addc_u32 s29, s29, 0
	s_mov_b32 m0, s52
	s_nop 0
	global_load_lds_dwordx4 v130, s[28:29]
	s_mov_b32 m0, s53
	s_nop 0
	global_load_lds_dwordx4 v132, s[28:29]
	s_add_i32 s64, 0, 0x1c000
	ds_read_b128 v[198:201], v240 offset:49152
	ds_read_b128 v[202:205], v240 offset:50176
	ds_read_b128 v[206:209], v240 offset:51200
	ds_read_b128 v[210:213], v240 offset:52224
	s_waitcnt lgkmcnt(0)
	s_barrier
	v_mfma_f32_16x16x32_bf16 v[126:129], v[146:149], v[162:165], v[126:129]
	v_mfma_f32_16x16x32_bf16 v[126:129], v[150:153], v[166:169], v[126:129]
	v_mfma_f32_16x16x32_bf16 v[110:113], v[146:149], v[170:173], v[110:113]
	v_mfma_f32_16x16x32_bf16 v[110:113], v[150:153], v[174:177], v[110:113]
	v_mfma_f32_16x16x32_bf16 v[94:97], v[146:149], v[182:185], v[94:97]
	v_mfma_f32_16x16x32_bf16 v[94:97], v[150:153], v[186:189], v[94:97]
	v_mfma_f32_16x16x32_bf16 v[78:81], v[146:149], v[190:193], v[78:81]
	v_mfma_f32_16x16x32_bf16 v[78:81], v[150:153], v[194:197], v[78:81]
	v_mfma_f32_16x16x32_bf16 v[118:121], v[154:157], v[162:165], v[118:121]
	v_mfma_f32_16x16x32_bf16 v[118:121], v[158:161], v[166:169], v[118:121]
	v_mfma_f32_16x16x32_bf16 v[102:105], v[154:157], v[170:173], v[102:105]
	v_mfma_f32_16x16x32_bf16 v[102:105], v[158:161], v[174:177], v[102:105]
	v_mfma_f32_16x16x32_bf16 v[86:89], v[154:157], v[182:185], v[86:89]
	v_mfma_f32_16x16x32_bf16 v[86:89], v[158:161], v[186:189], v[86:89]
	v_mfma_f32_16x16x32_bf16 v[70:73], v[154:157], v[190:193], v[70:73]
	v_mfma_f32_16x16x32_bf16 v[70:73], v[158:161], v[194:197], v[70:73]
	v_mfma_f32_16x16x32_bf16 v[122:125], v[198:201], v[162:165], v[122:125]
	v_mfma_f32_16x16x32_bf16 v[122:125], v[202:205], v[166:169], v[122:125]
	v_mfma_f32_16x16x32_bf16 v[106:109], v[198:201], v[170:173], v[106:109]
	v_mfma_f32_16x16x32_bf16 v[106:109], v[202:205], v[174:177], v[106:109]
	v_mfma_f32_16x16x32_bf16 v[90:93], v[198:201], v[182:185], v[90:93]
	v_mfma_f32_16x16x32_bf16 v[90:93], v[202:205], v[186:189], v[90:93]
	v_mfma_f32_16x16x32_bf16 v[74:77], v[198:201], v[190:193], v[74:77]
	v_mfma_f32_16x16x32_bf16 v[74:77], v[202:205], v[194:197], v[74:77]
	v_mfma_f32_16x16x32_bf16 v[114:117], v[206:209], v[162:165], v[114:117]
	v_mfma_f32_16x16x32_bf16 v[114:117], v[210:213], v[166:169], v[114:117]
	v_mfma_f32_16x16x32_bf16 v[98:101], v[206:209], v[170:173], v[98:101]
	v_mfma_f32_16x16x32_bf16 v[98:101], v[210:213], v[174:177], v[98:101]
	v_mfma_f32_16x16x32_bf16 v[82:85], v[206:209], v[182:185], v[82:85]
	v_mfma_f32_16x16x32_bf16 v[82:85], v[210:213], v[186:189], v[82:85]
	v_mfma_f32_16x16x32_bf16 v[66:69], v[206:209], v[190:193], v[66:69]
	v_mfma_f32_16x16x32_bf16 v[66:69], v[210:213], v[194:197], v[66:69]
	s_barrier
	ds_read_b128 v[162:165], v145 offset:49152
	ds_read_b128 v[166:169], v145 offset:50176
	ds_read_b128 v[170:173], v145 offset:51200
	ds_read_b128 v[174:177], v145 offset:52224
	ds_read_b128 v[182:185], v145 offset:53248
	ds_read_b128 v[186:189], v145 offset:54272
	ds_read_b128 v[190:193], v145 offset:55296
	ds_read_b128 v[194:197], v145 offset:56320
	s_add_u32 s98, s50, 0x80
	s_addc_u32 s99, s51, 0
	s_add_i32 s28, s35, s46
	s_mov_b32 m0, s28
	s_nop 0
	global_load_lds_dwordx4 v178, s[98:99]
	s_add_i32 m0, s28, 0x2000
	s_nop 0
	global_load_lds_dwordx4 v134, s[98:99]
	s_add_u32 s28, s50, 0x80080
	s_addc_u32 s29, s51, 0
	s_add_i32 s35, s64, s46
	s_mov_b32 m0, s35
	s_nop 0
	global_load_lds_dwordx4 v178, s[28:29]
	s_add_i32 m0, s35, 0x2000
	s_nop 0
	global_load_lds_dwordx4 v134, s[28:29]
	s_waitcnt vmcnt(4)
	s_waitcnt lgkmcnt(0)
	s_barrier
	v_mfma_f32_16x16x32_bf16 v[62:65], v[146:149], v[162:165], v[62:65]
	v_mfma_f32_16x16x32_bf16 v[62:65], v[150:153], v[166:169], v[62:65]
	v_mfma_f32_16x16x32_bf16 v[46:49], v[146:149], v[170:173], v[46:49]
	v_mfma_f32_16x16x32_bf16 v[46:49], v[150:153], v[174:177], v[46:49]
	v_mfma_f32_16x16x32_bf16 v[30:33], v[146:149], v[182:185], v[30:33]
	v_mfma_f32_16x16x32_bf16 v[30:33], v[150:153], v[186:189], v[30:33]
	v_mfma_f32_16x16x32_bf16 v[14:17], v[146:149], v[190:193], v[14:17]
	v_mfma_f32_16x16x32_bf16 v[14:17], v[150:153], v[194:197], v[14:17]
	v_mfma_f32_16x16x32_bf16 v[54:57], v[154:157], v[162:165], v[54:57]
	v_mfma_f32_16x16x32_bf16 v[54:57], v[158:161], v[166:169], v[54:57]
	v_mfma_f32_16x16x32_bf16 v[38:41], v[154:157], v[170:173], v[38:41]
	v_mfma_f32_16x16x32_bf16 v[38:41], v[158:161], v[174:177], v[38:41]
	v_mfma_f32_16x16x32_bf16 v[22:25], v[154:157], v[182:185], v[22:25]
	v_mfma_f32_16x16x32_bf16 v[22:25], v[158:161], v[186:189], v[22:25]
	v_mfma_f32_16x16x32_bf16 v[6:9], v[154:157], v[190:193], v[6:9]
	v_mfma_f32_16x16x32_bf16 v[6:9], v[158:161], v[194:197], v[6:9]
	v_mfma_f32_16x16x32_bf16 v[58:61], v[198:201], v[162:165], v[58:61]
	v_mfma_f32_16x16x32_bf16 v[58:61], v[202:205], v[166:169], v[58:61]
	v_mfma_f32_16x16x32_bf16 v[42:45], v[198:201], v[170:173], v[42:45]
	v_mfma_f32_16x16x32_bf16 v[42:45], v[202:205], v[174:177], v[42:45]
	v_mfma_f32_16x16x32_bf16 v[26:29], v[198:201], v[182:185], v[26:29]
	v_mfma_f32_16x16x32_bf16 v[26:29], v[202:205], v[186:189], v[26:29]
	v_mfma_f32_16x16x32_bf16 v[10:13], v[198:201], v[190:193], v[10:13]
	v_mfma_f32_16x16x32_bf16 v[10:13], v[202:205], v[194:197], v[10:13]
	v_mfma_f32_16x16x32_bf16 v[50:53], v[206:209], v[162:165], v[50:53]
	v_mfma_f32_16x16x32_bf16 v[50:53], v[210:213], v[166:169], v[50:53]
	v_mfma_f32_16x16x32_bf16 v[34:37], v[206:209], v[170:173], v[34:37]
	v_mfma_f32_16x16x32_bf16 v[34:37], v[210:213], v[174:177], v[34:37]
	v_mfma_f32_16x16x32_bf16 v[18:21], v[206:209], v[182:185], v[18:21]
	v_mfma_f32_16x16x32_bf16 v[18:21], v[210:213], v[186:189], v[18:21]
	v_mfma_f32_16x16x32_bf16 v[2:5], v[206:209], v[190:193], v[2:5]
	v_mfma_f32_16x16x32_bf16 v[2:5], v[210:213], v[194:197], v[2:5]
	s_add_i32 s63, s63, 2
	s_add_u32 s26, s26, 0x100
	s_addc_u32 s27, s27, 0
	s_add_u32 s59, s59, 0x100
	s_addc_u32 s62, s62, 0
	s_cmp_gt_u32 s63, 29
	s_barrier
; __device__ __forceinline__ unsigned cvt_pk_bf16(float lo, float hi) { const f32x2_t v = {lo, hi}; return __builtin_bit_cast(unsigned, __builtin_convertvector(v, bf16x2_t)); }
;     __device__ __forceinline__ void operator()(f32x4 (&acc)[2][2][4][2], const Unit& u, int wr, int wc, int fr, int fq) const {
;         const int row0 = u.pm * BM + wr * 64 + fr, col0 = u.pn * HALF + wc * 32 + 8 * fq;
; #pragma unroll
;         for (int ai = 0; ai < 2; ++ai)
; #pragma unroll
;             for (int m = 0; m < 4; ++m) { bf16_t* rowp = O + (size_t)(row0 + ai * HALF + m * 16) * FF + col0;
;                 float h[8];
; #pragma unroll
;                 for (int n = 0; n < 2; ++n)
; #pragma unroll
;                     for (int e = 0; e < 4; ++e) { const float g = acc[ai][0][m][n][e], up = acc[ai][1][m][n][e]; h[n * 4 + e] = g * __builtin_amdgcn_rcpf(1.0f + __builtin_amdgcn_exp2f(-1.4426950408889634f * g)) * up; }
;                 u32x4 w; w.x = cvt_pk_bf16(h[0], h[1]); w.y = cvt_pk_bf16(h[2], h[3]); w.z = cvt_pk_bf16(h[4], h[5]); w.w = cvt_pk_bf16(h[6], h[7]);
;                 __builtin_nontemporal_store(w, (u32x4*)rowp); }
	s_cbranch_scc0 .LBB0_1140
	v_mul_f32_e32 v1, 0xbfb8aa3b, v126
	v_exp_f32_e32 v1, v1
	v_lshl_or_b32 v148, s22, 7, v144
	v_lshl_add_u32 v146, s24, 8, v142
	v_ashrrev_i32_e32 v149, 31, v148
	v_add_f32_e32 v1, 1.0, v1
	v_rcp_f32_e32 v152, v1
	v_mul_f32_e32 v1, 0xbfb8aa3b, v127
	v_exp_f32_e32 v1, v1
	v_mov_b64_e32 v[140:141], s[8:9]
	v_mad_i64_i32 v[150:151], s[26:27], v146, s61, v[140:141]
	v_add_f32_e32 v1, 1.0, v1
	v_rcp_f32_e32 v153, v1
	v_mul_f32_e32 v1, 0xbfb8aa3b, v128
	v_exp_f32_e32 v1, v1
	s_and_b64 vcc, exec, s[6:7]
	v_pk_mul_f32 v[126:127], v[126:127], v[152:153]
	s_mov_b32 s22, s10
	v_add_f32_e32 v1, 1.0, v1
	v_pk_mul_f32 v[122:123], v[126:127], v[122:123]
	v_rcp_f32_e32 v126, v1
	v_mul_f32_e32 v1, 0xbfb8aa3b, v129
	v_exp_f32_e32 v1, v1
	s_mov_b32 s24, s12
	s_mov_b64 s[50:51], s[20:21]
	v_add_f32_e32 v1, 1.0, v1
	v_rcp_f32_e32 v127, v1
	v_mul_f32_e32 v1, 0xbfb8aa3b, v118
	v_exp_f32_e32 v1, v1
	v_pk_mul_f32 v[126:127], v[128:129], v[126:127]
	s_nop 0
	v_pk_mul_f32 v[124:125], v[126:127], v[124:125]
	v_add_f32_e32 v1, 1.0, v1
	v_rcp_f32_e32 v126, v1
	v_mul_f32_e32 v1, 0xbfb8aa3b, v119
	v_exp_f32_e32 v1, v1
	s_nop 0
	v_add_f32_e32 v1, 1.0, v1
	v_rcp_f32_e32 v127, v1
	v_mul_f32_e32 v1, 0xbfb8aa3b, v120
	v_exp_f32_e32 v1, v1
	v_pk_mul_f32 v[118:119], v[118:119], v[126:127]
	s_nop 0
	v_pk_mul_f32 v[118:119], v[118:119], v[114:115]
	v_add_f32_e32 v1, 1.0, v1
	v_rcp_f32_e32 v114, v1
	v_mul_f32_e32 v1, 0xbfb8aa3b, v121
	v_exp_f32_e32 v1, v1
	v_cvt_pk_bf16_f32 v118, v118, v119
	v_add_f32_e32 v1, 1.0, v1
	v_rcp_f32_e32 v115, v1
	v_or_b32_e32 v1, 16, v146
	v_pk_mul_f32 v[114:115], v[120:121], v[114:115]
	s_nop 0
	v_pk_mul_f32 v[120:121], v[114:115], v[116:117]
	v_lshlrev_b64 v[114:115], 1, v[148:149]
	v_lshl_add_u64 v[126:127], v[150:151], 0, v[114:115]
	v_cvt_pk_bf16_f32 v116, v122, v123
	v_cvt_pk_bf16_f32 v117, v124, v125
	v_cvt_pk_bf16_f32 v119, v120, v121
	global_store_dwordx4 v[126:127], v[116:119], off nt
	s_nop 1
	v_mad_i64_i32 v[116:117], s[26:27], v1, s61, v[140:141]
	v_mul_f32_e32 v1, 0xbfb8aa3b, v110
	v_exp_f32_e32 v1, v1
	s_nop 0
	v_add_f32_e32 v1, 1.0, v1
	v_rcp_f32_e32 v118, v1
	v_mul_f32_e32 v1, 0xbfb8aa3b, v111
	v_exp_f32_e32 v1, v1
	s_nop 0
	v_add_f32_e32 v1, 1.0, v1
	v_rcp_f32_e32 v119, v1
	v_mul_f32_e32 v1, 0xbfb8aa3b, v112
	v_exp_f32_e32 v1, v1
	v_pk_mul_f32 v[110:111], v[110:111], v[118:119]
	s_nop 0
	v_pk_mul_f32 v[106:107], v[110:111], v[106:107]
	v_add_f32_e32 v1, 1.0, v1
	v_rcp_f32_e32 v110, v1
	v_mul_f32_e32 v1, 0xbfb8aa3b, v113
	v_exp_f32_e32 v1, v1
	s_nop 0
	v_add_f32_e32 v1, 1.0, v1
	v_rcp_f32_e32 v111, v1
	v_mul_f32_e32 v1, 0xbfb8aa3b, v102
	v_exp_f32_e32 v1, v1
	v_pk_mul_f32 v[110:111], v[112:113], v[110:111]
	s_nop 0
	v_pk_mul_f32 v[108:109], v[110:111], v[108:109]
	v_add_f32_e32 v1, 1.0, v1
	v_rcp_f32_e32 v110, v1
	v_mul_f32_e32 v1, 0xbfb8aa3b, v103
	v_exp_f32_e32 v1, v1
	s_nop 0
	v_add_f32_e32 v1, 1.0, v1
	v_rcp_f32_e32 v111, v1
	v_mul_f32_e32 v1, 0xbfb8aa3b, v104
	v_exp_f32_e32 v1, v1
	v_pk_mul_f32 v[102:103], v[102:103], v[110:111]
	s_nop 0
	v_pk_mul_f32 v[102:103], v[102:103], v[98:99]
	v_add_f32_e32 v1, 1.0, v1
	v_rcp_f32_e32 v98, v1
	v_mul_f32_e32 v1, 0xbfb8aa3b, v105
	v_exp_f32_e32 v1, v1
	v_lshl_add_u64 v[110:111], v[116:117], 0, v[114:115]
	v_add_f32_e32 v1, 1.0, v1
	v_rcp_f32_e32 v99, v1
	v_or_b32_e32 v1, 32, v146
	v_pk_mul_f32 v[98:99], v[104:105], v[98:99]
	s_nop 0
	v_pk_mul_f32 v[104:105], v[98:99], v[100:101]
	v_cvt_pk_bf16_f32 v98, v106, v107
	v_cvt_pk_bf16_f32 v99, v108, v109
	v_cvt_pk_bf16_f32 v100, v102, v103
	v_cvt_pk_bf16_f32 v101, v104, v105
	global_store_dwordx4 v[110:111], v[98:101], off nt
	s_nop 1
	v_mad_i64_i32 v[98:99], s[26:27], v1, s61, v[140:141]
	v_mul_f32_e32 v1, 0xbfb8aa3b, v94
	v_exp_f32_e32 v1, v1
	s_nop 0
	v_add_f32_e32 v1, 1.0, v1
	v_rcp_f32_e32 v100, v1
	v_mul_f32_e32 v1, 0xbfb8aa3b, v95
	v_exp_f32_e32 v1, v1
	s_nop 0
	v_add_f32_e32 v1, 1.0, v1
	v_rcp_f32_e32 v101, v1
	v_mul_f32_e32 v1, 0xbfb8aa3b, v96
	v_exp_f32_e32 v1, v1
	v_pk_mul_f32 v[94:95], v[94:95], v[100:101]
	s_nop 0
	v_pk_mul_f32 v[90:91], v[94:95], v[90:91]
	v_add_f32_e32 v1, 1.0, v1
	v_rcp_f32_e32 v94, v1
	v_mul_f32_e32 v1, 0xbfb8aa3b, v97
	v_exp_f32_e32 v1, v1
	s_nop 0
	v_add_f32_e32 v1, 1.0, v1
	v_rcp_f32_e32 v95, v1
	v_mul_f32_e32 v1, 0xbfb8aa3b, v86
	v_exp_f32_e32 v1, v1
	v_pk_mul_f32 v[94:95], v[96:97], v[94:95]
	s_nop 0
	v_pk_mul_f32 v[92:93], v[94:95], v[92:93]
	v_add_f32_e32 v1, 1.0, v1
	v_rcp_f32_e32 v94, v1
	v_mul_f32_e32 v1, 0xbfb8aa3b, v87
	v_exp_f32_e32 v1, v1
	s_nop 0
	v_add_f32_e32 v1, 1.0, v1
	v_rcp_f32_e32 v95, v1
	v_mul_f32_e32 v1, 0xbfb8aa3b, v88
	v_exp_f32_e32 v1, v1
	v_pk_mul_f32 v[86:87], v[86:87], v[94:95]
	s_nop 0
	v_pk_mul_f32 v[86:87], v[86:87], v[82:83]
	v_add_f32_e32 v1, 1.0, v1
	v_rcp_f32_e32 v82, v1
	v_mul_f32_e32 v1, 0xbfb8aa3b, v89
	v_exp_f32_e32 v1, v1
	v_lshl_add_u64 v[94:95], v[98:99], 0, v[114:115]
	v_add_f32_e32 v1, 1.0, v1
	v_rcp_f32_e32 v83, v1
	v_or_b32_e32 v1, 48, v146
	v_pk_mul_f32 v[82:83], v[88:89], v[82:83]
	s_nop 0
	v_pk_mul_f32 v[88:89], v[82:83], v[84:85]
	v_cvt_pk_bf16_f32 v82, v90, v91
	v_cvt_pk_bf16_f32 v83, v92, v93
	v_cvt_pk_bf16_f32 v84, v86, v87
	v_cvt_pk_bf16_f32 v85, v88, v89
	global_store_dwordx4 v[94:95], v[82:85], off nt
	s_nop 1
	v_mad_i64_i32 v[82:83], s[26:27], v1, s61, v[140:141]
	v_mul_f32_e32 v1, 0xbfb8aa3b, v78
	v_exp_f32_e32 v1, v1
	s_nop 0
	v_add_f32_e32 v1, 1.0, v1
	v_rcp_f32_e32 v84, v1
	v_mul_f32_e32 v1, 0xbfb8aa3b, v79
	v_exp_f32_e32 v1, v1
	s_nop 0
	v_add_f32_e32 v1, 1.0, v1
	v_rcp_f32_e32 v85, v1
	v_mul_f32_e32 v1, 0xbfb8aa3b, v80
	v_exp_f32_e32 v1, v1
	v_pk_mul_f32 v[78:79], v[78:79], v[84:85]
	s_nop 0
	v_pk_mul_f32 v[74:75], v[78:79], v[74:75]
; __device__ __forceinline__ unsigned cvt_pk_bf16(float lo, float hi) { const f32x2_t v = {lo, hi}; return __builtin_bit_cast(unsigned, __builtin_convertvector(v, bf16x2_t)); }
;     __device__ __forceinline__ void operator()(f32x4 (&acc)[2][2][4][2], const Unit& u, int wr, int wc, int fr, int fq) const {
;     ...
;         for (int ai = 0; ai < 2; ++ai)
; #pragma unroll
;             for (int m = 0; m < 4; ++m) { bf16_t* rowp = O + (size_t)(row0 + ai * HALF + m * 16) * FF + col0;
;                 float h[8];
; #pragma unroll
;                 for (int n = 0; n < 2; ++n)
; #pragma unroll
;                     for (int e = 0; e < 4; ++e) { const float g = acc[ai][0][m][n][e], up = acc[ai][1][m][n][e]; h[n * 4 + e] = g * __builtin_amdgcn_rcpf(1.0f + __builtin_amdgcn_exp2f(-1.4426950408889634f * g)) * up; }
;                 u32x4 w; w.x = cvt_pk_bf16(h[0], h[1]); w.y = cvt_pk_bf16(h[2], h[3]); w.z = cvt_pk_bf16(h[4], h[5]); w.w = cvt_pk_bf16(h[6], h[7]);
;                 __builtin_nontemporal_store(w, (u32x4*)rowp); }
	v_add_f32_e32 v1, 1.0, v1
	v_rcp_f32_e32 v78, v1
	v_mul_f32_e32 v1, 0xbfb8aa3b, v81
	v_exp_f32_e32 v1, v1
	s_nop 0
	v_add_f32_e32 v1, 1.0, v1
	v_rcp_f32_e32 v79, v1
	v_mul_f32_e32 v1, 0xbfb8aa3b, v70
	v_exp_f32_e32 v1, v1
	v_pk_mul_f32 v[78:79], v[80:81], v[78:79]
	s_nop 0
	v_pk_mul_f32 v[76:77], v[78:79], v[76:77]
	v_add_f32_e32 v1, 1.0, v1
	v_rcp_f32_e32 v78, v1
	v_mul_f32_e32 v1, 0xbfb8aa3b, v71
	v_exp_f32_e32 v1, v1
	s_nop 0
	v_add_f32_e32 v1, 1.0, v1
	v_rcp_f32_e32 v79, v1
	v_mul_f32_e32 v1, 0xbfb8aa3b, v72
	v_exp_f32_e32 v1, v1
	v_pk_mul_f32 v[70:71], v[70:71], v[78:79]
	s_nop 0
	v_pk_mul_f32 v[70:71], v[70:71], v[66:67]
	v_add_f32_e32 v1, 1.0, v1
	v_rcp_f32_e32 v66, v1
	v_mul_f32_e32 v1, 0xbfb8aa3b, v73
	v_exp_f32_e32 v1, v1
	v_lshl_add_u64 v[78:79], v[82:83], 0, v[114:115]
	v_add_f32_e32 v1, 1.0, v1
	v_rcp_f32_e32 v67, v1
	v_add_u32_e32 v1, 0x80, v146
	v_pk_mul_f32 v[66:67], v[72:73], v[66:67]
	s_nop 0
	v_pk_mul_f32 v[72:73], v[66:67], v[68:69]
	v_cvt_pk_bf16_f32 v66, v74, v75
	v_cvt_pk_bf16_f32 v67, v76, v77
	v_cvt_pk_bf16_f32 v68, v70, v71
	v_cvt_pk_bf16_f32 v69, v72, v73
	global_store_dwordx4 v[78:79], v[66:69], off nt
	s_nop 1
	v_mad_i64_i32 v[66:67], s[26:27], v1, s61, v[140:141]
	v_mul_f32_e32 v1, 0xbfb8aa3b, v62
	v_exp_f32_e32 v1, v1
	s_nop 0
	v_add_f32_e32 v1, 1.0, v1
	v_rcp_f32_e32 v68, v1
	v_mul_f32_e32 v1, 0xbfb8aa3b, v63
	v_exp_f32_e32 v1, v1
	s_nop 0
	v_add_f32_e32 v1, 1.0, v1
	v_rcp_f32_e32 v69, v1
	v_mul_f32_e32 v1, 0xbfb8aa3b, v64
	v_exp_f32_e32 v1, v1
	v_pk_mul_f32 v[62:63], v[62:63], v[68:69]
	s_nop 0
	v_pk_mul_f32 v[58:59], v[62:63], v[58:59]
	v_add_f32_e32 v1, 1.0, v1
	v_rcp_f32_e32 v62, v1
	v_mul_f32_e32 v1, 0xbfb8aa3b, v65
	v_exp_f32_e32 v1, v1
	s_nop 0
	v_add_f32_e32 v1, 1.0, v1
	v_rcp_f32_e32 v63, v1
	v_mul_f32_e32 v1, 0xbfb8aa3b, v54
	v_exp_f32_e32 v1, v1
	v_pk_mul_f32 v[62:63], v[64:65], v[62:63]
	s_nop 0
	v_pk_mul_f32 v[60:61], v[62:63], v[60:61]
	v_add_f32_e32 v1, 1.0, v1
	v_rcp_f32_e32 v62, v1
	v_mul_f32_e32 v1, 0xbfb8aa3b, v55
	v_exp_f32_e32 v1, v1
	s_nop 0
	v_add_f32_e32 v1, 1.0, v1
	v_rcp_f32_e32 v63, v1
	v_mul_f32_e32 v1, 0xbfb8aa3b, v56
	v_exp_f32_e32 v1, v1
	v_pk_mul_f32 v[54:55], v[54:55], v[62:63]
	s_nop 0
	v_pk_mul_f32 v[54:55], v[54:55], v[50:51]
	v_add_f32_e32 v1, 1.0, v1
	v_rcp_f32_e32 v50, v1
	v_mul_f32_e32 v1, 0xbfb8aa3b, v57
	v_exp_f32_e32 v1, v1
	v_lshl_add_u64 v[62:63], v[66:67], 0, v[114:115]
	v_add_f32_e32 v1, 1.0, v1
	v_rcp_f32_e32 v51, v1
	v_add_u32_e32 v1, 0x90, v146
	v_pk_mul_f32 v[50:51], v[56:57], v[50:51]
	s_nop 0
	v_pk_mul_f32 v[56:57], v[50:51], v[52:53]
	v_cvt_pk_bf16_f32 v50, v58, v59
	v_cvt_pk_bf16_f32 v51, v60, v61
	v_cvt_pk_bf16_f32 v52, v54, v55
	v_cvt_pk_bf16_f32 v53, v56, v57
	global_store_dwordx4 v[62:63], v[50:53], off nt
	s_nop 1
	v_mad_i64_i32 v[50:51], s[26:27], v1, s61, v[140:141]
	v_mul_f32_e32 v1, 0xbfb8aa3b, v46
	v_exp_f32_e32 v1, v1
	s_nop 0
	v_add_f32_e32 v1, 1.0, v1
	v_rcp_f32_e32 v52, v1
	v_mul_f32_e32 v1, 0xbfb8aa3b, v47
	v_exp_f32_e32 v1, v1
	s_nop 0
	v_add_f32_e32 v1, 1.0, v1
	v_rcp_f32_e32 v53, v1
	v_mul_f32_e32 v1, 0xbfb8aa3b, v48
	v_exp_f32_e32 v1, v1
	v_pk_mul_f32 v[46:47], v[46:47], v[52:53]
	s_nop 0
	v_pk_mul_f32 v[42:43], v[46:47], v[42:43]
	v_add_f32_e32 v1, 1.0, v1
	v_rcp_f32_e32 v46, v1
	v_mul_f32_e32 v1, 0xbfb8aa3b, v49
	v_exp_f32_e32 v1, v1
	s_nop 0
	v_add_f32_e32 v1, 1.0, v1
	v_rcp_f32_e32 v47, v1
	v_mul_f32_e32 v1, 0xbfb8aa3b, v38
	v_exp_f32_e32 v1, v1
	v_pk_mul_f32 v[46:47], v[48:49], v[46:47]
	s_nop 0
	v_pk_mul_f32 v[44:45], v[46:47], v[44:45]
	v_add_f32_e32 v1, 1.0, v1
	v_rcp_f32_e32 v46, v1
	v_mul_f32_e32 v1, 0xbfb8aa3b, v39
	v_exp_f32_e32 v1, v1
	s_nop 0
	v_add_f32_e32 v1, 1.0, v1
	v_rcp_f32_e32 v47, v1
	v_mul_f32_e32 v1, 0xbfb8aa3b, v40
	v_exp_f32_e32 v1, v1
	v_pk_mul_f32 v[38:39], v[38:39], v[46:47]
	s_nop 0
; __device__ __forceinline__ unsigned cvt_pk_bf16(float lo, float hi) { const f32x2_t v = {lo, hi}; return __builtin_bit_cast(unsigned, __builtin_convertvector(v, bf16x2_t)); }
; #define PG8_WAIT_V(n) asm volatile("s_waitcnt vmcnt(" #n ")" ::: "memory")
; #define PG8_BAR __builtin_amdgcn_s_barrier()
;     __device__ __forceinline__ void operator()(f32x4 (&acc)[2][2][4][2], const Unit& u, int wr, int wc, int fr, int fq) const {
;     ...
;         for (int ai = 0; ai < 2; ++ai)
; #pragma unroll
;             for (int m = 0; m < 4; ++m) { bf16_t* rowp = O + (size_t)(row0 + ai * HALF + m * 16) * FF + col0;
;                 float h[8];
; #pragma unroll
;                 for (int n = 0; n < 2; ++n)
; #pragma unroll
;                     for (int e = 0; e < 4; ++e) { const float g = acc[ai][0][m][n][e], up = acc[ai][1][m][n][e]; h[n * 4 + e] = g * __builtin_amdgcn_rcpf(1.0f + __builtin_amdgcn_exp2f(-1.4426950408889634f * g)) * up; }
;                 u32x4 w; w.x = cvt_pk_bf16(h[0], h[1]); w.y = cvt_pk_bf16(h[2], h[3]); w.z = cvt_pk_bf16(h[4], h[5]); w.w = cvt_pk_bf16(h[6], h[7]);
;                 __builtin_nontemporal_store(w, (u32x4*)rowp); }
; template <class Epi, class Sched>
; __device__ __forceinline__ void gemm_phase(LAS unsigned char* lds, const Gemm g, const Sched& S, const Epi& E) {
;     ...
;     PG8_WAIT_V(0);
;     if (wr == 0) PG8_BAR;
;     PG8_BAR;
	v_pk_mul_f32 v[38:39], v[38:39], v[34:35]
	v_add_f32_e32 v1, 1.0, v1
	v_rcp_f32_e32 v34, v1
	v_mul_f32_e32 v1, 0xbfb8aa3b, v41
	v_exp_f32_e32 v1, v1
	v_lshl_add_u64 v[46:47], v[50:51], 0, v[114:115]
	v_add_f32_e32 v1, 1.0, v1
	v_rcp_f32_e32 v35, v1
	v_add_u32_e32 v1, 0xa0, v146
	v_pk_mul_f32 v[34:35], v[40:41], v[34:35]
	s_nop 0
	v_pk_mul_f32 v[40:41], v[34:35], v[36:37]
	v_cvt_pk_bf16_f32 v34, v42, v43
	v_cvt_pk_bf16_f32 v35, v44, v45
	v_cvt_pk_bf16_f32 v36, v38, v39
	v_cvt_pk_bf16_f32 v37, v40, v41
	global_store_dwordx4 v[46:47], v[34:37], off nt
	s_nop 1
	v_mad_i64_i32 v[34:35], s[26:27], v1, s61, v[140:141]
	v_mul_f32_e32 v1, 0xbfb8aa3b, v30
	v_exp_f32_e32 v1, v1
	s_nop 0
	v_add_f32_e32 v1, 1.0, v1
	v_rcp_f32_e32 v36, v1
	v_mul_f32_e32 v1, 0xbfb8aa3b, v31
	v_exp_f32_e32 v1, v1
	s_nop 0
	v_add_f32_e32 v1, 1.0, v1
	v_rcp_f32_e32 v37, v1
	v_mul_f32_e32 v1, 0xbfb8aa3b, v32
	v_exp_f32_e32 v1, v1
	v_pk_mul_f32 v[30:31], v[30:31], v[36:37]
	s_nop 0
	v_pk_mul_f32 v[26:27], v[30:31], v[26:27]
	v_add_f32_e32 v1, 1.0, v1
	v_rcp_f32_e32 v30, v1
	v_mul_f32_e32 v1, 0xbfb8aa3b, v33
	v_exp_f32_e32 v1, v1
	s_nop 0
	v_add_f32_e32 v1, 1.0, v1
	v_rcp_f32_e32 v31, v1
	v_mul_f32_e32 v1, 0xbfb8aa3b, v22
	v_exp_f32_e32 v1, v1
	v_pk_mul_f32 v[30:31], v[32:33], v[30:31]
	s_nop 0
	v_pk_mul_f32 v[28:29], v[30:31], v[28:29]
	v_add_f32_e32 v1, 1.0, v1
	v_rcp_f32_e32 v30, v1
	v_mul_f32_e32 v1, 0xbfb8aa3b, v23
	v_exp_f32_e32 v1, v1
	s_nop 0
	v_add_f32_e32 v1, 1.0, v1
	v_rcp_f32_e32 v31, v1
	v_mul_f32_e32 v1, 0xbfb8aa3b, v24
	v_exp_f32_e32 v1, v1
	v_pk_mul_f32 v[22:23], v[22:23], v[30:31]
	s_nop 0
	v_pk_mul_f32 v[22:23], v[22:23], v[18:19]
	v_add_f32_e32 v1, 1.0, v1
	v_rcp_f32_e32 v18, v1
	v_mul_f32_e32 v1, 0xbfb8aa3b, v25
	v_exp_f32_e32 v1, v1
	v_lshl_add_u64 v[30:31], v[34:35], 0, v[114:115]
	v_add_f32_e32 v1, 1.0, v1
	v_rcp_f32_e32 v19, v1
	v_add_u32_e32 v1, 0xb0, v146
	v_pk_mul_f32 v[18:19], v[24:25], v[18:19]
	s_nop 0
	v_pk_mul_f32 v[24:25], v[18:19], v[20:21]
	v_cvt_pk_bf16_f32 v18, v26, v27
	v_cvt_pk_bf16_f32 v19, v28, v29
	v_cvt_pk_bf16_f32 v20, v22, v23
	v_cvt_pk_bf16_f32 v21, v24, v25
	global_store_dwordx4 v[30:31], v[18:21], off nt
	s_nop 1
	v_mad_i64_i32 v[18:19], s[26:27], v1, s61, v[140:141]
	v_mul_f32_e32 v1, 0xbfb8aa3b, v14
	v_exp_f32_e32 v1, v1
	s_mov_b64 s[26:27], s[16:17]
	v_add_f32_e32 v1, 1.0, v1
	v_rcp_f32_e32 v20, v1
	v_mul_f32_e32 v1, 0xbfb8aa3b, v15
	v_exp_f32_e32 v1, v1
	s_nop 0
	v_add_f32_e32 v1, 1.0, v1
	v_rcp_f32_e32 v21, v1
	v_mul_f32_e32 v1, 0xbfb8aa3b, v16
	v_exp_f32_e32 v1, v1
	v_pk_mul_f32 v[14:15], v[14:15], v[20:21]
	s_nop 0
	v_pk_mul_f32 v[10:11], v[14:15], v[10:11]
	v_add_f32_e32 v1, 1.0, v1
	v_rcp_f32_e32 v14, v1
	v_mul_f32_e32 v1, 0xbfb8aa3b, v17
	v_exp_f32_e32 v1, v1
	s_nop 0
	v_add_f32_e32 v1, 1.0, v1
	v_rcp_f32_e32 v15, v1
	v_mul_f32_e32 v1, 0xbfb8aa3b, v6
	v_exp_f32_e32 v1, v1
	v_pk_mul_f32 v[14:15], v[16:17], v[14:15]
	s_nop 0
	v_pk_mul_f32 v[12:13], v[14:15], v[12:13]
	v_add_f32_e32 v1, 1.0, v1
	v_rcp_f32_e32 v14, v1
	v_mul_f32_e32 v1, 0xbfb8aa3b, v7
	v_exp_f32_e32 v1, v1
	s_nop 0
	v_add_f32_e32 v1, 1.0, v1
	v_rcp_f32_e32 v15, v1
	v_mul_f32_e32 v1, 0xbfb8aa3b, v8
	v_exp_f32_e32 v1, v1
	v_pk_mul_f32 v[6:7], v[6:7], v[14:15]
	s_nop 0
	v_pk_mul_f32 v[6:7], v[6:7], v[2:3]
	v_add_f32_e32 v1, 1.0, v1
	v_rcp_f32_e32 v2, v1
	v_mul_f32_e32 v1, 0xbfb8aa3b, v9
	v_exp_f32_e32 v1, v1
	v_lshl_add_u64 v[14:15], v[18:19], 0, v[114:115]
	v_add_f32_e32 v1, 1.0, v1
	v_rcp_f32_e32 v3, v1
	s_nop 0
	v_pk_mul_f32 v[2:3], v[8:9], v[2:3]
	s_nop 0
	v_pk_mul_f32 v[8:9], v[2:3], v[4:5]
	v_cvt_pk_bf16_f32 v2, v10, v11
	v_cvt_pk_bf16_f32 v3, v12, v13
	v_cvt_pk_bf16_f32 v4, v6, v7
	v_cvt_pk_bf16_f32 v5, v8, v9
	global_store_dwordx4 v[14:15], v[2:5], off nt
	s_cbranch_vccz .LBB0_1136
	s_waitcnt vmcnt(0)
	s_cmpk_gt_u32 s1, 0xff
	s_cbranch_scc1 .LBB0_1144
	s_barrier

; #define PG8_STAGE(bufoff, gbase, voff) do { _Pragma("unroll") for (int _i = 0; _i < 2; ++_i) \
;         __builtin_amdgcn_global_load_lds((const unsigned*)((const char*)(gbase) + (voff)[_i]), (LAS unsigned*)(lds + (bufoff) + ldsw + _i * 8192), 16, 0, 0); } while (0)
; #define PG8_LDA(dst, b, h) do { _Pragma("unroll") for (int m = 0; m < 4; ++m) _Pragma("unroll") for (int k = 0; k < 2; ++k) dst[m][k] = *(const LAS bf16x8*)(lds + PG8_SA(b, h) + aoff + m * 2048 + k * 1024); } while (0)
; #define PG8_LDB(dst, b, h) do { _Pragma("unroll") for (int n = 0; n < 2; ++n) _Pragma("unroll") for (int k = 0; k < 2; ++k) dst[n][k] = *(const LAS bf16x8*)(lds + PG8_SB(b, h) + boff + n * 2048 + k * 1024); } while (0)
; #define PG8_SCHED __builtin_amdgcn_sched_barrier(0)
; template <class Epi, class Sched>
; __device__ __forceinline__ void gemm_phase(LAS unsigned char* lds, const Gemm g, const Sched& S, const Epi& E) {
;     ...
;         const int ntu = cur.nt ? cur.nt : nt;
;         for (int t = 0; t < ntu; t += 2) {
;             const bool last = (t == ntu - 2);
;             const char* a1 = cA + (size_t)(t + 1) * kstep;
;             const char* a2 = last ? nA : cA + (size_t)(t + 2) * kstep; const char* b2 = last ? nB : cB + (size_t)(t + 2) * kstep;
;             const char* a3 = a2 + kstep; const char* b3 = b2 + kstep;
;             if (last && has_next) S.a_ready(nxt);
;             PG8_LDB(B0, 0, 0); PG8_SCHED; PG8_LDA(At, 0, 0); PG8_STAGE(PG8_SA(1, 1), a1 + hstepA, voffA);
;     ...
;         if (!E.keep(cur)) {
; #pragma unroll
;             for (int a = 0; a < 2; ++a)
; #pragma unroll
;                 for (int b = 0; b < 2; ++b)
; #pragma unroll
;                     for (int m = 0; m < 4; ++m)
; #pragma unroll
;                         for (int n = 0; n < 2; ++n) acc[a][b][m][n] = (f32x4){0.f, 0.f, 0.f, 0.f};
.LBB0_1236:
	s_cmp_lg_u32 s26, 0
	s_cselect_b64 s[20:21], -1, 0
	s_and_b64 s[28:29], s[20:21], exec
	s_cselect_b32 s68, s26, 0x58
	s_cmp_lt_i32 s68, 1
	s_cbranch_scc1 .LBB0_1240
	s_add_i32 s69, s68, -2
	s_add_u32 s70, s24, 0x100
	v_mov_b32_e32 v2, 0
	s_addc_u32 s71, s25, 0
	s_mov_b32 s26, 0
	v_mov_b32_e32 v3, v2
	v_mov_b32_e32 v4, v2
	v_mov_b32_e32 v5, v2
	v_mov_b32_e32 v6, v2
	v_mov_b32_e32 v7, v2
	v_mov_b32_e32 v8, v2
	v_mov_b32_e32 v9, v2
	v_mov_b32_e32 v18, v2
	v_mov_b32_e32 v19, v2
	v_mov_b32_e32 v20, v2
	v_mov_b32_e32 v21, v2
	v_mov_b32_e32 v22, v2
	v_mov_b32_e32 v23, v2
	v_mov_b32_e32 v24, v2
	v_mov_b32_e32 v25, v2
	v_mov_b32_e32 v34, v2
	v_mov_b32_e32 v35, v2
	v_mov_b32_e32 v36, v2
	v_mov_b32_e32 v37, v2
	v_mov_b32_e32 v38, v2
	v_mov_b32_e32 v39, v2
	v_mov_b32_e32 v40, v2
	v_mov_b32_e32 v41, v2
	v_mov_b32_e32 v50, v2
	v_mov_b32_e32 v51, v2
	v_mov_b32_e32 v52, v2
	v_mov_b32_e32 v53, v2
	v_mov_b32_e32 v54, v2
	v_mov_b32_e32 v55, v2
	v_mov_b32_e32 v56, v2
	v_mov_b32_e32 v57, v2
	v_mov_b32_e32 v10, v2
	v_mov_b32_e32 v11, v2
	v_mov_b32_e32 v12, v2
	v_mov_b32_e32 v13, v2
	v_mov_b32_e32 v14, v2
	v_mov_b32_e32 v15, v2
	v_mov_b32_e32 v16, v2
	v_mov_b32_e32 v17, v2
	v_mov_b32_e32 v26, v2
	v_mov_b32_e32 v27, v2
	v_mov_b32_e32 v28, v2
	v_mov_b32_e32 v29, v2
	v_mov_b32_e32 v30, v2
	v_mov_b32_e32 v31, v2
	v_mov_b32_e32 v32, v2
	v_mov_b32_e32 v33, v2
	v_mov_b32_e32 v42, v2
	v_mov_b32_e32 v43, v2
	v_mov_b32_e32 v44, v2
	v_mov_b32_e32 v45, v2
	v_mov_b32_e32 v46, v2
	v_mov_b32_e32 v47, v2
	v_mov_b32_e32 v48, v2
	v_mov_b32_e32 v49, v2
	v_mov_b32_e32 v58, v2
	v_mov_b32_e32 v59, v2
	v_mov_b32_e32 v60, v2
	v_mov_b32_e32 v61, v2
	v_mov_b32_e32 v62, v2
	v_mov_b32_e32 v63, v2
	v_mov_b32_e32 v64, v2
	v_mov_b32_e32 v65, v2
	v_mov_b32_e32 v66, v2
	v_mov_b32_e32 v67, v2
	v_mov_b32_e32 v68, v2
	v_mov_b32_e32 v69, v2
	v_mov_b32_e32 v70, v2
	v_mov_b32_e32 v71, v2
	v_mov_b32_e32 v72, v2
	v_mov_b32_e32 v73, v2
	v_mov_b32_e32 v82, v2
	v_mov_b32_e32 v83, v2
	v_mov_b32_e32 v84, v2
	v_mov_b32_e32 v85, v2
	v_mov_b32_e32 v86, v2
	v_mov_b32_e32 v87, v2
	v_mov_b32_e32 v88, v2
	v_mov_b32_e32 v89, v2
	v_mov_b32_e32 v98, v2
	v_mov_b32_e32 v99, v2
	v_mov_b32_e32 v100, v2
	v_mov_b32_e32 v101, v2
	v_mov_b32_e32 v102, v2
	v_mov_b32_e32 v103, v2
	v_mov_b32_e32 v104, v2
	v_mov_b32_e32 v105, v2
	v_mov_b32_e32 v114, v2
	v_mov_b32_e32 v115, v2
	v_mov_b32_e32 v116, v2
	v_mov_b32_e32 v117, v2
	v_mov_b32_e32 v118, v2
	v_mov_b32_e32 v119, v2
	v_mov_b32_e32 v120, v2
	v_mov_b32_e32 v121, v2
	v_mov_b32_e32 v74, v2
	v_mov_b32_e32 v75, v2
	v_mov_b32_e32 v76, v2
	v_mov_b32_e32 v77, v2
	v_mov_b32_e32 v78, v2
	v_mov_b32_e32 v79, v2
	v_mov_b32_e32 v80, v2
	v_mov_b32_e32 v81, v2
	v_mov_b32_e32 v90, v2
	v_mov_b32_e32 v91, v2
	v_mov_b32_e32 v92, v2
	v_mov_b32_e32 v93, v2
	v_mov_b32_e32 v94, v2
	v_mov_b32_e32 v95, v2
	v_mov_b32_e32 v96, v2
	v_mov_b32_e32 v97, v2
	v_mov_b32_e32 v106, v2
	v_mov_b32_e32 v107, v2
	v_mov_b32_e32 v108, v2
	v_mov_b32_e32 v109, v2
	v_mov_b32_e32 v110, v2
	v_mov_b32_e32 v111, v2
	v_mov_b32_e32 v112, v2
	v_mov_b32_e32 v113, v2
	v_mov_b32_e32 v122, v2
	v_mov_b32_e32 v123, v2
	v_mov_b32_e32 v124, v2
	v_mov_b32_e32 v125, v2
	v_mov_b32_e32 v126, v2
	v_mov_b32_e32 v127, v2
	v_mov_b32_e32 v128, v2
	v_mov_b32_e32 v129, v2
	v_add_u32_e32 v240, 0x10000, v141
.LBB0_1238:
	s_add_i32 s72, s26, 2
	s_add_u32 s24, s22, 0x100
	s_addc_u32 s25, s23, 0
	s_add_i32 s35, 0, 0x10000
	ds_read_b128 v[144:147], v240
	ds_read_b128 v[148:151], v240 offset:1024
	ds_read_b128 v[152:155], v240 offset:2048
	ds_read_b128 v[156:159], v240 offset:3072
	s_cmp_eq_u32 s69, s26
	s_cselect_b32 s26, s16, s70
	s_cselect_b32 s29, s13, s25
	s_cselect_b32 s28, s12, s24
	s_cselect_b32 s27, s17, s71
	ds_read_b128 v[160:163], v143
	ds_read_b128 v[164:167], v143 offset:1024
	ds_read_b128 v[168:171], v143 offset:2048
	ds_read_b128 v[172:175], v143 offset:3072
	ds_read_b128 v[182:185], v143 offset:4096
	ds_read_b128 v[186:189], v143 offset:5120
	ds_read_b128 v[190:193], v143 offset:6144
	ds_read_b128 v[194:197], v143 offset:7168
	s_add_u32 s98, s22, 0xffea0000
	s_addc_u32 s99, s23, -1
	s_mov_b32 m0, s56
	s_nop 0
	global_load_lds_dwordx4 v136, s[98:99]
	s_mov_b32 m0, s57
	s_nop 0
	global_load_lds_dwordx4 v138, s[98:99]
	s_add_i32 m0, s52, 0xc000
	s_nop 0
	global_load_lds_dwordx4 v136, s[22:23]
	s_add_i32 m0, s52, 0xe000
	s_nop 0
	global_load_lds_dwordx4 v138, s[22:23]
	s_add_i32 s76, 0, 0x14000
	ds_read_b128 v[198:201], v240 offset:16384
	ds_read_b128 v[202:205], v240 offset:17408
	ds_read_b128 v[206:209], v240 offset:18432
	ds_read_b128 v[210:213], v240 offset:19456
	s_waitcnt lgkmcnt(0)
	s_barrier
; #define PG8_STAGE(bufoff, gbase, voff) do { _Pragma("unroll") for (int _i = 0; _i < 2; ++_i) \
;         __builtin_amdgcn_global_load_lds((const unsigned*)((const char*)(gbase) + (voff)[_i]), (LAS unsigned*)(lds + (bufoff) + ldsw + _i * 8192), 16, 0, 0); } while (0)
; #define PG8_LDA(dst, b, h) do { _Pragma("unroll") for (int m = 0; m < 4; ++m) _Pragma("unroll") for (int k = 0; k < 2; ++k) dst[m][k] = *(const LAS bf16x8*)(lds + PG8_SA(b, h) + aoff + m * 2048 + k * 1024); } while (0)
; #define PG8_LDB(dst, b, h) do { _Pragma("unroll") for (int n = 0; n < 2; ++n) _Pragma("unroll") for (int k = 0; k < 2; ++k) dst[n][k] = *(const LAS bf16x8*)(lds + PG8_SB(b, h) + boff + n * 2048 + k * 1024); } while (0)
; #define PG8_MMA(ai, bj, At, Bt) do { __builtin_amdgcn_s_setprio(1); _Pragma("unroll") for (int m = 0; m < 4; ++m) _Pragma("unroll") for (int n = 0; n < 2; ++n) _Pragma("unroll") for (int k = 0; k < 2; ++k) \
;         acc[ai][bj][m][n] = __builtin_amdgcn_mfma_f32_16x16x32_bf16(Bt[n][k], At[m][k], acc[ai][bj][m][n], 0, 0, 0); __builtin_amdgcn_s_setprio(0); } while (0)
; #define PG8_WAIT_V(n) asm volatile("s_waitcnt vmcnt(" #n ")" ::: "memory")
; #define PG8_WAIT_L(n) asm volatile("s_waitcnt lgkmcnt(" #n ")" ::: "memory")
; #define PG8_BAR __builtin_amdgcn_s_barrier()
; #define PG8_SCHED __builtin_amdgcn_sched_barrier(0)
; template <class Epi, class Sched>
; __device__ __forceinline__ void gemm_phase(LAS unsigned char* lds, const Gemm g, const Sched& S, const Epi& E) {
;     ...
;             PG8_WAIT_L(8); PG8_BAR; PG8_WAIT_L(0); PG8_MMA(0, 0, At, B0); PG8_BAR; PG8_SCHED;
;             PG8_LDB(B1, 0, 1); PG8_STAGE(PG8_SB(0, 0), b2, voffB);
;             PG8_BAR; PG8_WAIT_L(0); PG8_MMA(0, 1, At, B1); PG8_BAR;
;             PG8_LDA(At, 0, 1); PG8_STAGE(PG8_SA(0, 0), a2, voffA);
;             PG8_BAR; PG8_WAIT_L(0); PG8_MMA(1, 0, At, B0); PG8_BAR; PG8_SCHED;
;             PG8_STAGE(PG8_SB(0, 1), b2 + hstepB, voffB);
;             PG8_WAIT_V(6); PG8_BAR; PG8_MMA(1, 1, At, B1); PG8_BAR;
;             PG8_LDB(B0, 1, 0); PG8_SCHED; PG8_LDA(At, 1, 0); PG8_STAGE(PG8_SA(0, 1), a2 + hstepA, voffA);
	v_mfma_f32_16x16x32_bf16 v[126:129], v[144:147], v[160:163], v[126:129]
	v_mfma_f32_16x16x32_bf16 v[126:129], v[148:151], v[164:167], v[126:129]
	v_mfma_f32_16x16x32_bf16 v[110:113], v[144:147], v[168:171], v[110:113]
	v_mfma_f32_16x16x32_bf16 v[110:113], v[148:151], v[172:175], v[110:113]
	v_mfma_f32_16x16x32_bf16 v[94:97], v[144:147], v[182:185], v[94:97]
	v_mfma_f32_16x16x32_bf16 v[94:97], v[148:151], v[186:189], v[94:97]
	v_mfma_f32_16x16x32_bf16 v[78:81], v[144:147], v[190:193], v[78:81]
	v_mfma_f32_16x16x32_bf16 v[78:81], v[148:151], v[194:197], v[78:81]
	v_mfma_f32_16x16x32_bf16 v[122:125], v[152:155], v[160:163], v[122:125]
	v_mfma_f32_16x16x32_bf16 v[122:125], v[156:159], v[164:167], v[122:125]
	v_mfma_f32_16x16x32_bf16 v[106:109], v[152:155], v[168:171], v[106:109]
	v_mfma_f32_16x16x32_bf16 v[106:109], v[156:159], v[172:175], v[106:109]
	v_mfma_f32_16x16x32_bf16 v[90:93], v[152:155], v[182:185], v[90:93]
	v_mfma_f32_16x16x32_bf16 v[90:93], v[156:159], v[186:189], v[90:93]
	v_mfma_f32_16x16x32_bf16 v[74:77], v[152:155], v[190:193], v[74:77]
	v_mfma_f32_16x16x32_bf16 v[74:77], v[156:159], v[194:197], v[74:77]
	v_mfma_f32_16x16x32_bf16 v[118:121], v[198:201], v[160:163], v[118:121]
	v_mfma_f32_16x16x32_bf16 v[118:121], v[202:205], v[164:167], v[118:121]
	v_mfma_f32_16x16x32_bf16 v[102:105], v[198:201], v[168:171], v[102:105]
	v_mfma_f32_16x16x32_bf16 v[102:105], v[202:205], v[172:175], v[102:105]
	v_mfma_f32_16x16x32_bf16 v[86:89], v[198:201], v[182:185], v[86:89]
	v_mfma_f32_16x16x32_bf16 v[86:89], v[202:205], v[186:189], v[86:89]
	v_mfma_f32_16x16x32_bf16 v[70:73], v[198:201], v[190:193], v[70:73]
	v_mfma_f32_16x16x32_bf16 v[70:73], v[202:205], v[194:197], v[70:73]
	v_mfma_f32_16x16x32_bf16 v[114:117], v[206:209], v[160:163], v[114:117]
	v_mfma_f32_16x16x32_bf16 v[114:117], v[210:213], v[164:167], v[114:117]
	v_mfma_f32_16x16x32_bf16 v[98:101], v[206:209], v[168:171], v[98:101]
	v_mfma_f32_16x16x32_bf16 v[98:101], v[210:213], v[172:175], v[98:101]
	v_mfma_f32_16x16x32_bf16 v[82:85], v[206:209], v[182:185], v[82:85]
	v_mfma_f32_16x16x32_bf16 v[82:85], v[210:213], v[186:189], v[82:85]
	v_mfma_f32_16x16x32_bf16 v[66:69], v[206:209], v[190:193], v[66:69]
	v_mfma_f32_16x16x32_bf16 v[66:69], v[210:213], v[194:197], v[66:69]
	s_barrier
	ds_read_b128 v[160:163], v143 offset:16384
	ds_read_b128 v[164:167], v143 offset:17408
	ds_read_b128 v[168:171], v143 offset:18432
	ds_read_b128 v[172:175], v143 offset:19456
	ds_read_b128 v[182:185], v143 offset:20480
	ds_read_b128 v[186:189], v143 offset:21504
	ds_read_b128 v[190:193], v143 offset:22528
	ds_read_b128 v[194:197], v143 offset:23552
	s_add_i32 s22, s35, s50
	s_mov_b32 m0, s22
	s_nop 0
	global_load_lds_dwordx4 v178, s[26:27]
	s_add_i32 m0, s22, 0x2000
	s_nop 0
	global_load_lds_dwordx4 v134, s[26:27]
	s_add_u32 s22, s26, 0x160000
	s_addc_u32 s23, s27, 0
	s_add_i32 s35, s76, s50
	s_mov_b32 m0, s35
	s_nop 0
	global_load_lds_dwordx4 v178, s[22:23]
	s_add_i32 m0, s35, 0x2000
	s_nop 0
	global_load_lds_dwordx4 v134, s[22:23]
	s_waitcnt vmcnt(4)
	s_waitcnt lgkmcnt(0)
	s_barrier
	v_mfma_f32_16x16x32_bf16 v[62:65], v[144:147], v[160:163], v[62:65]
	v_mfma_f32_16x16x32_bf16 v[62:65], v[148:151], v[164:167], v[62:65]
	v_mfma_f32_16x16x32_bf16 v[46:49], v[144:147], v[168:171], v[46:49]
	v_mfma_f32_16x16x32_bf16 v[46:49], v[148:151], v[172:175], v[46:49]
	v_mfma_f32_16x16x32_bf16 v[30:33], v[144:147], v[182:185], v[30:33]
	v_mfma_f32_16x16x32_bf16 v[30:33], v[148:151], v[186:189], v[30:33]
	v_mfma_f32_16x16x32_bf16 v[14:17], v[144:147], v[190:193], v[14:17]
	v_mfma_f32_16x16x32_bf16 v[14:17], v[148:151], v[194:197], v[14:17]
	v_mfma_f32_16x16x32_bf16 v[58:61], v[152:155], v[160:163], v[58:61]
	v_mfma_f32_16x16x32_bf16 v[58:61], v[156:159], v[164:167], v[58:61]
	v_mfma_f32_16x16x32_bf16 v[42:45], v[152:155], v[168:171], v[42:45]
	v_mfma_f32_16x16x32_bf16 v[42:45], v[156:159], v[172:175], v[42:45]
	v_mfma_f32_16x16x32_bf16 v[26:29], v[152:155], v[182:185], v[26:29]
	v_mfma_f32_16x16x32_bf16 v[26:29], v[156:159], v[186:189], v[26:29]
	v_mfma_f32_16x16x32_bf16 v[10:13], v[152:155], v[190:193], v[10:13]
	v_mfma_f32_16x16x32_bf16 v[10:13], v[156:159], v[194:197], v[10:13]
	v_mfma_f32_16x16x32_bf16 v[54:57], v[198:201], v[160:163], v[54:57]
	v_mfma_f32_16x16x32_bf16 v[54:57], v[202:205], v[164:167], v[54:57]
	v_mfma_f32_16x16x32_bf16 v[38:41], v[198:201], v[168:171], v[38:41]
	v_mfma_f32_16x16x32_bf16 v[38:41], v[202:205], v[172:175], v[38:41]
	v_mfma_f32_16x16x32_bf16 v[22:25], v[198:201], v[182:185], v[22:25]
	v_mfma_f32_16x16x32_bf16 v[22:25], v[202:205], v[186:189], v[22:25]
	v_mfma_f32_16x16x32_bf16 v[6:9], v[198:201], v[190:193], v[6:9]
	v_mfma_f32_16x16x32_bf16 v[6:9], v[202:205], v[194:197], v[6:9]
	v_mfma_f32_16x16x32_bf16 v[50:53], v[206:209], v[160:163], v[50:53]
	v_mfma_f32_16x16x32_bf16 v[50:53], v[210:213], v[164:167], v[50:53]
	v_mfma_f32_16x16x32_bf16 v[34:37], v[206:209], v[168:171], v[34:37]
	v_mfma_f32_16x16x32_bf16 v[34:37], v[210:213], v[172:175], v[34:37]
	v_mfma_f32_16x16x32_bf16 v[18:21], v[206:209], v[182:185], v[18:21]
	v_mfma_f32_16x16x32_bf16 v[18:21], v[210:213], v[186:189], v[18:21]
	v_mfma_f32_16x16x32_bf16 v[2:5], v[206:209], v[190:193], v[2:5]
	v_mfma_f32_16x16x32_bf16 v[2:5], v[210:213], v[194:197], v[2:5]
	s_add_i32 s35, 0, 0x18000
	s_barrier
; #define PG8_STAGE(bufoff, gbase, voff) do { _Pragma("unroll") for (int _i = 0; _i < 2; ++_i) \
;         __builtin_amdgcn_global_load_lds((const unsigned*)((const char*)(gbase) + (voff)[_i]), (LAS unsigned*)(lds + (bufoff) + ldsw + _i * 8192), 16, 0, 0); } while (0)
; #define PG8_LDA(dst, b, h) do { _Pragma("unroll") for (int m = 0; m < 4; ++m) _Pragma("unroll") for (int k = 0; k < 2; ++k) dst[m][k] = *(const LAS bf16x8*)(lds + PG8_SA(b, h) + aoff + m * 2048 + k * 1024); } while (0)
; #define PG8_LDB(dst, b, h) do { _Pragma("unroll") for (int n = 0; n < 2; ++n) _Pragma("unroll") for (int k = 0; k < 2; ++k) dst[n][k] = *(const LAS bf16x8*)(lds + PG8_SB(b, h) + boff + n * 2048 + k * 1024); } while (0)
; #define PG8_MMA(ai, bj, At, Bt) do { __builtin_amdgcn_s_setprio(1); _Pragma("unroll") for (int m = 0; m < 4; ++m) _Pragma("unroll") for (int n = 0; n < 2; ++n) _Pragma("unroll") for (int k = 0; k < 2; ++k) \
;         acc[ai][bj][m][n] = __builtin_amdgcn_mfma_f32_16x16x32_bf16(Bt[n][k], At[m][k], acc[ai][bj][m][n], 0, 0, 0); __builtin_amdgcn_s_setprio(0); } while (0)
; #define PG8_WAIT_V(n) asm volatile("s_waitcnt vmcnt(" #n ")" ::: "memory")
; #define PG8_WAIT_L(n) asm volatile("s_waitcnt lgkmcnt(" #n ")" ::: "memory")
; #define PG8_BAR __builtin_amdgcn_s_barrier()
; #define PG8_SCHED __builtin_amdgcn_sched_barrier(0)
; template <class Epi, class Sched>
; __device__ __forceinline__ void gemm_phase(LAS unsigned char* lds, const Gemm g, const Sched& S, const Epi& E) {
;     ...
;             PG8_LDB(B0, 1, 0); PG8_SCHED; PG8_LDA(At, 1, 0); PG8_STAGE(PG8_SA(0, 1), a2 + hstepA, voffA);
;             PG8_WAIT_L(8); PG8_BAR; PG8_WAIT_L(0); PG8_MMA(0, 0, At, B0); PG8_BAR; PG8_SCHED;
;             PG8_LDB(B1, 1, 1); PG8_STAGE(PG8_SB(1, 0), b3, voffB);
;             PG8_BAR; PG8_WAIT_L(0); PG8_MMA(0, 1, At, B1); PG8_BAR;
;             PG8_LDA(At, 1, 1); PG8_STAGE(PG8_SA(1, 0), a3, voffA);
;             PG8_BAR; PG8_WAIT_L(0); PG8_MMA(1, 0, At, B0); PG8_BAR; PG8_SCHED;
;             PG8_STAGE(PG8_SB(1, 1), b3 + hstepB, voffB);
;             PG8_WAIT_V(6); PG8_BAR; PG8_MMA(1, 1, At, B1); PG8_BAR;
;         }
	ds_read_b128 v[144:147], v240 offset:32768
	ds_read_b128 v[148:151], v240 offset:33792
	ds_read_b128 v[152:155], v240 offset:34816
	ds_read_b128 v[156:159], v240 offset:35840
	ds_read_b128 v[160:163], v143 offset:32768
	ds_read_b128 v[164:167], v143 offset:33792
	ds_read_b128 v[168:171], v143 offset:34816
	ds_read_b128 v[172:175], v143 offset:35840
	ds_read_b128 v[182:185], v143 offset:36864
	ds_read_b128 v[186:189], v143 offset:37888
	ds_read_b128 v[190:193], v143 offset:38912
	ds_read_b128 v[194:197], v143 offset:39936
	s_mov_b32 m0, s52
	s_nop 0
	global_load_lds_dwordx4 v130, s[28:29]
	s_mov_b32 m0, s53
	s_nop 0
	global_load_lds_dwordx4 v132, s[28:29]
	s_add_u32 s22, s28, 0x160000
	s_addc_u32 s23, s29, 0
	s_mov_b32 m0, s54
	s_nop 0
	global_load_lds_dwordx4 v130, s[22:23]
	s_mov_b32 m0, s55
	s_nop 0
	global_load_lds_dwordx4 v132, s[22:23]
	s_add_i32 s28, 0, 0x1c000
	ds_read_b128 v[198:201], v240 offset:49152
	ds_read_b128 v[202:205], v240 offset:50176
	ds_read_b128 v[206:209], v240 offset:51200
	ds_read_b128 v[210:213], v240 offset:52224
	s_waitcnt lgkmcnt(0)
	s_barrier
	v_mfma_f32_16x16x32_bf16 v[126:129], v[144:147], v[160:163], v[126:129]
	v_mfma_f32_16x16x32_bf16 v[126:129], v[148:151], v[164:167], v[126:129]
	v_mfma_f32_16x16x32_bf16 v[110:113], v[144:147], v[168:171], v[110:113]
	v_mfma_f32_16x16x32_bf16 v[110:113], v[148:151], v[172:175], v[110:113]
	v_mfma_f32_16x16x32_bf16 v[94:97], v[144:147], v[182:185], v[94:97]
	v_mfma_f32_16x16x32_bf16 v[94:97], v[148:151], v[186:189], v[94:97]
	v_mfma_f32_16x16x32_bf16 v[78:81], v[144:147], v[190:193], v[78:81]
	v_mfma_f32_16x16x32_bf16 v[78:81], v[148:151], v[194:197], v[78:81]
	v_mfma_f32_16x16x32_bf16 v[122:125], v[152:155], v[160:163], v[122:125]
	v_mfma_f32_16x16x32_bf16 v[122:125], v[156:159], v[164:167], v[122:125]
	v_mfma_f32_16x16x32_bf16 v[106:109], v[152:155], v[168:171], v[106:109]
	v_mfma_f32_16x16x32_bf16 v[106:109], v[156:159], v[172:175], v[106:109]
	v_mfma_f32_16x16x32_bf16 v[90:93], v[152:155], v[182:185], v[90:93]
	v_mfma_f32_16x16x32_bf16 v[90:93], v[156:159], v[186:189], v[90:93]
	v_mfma_f32_16x16x32_bf16 v[74:77], v[152:155], v[190:193], v[74:77]
	v_mfma_f32_16x16x32_bf16 v[74:77], v[156:159], v[194:197], v[74:77]
	v_mfma_f32_16x16x32_bf16 v[118:121], v[198:201], v[160:163], v[118:121]
	v_mfma_f32_16x16x32_bf16 v[118:121], v[202:205], v[164:167], v[118:121]
	v_mfma_f32_16x16x32_bf16 v[102:105], v[198:201], v[168:171], v[102:105]
	v_mfma_f32_16x16x32_bf16 v[102:105], v[202:205], v[172:175], v[102:105]
	v_mfma_f32_16x16x32_bf16 v[86:89], v[198:201], v[182:185], v[86:89]
	v_mfma_f32_16x16x32_bf16 v[86:89], v[202:205], v[186:189], v[86:89]
	v_mfma_f32_16x16x32_bf16 v[70:73], v[198:201], v[190:193], v[70:73]
	v_mfma_f32_16x16x32_bf16 v[70:73], v[202:205], v[194:197], v[70:73]
	v_mfma_f32_16x16x32_bf16 v[114:117], v[206:209], v[160:163], v[114:117]
	v_mfma_f32_16x16x32_bf16 v[114:117], v[210:213], v[164:167], v[114:117]
	v_mfma_f32_16x16x32_bf16 v[98:101], v[206:209], v[168:171], v[98:101]
	v_mfma_f32_16x16x32_bf16 v[98:101], v[210:213], v[172:175], v[98:101]
	v_mfma_f32_16x16x32_bf16 v[82:85], v[206:209], v[182:185], v[82:85]
	v_mfma_f32_16x16x32_bf16 v[82:85], v[210:213], v[186:189], v[82:85]
	v_mfma_f32_16x16x32_bf16 v[66:69], v[206:209], v[190:193], v[66:69]
	v_mfma_f32_16x16x32_bf16 v[66:69], v[210:213], v[194:197], v[66:69]
	s_barrier
	ds_read_b128 v[160:163], v143 offset:49152
	ds_read_b128 v[164:167], v143 offset:50176
	ds_read_b128 v[168:171], v143 offset:51200
	ds_read_b128 v[172:175], v143 offset:52224
	ds_read_b128 v[182:185], v143 offset:53248
	ds_read_b128 v[186:189], v143 offset:54272
	ds_read_b128 v[190:193], v143 offset:55296
	ds_read_b128 v[194:197], v143 offset:56320
	s_add_u32 s98, s26, 0x80
	s_addc_u32 s99, s27, 0
	s_add_i32 s22, s35, s50
	s_mov_b32 m0, s22
	s_nop 0
	global_load_lds_dwordx4 v178, s[98:99]
	s_add_i32 m0, s22, 0x2000
	s_nop 0
	global_load_lds_dwordx4 v134, s[98:99]
	s_add_u32 s22, s26, 0x160080
	s_addc_u32 s23, s27, 0
	s_add_i32 s26, s28, s50
	s_mov_b32 m0, s26
	s_nop 0
	global_load_lds_dwordx4 v178, s[22:23]
	s_add_i32 m0, s26, 0x2000
	s_nop 0
	global_load_lds_dwordx4 v134, s[22:23]
	s_waitcnt vmcnt(4)
	s_waitcnt lgkmcnt(0)
	s_barrier
	v_mfma_f32_16x16x32_bf16 v[62:65], v[144:147], v[160:163], v[62:65]
	v_mfma_f32_16x16x32_bf16 v[62:65], v[148:151], v[164:167], v[62:65]
	v_mfma_f32_16x16x32_bf16 v[46:49], v[144:147], v[168:171], v[46:49]
	v_mfma_f32_16x16x32_bf16 v[46:49], v[148:151], v[172:175], v[46:49]
	v_mfma_f32_16x16x32_bf16 v[30:33], v[144:147], v[182:185], v[30:33]
	v_mfma_f32_16x16x32_bf16 v[30:33], v[148:151], v[186:189], v[30:33]
	v_mfma_f32_16x16x32_bf16 v[14:17], v[144:147], v[190:193], v[14:17]
	v_mfma_f32_16x16x32_bf16 v[14:17], v[148:151], v[194:197], v[14:17]
	v_mfma_f32_16x16x32_bf16 v[58:61], v[152:155], v[160:163], v[58:61]
	v_mfma_f32_16x16x32_bf16 v[58:61], v[156:159], v[164:167], v[58:61]
	v_mfma_f32_16x16x32_bf16 v[42:45], v[152:155], v[168:171], v[42:45]
	v_mfma_f32_16x16x32_bf16 v[42:45], v[156:159], v[172:175], v[42:45]
	v_mfma_f32_16x16x32_bf16 v[26:29], v[152:155], v[182:185], v[26:29]
	v_mfma_f32_16x16x32_bf16 v[26:29], v[156:159], v[186:189], v[26:29]
	v_mfma_f32_16x16x32_bf16 v[10:13], v[152:155], v[190:193], v[10:13]
	v_mfma_f32_16x16x32_bf16 v[10:13], v[156:159], v[194:197], v[10:13]
	v_mfma_f32_16x16x32_bf16 v[54:57], v[198:201], v[160:163], v[54:57]
	v_mfma_f32_16x16x32_bf16 v[54:57], v[202:205], v[164:167], v[54:57]
	v_mfma_f32_16x16x32_bf16 v[38:41], v[198:201], v[168:171], v[38:41]
	v_mfma_f32_16x16x32_bf16 v[38:41], v[202:205], v[172:175], v[38:41]
	v_mfma_f32_16x16x32_bf16 v[22:25], v[198:201], v[182:185], v[22:25]
	v_mfma_f32_16x16x32_bf16 v[22:25], v[202:205], v[186:189], v[22:25]
	v_mfma_f32_16x16x32_bf16 v[6:9], v[198:201], v[190:193], v[6:9]
	v_mfma_f32_16x16x32_bf16 v[6:9], v[202:205], v[194:197], v[6:9]
	v_mfma_f32_16x16x32_bf16 v[50:53], v[206:209], v[160:163], v[50:53]
	v_mfma_f32_16x16x32_bf16 v[50:53], v[210:213], v[164:167], v[50:53]
	v_mfma_f32_16x16x32_bf16 v[34:37], v[206:209], v[168:171], v[34:37]
	v_mfma_f32_16x16x32_bf16 v[34:37], v[210:213], v[172:175], v[34:37]
	v_mfma_f32_16x16x32_bf16 v[18:21], v[206:209], v[182:185], v[18:21]
	v_mfma_f32_16x16x32_bf16 v[18:21], v[210:213], v[186:189], v[18:21]
	v_mfma_f32_16x16x32_bf16 v[2:5], v[206:209], v[190:193], v[2:5]
	v_mfma_f32_16x16x32_bf16 v[2:5], v[210:213], v[194:197], v[2:5]
	s_add_u32 s70, s70, 0x100
	s_addc_u32 s71, s71, 0
	s_cmp_ge_i32 s72, s68
	s_mov_b64 s[22:23], s[24:25]
	s_mov_b32 s26, s72
	s_barrier
	s_cbranch_scc0 .LBB0_1238
	v_readlane_b32 s76, v255, 26
	v_readlane_b32 s77, v255, 27
	s_branch .LBB0_1241
